# peel first K-iteration of 12 GEMM loops with C=0 MFMAs, drop 127 accumulator-zeroing movs per unit
# speedup vs baseline: 1.0027x; 1.0027x over previous
.LBB0_294:
	s_lshl_b32 s72, s58, 19
	s_and_b64 s[6:7], s[6:7], exec
	v_mov_b32_e32 v2, 0
	s_cselect_b32 s6, s72, s86
	s_add_i32 s7, s86, 0x60080
	s_addk_i32 s79, 0x100
	s_mov_b32 s86, -2
	ds_read_b128 v[136:139], v147
	ds_read_b128 v[140:143], v147 offset:1024
	ds_read_b128 v[152:155], v147 offset:2048
	ds_read_b128 v[156:159], v147 offset:3072
	s_add_i32 s10, s7, 0xfffa0080
	s_cmp_eq_u32 s86, 12
	s_cselect_b32 s88, s6, s10
	s_cselect_b32 s87, s59, s79
	s_or_b32 s89, s88, 0x80
	s_add_i32 s10, s7, 0xfffe0000
	s_mov_b32 m0, s39
	ds_read_b128 v[160:163], v148
	ds_read_b128 v[164:167], v148 offset:1024
	ds_read_b128 v[168:171], v148 offset:2048
	ds_read_b128 v[172:175], v148 offset:3072
	ds_read_b128 v[176:179], v148 offset:4096
	ds_read_b128 v[180:183], v148 offset:5120
	ds_read_b128 v[184:187], v148 offset:6144
	ds_read_b128 v[188:191], v148 offset:7168
	buffer_load_dwordx4 v1, s[40:43], s10 offen lds
	s_mov_b32 m0, s45
	s_nop 0
	buffer_load_dwordx4 v1, s[40:43], s7 offen lds
	s_waitcnt lgkmcnt(8)
	s_barrier
	s_waitcnt lgkmcnt(0)
	s_setprio 1
	s_waitcnt lgkmcnt(7)
	v_mfma_f32_16x16x32_bf16 v[126:129], v[136:139], v[160:163], 0
	v_mfma_f32_16x16x32_bf16 v[122:125], v[152:155], v[160:163], 0
	s_waitcnt lgkmcnt(5)
	v_mfma_f32_16x16x32_bf16 v[118:121], v[136:139], v[168:171], 0
	v_mfma_f32_16x16x32_bf16 v[110:113], v[152:155], v[168:171], 0
	s_waitcnt lgkmcnt(3)
	v_mfma_f32_16x16x32_bf16 v[102:105], v[136:139], v[176:179], 0
	v_mfma_f32_16x16x32_bf16 v[94:97], v[152:155], v[176:179], 0
	s_waitcnt lgkmcnt(1)
	v_mfma_f32_16x16x32_bf16 v[86:89], v[136:139], v[184:187], 0
	v_mfma_f32_16x16x32_bf16 v[78:81], v[152:155], v[184:187], 0
	v_mfma_f32_16x16x32_bf16 v[126:129], v[140:143], v[164:167], v[126:129]
	v_mfma_f32_16x16x32_bf16 v[122:125], v[156:159], v[164:167], v[122:125]
	v_mfma_f32_16x16x32_bf16 v[118:121], v[140:143], v[172:175], v[118:121]
	v_mfma_f32_16x16x32_bf16 v[110:113], v[156:159], v[172:175], v[110:113]
	v_mfma_f32_16x16x32_bf16 v[102:105], v[140:143], v[180:183], v[102:105]
	v_mfma_f32_16x16x32_bf16 v[94:97], v[156:159], v[180:183], v[94:97]
	s_waitcnt lgkmcnt(0)
	v_mfma_f32_16x16x32_bf16 v[86:89], v[140:143], v[188:191], v[86:89]
	v_mfma_f32_16x16x32_bf16 v[78:81], v[156:159], v[188:191], v[78:81]
	s_setprio 0
	s_barrier
	s_mov_b32 m0, s23
	s_mov_b32 s10, s42
	s_mov_b32 s11, s43
	ds_read_b128 v[192:195], v149
	ds_read_b128 v[196:199], v149 offset:1024
	ds_read_b128 v[200:203], v149 offset:2048
	ds_read_b128 v[204:207], v149 offset:3072
	buffer_load_dwordx4 v144, s[8:11], s87 offen lds
	s_add_i32 s33, s87, 0x20000
	s_mov_b32 m0, s24
	s_nop 0
	buffer_load_dwordx4 v144, s[8:11], s33 offen lds
	s_barrier
	s_waitcnt lgkmcnt(0)
	s_setprio 1
	s_waitcnt lgkmcnt(3)
	v_mfma_f32_16x16x32_bf16 v[114:117], v[192:195], v[160:163], 0
	s_waitcnt lgkmcnt(1)
	v_mfma_f32_16x16x32_bf16 v[106:109], v[200:203], v[160:163], 0
	v_mfma_f32_16x16x32_bf16 v[98:101], v[192:195], v[168:171], 0
	v_mfma_f32_16x16x32_bf16 v[90:93], v[200:203], v[168:171], 0
	v_mfma_f32_16x16x32_bf16 v[82:85], v[192:195], v[176:179], 0
	v_mfma_f32_16x16x32_bf16 v[74:77], v[200:203], v[176:179], 0
	v_mfma_f32_16x16x32_bf16 v[70:73], v[192:195], v[184:187], 0
	v_mfma_f32_16x16x32_bf16 v[66:69], v[200:203], v[184:187], 0
	v_mfma_f32_16x16x32_bf16 v[114:117], v[196:199], v[164:167], v[114:117]
	s_waitcnt lgkmcnt(0)
	v_mfma_f32_16x16x32_bf16 v[106:109], v[204:207], v[164:167], v[106:109]
	v_mfma_f32_16x16x32_bf16 v[98:101], v[196:199], v[172:175], v[98:101]
	v_mfma_f32_16x16x32_bf16 v[90:93], v[204:207], v[172:175], v[90:93]
	v_mfma_f32_16x16x32_bf16 v[82:85], v[196:199], v[180:183], v[82:85]
	v_mfma_f32_16x16x32_bf16 v[74:77], v[204:207], v[180:183], v[74:77]
	v_mfma_f32_16x16x32_bf16 v[70:73], v[196:199], v[188:191], v[70:73]
	v_mfma_f32_16x16x32_bf16 v[66:69], v[204:207], v[188:191], v[66:69]
	s_setprio 0
	s_mov_b32 m0, s22
	s_barrier
	ds_read_b128 v[160:163], v148 offset:16384
	ds_read_b128 v[164:167], v148 offset:17408
	ds_read_b128 v[168:171], v148 offset:18432
	ds_read_b128 v[172:175], v148 offset:19456
	ds_read_b128 v[176:179], v148 offset:20480
	ds_read_b128 v[180:183], v148 offset:21504
	ds_read_b128 v[184:187], v148 offset:22528
	ds_read_b128 v[188:191], v148 offset:23552
	buffer_load_dwordx4 v1, s[40:43], s88 offen lds
	s_add_i32 s33, s88, 0x20000
	s_mov_b32 m0, s25
	s_nop 0
	buffer_load_dwordx4 v1, s[40:43], s33 offen lds
	s_barrier
	s_waitcnt lgkmcnt(0)
	s_setprio 1
	s_waitcnt lgkmcnt(7)
	v_mfma_f32_16x16x32_bf16 v[62:65], v[136:139], v[160:163], 0
	v_mfma_f32_16x16x32_bf16 v[58:61], v[152:155], v[160:163], 0
	s_waitcnt lgkmcnt(5)
	v_mfma_f32_16x16x32_bf16 v[54:57], v[136:139], v[168:171], 0
	v_mfma_f32_16x16x32_bf16 v[46:49], v[152:155], v[168:171], 0
	s_waitcnt lgkmcnt(3)
	v_mfma_f32_16x16x32_bf16 v[38:41], v[136:139], v[176:179], 0
	v_mfma_f32_16x16x32_bf16 v[30:33], v[152:155], v[176:179], 0
	s_waitcnt lgkmcnt(1)
	v_mfma_f32_16x16x32_bf16 v[22:25], v[136:139], v[184:187], 0
	v_mfma_f32_16x16x32_bf16 v[14:17], v[152:155], v[184:187], 0
	v_mfma_f32_16x16x32_bf16 v[62:65], v[140:143], v[164:167], v[62:65]
	v_mfma_f32_16x16x32_bf16 v[58:61], v[156:159], v[164:167], v[58:61]
	v_mfma_f32_16x16x32_bf16 v[54:57], v[140:143], v[172:175], v[54:57]
	v_mfma_f32_16x16x32_bf16 v[46:49], v[156:159], v[172:175], v[46:49]
	v_mfma_f32_16x16x32_bf16 v[38:41], v[140:143], v[180:183], v[38:41]
	v_mfma_f32_16x16x32_bf16 v[30:33], v[156:159], v[180:183], v[30:33]
	s_waitcnt lgkmcnt(0)
	v_mfma_f32_16x16x32_bf16 v[22:25], v[140:143], v[188:191], v[22:25]
	v_mfma_f32_16x16x32_bf16 v[14:17], v[156:159], v[188:191], v[14:17]
	s_setprio 0
	s_barrier
	s_mov_b32 m0, s26
	s_add_i32 s33, s87, 0x40000
	buffer_load_dwordx4 v144, s[8:11], s33 offen lds
	s_add_i32 s33, s87, 0x60000
	s_mov_b32 m0, s27
	s_nop 0
	buffer_load_dwordx4 v144, s[8:11], s33 offen lds
	s_cmp_eq_u32 s100, 0
	s_cbranch_scc1 .Lfw_1_a_p
	s_waitcnt vmcnt(16)
	s_mov_b32 s100, 0
	s_branch .Lfw_1_b_p

.Lfw_1_b_p:
	s_barrier
	s_setprio 1
	v_mfma_f32_16x16x32_bf16 v[50:53], v[192:195], v[160:163], 0
	v_mfma_f32_16x16x32_bf16 v[42:45], v[200:203], v[160:163], 0
	v_mfma_f32_16x16x32_bf16 v[34:37], v[192:195], v[168:171], 0
	v_mfma_f32_16x16x32_bf16 v[26:29], v[200:203], v[168:171], 0
	v_mfma_f32_16x16x32_bf16 v[18:21], v[192:195], v[176:179], 0
	v_mfma_f32_16x16x32_bf16 v[10:13], v[200:203], v[176:179], 0
	v_mfma_f32_16x16x32_bf16 v[6:9], v[192:195], v[184:187], 0
	v_mfma_f32_16x16x32_bf16 v[2:5], v[200:203], v[184:187], 0
	v_mfma_f32_16x16x32_bf16 v[50:53], v[196:199], v[164:167], v[50:53]
	v_mfma_f32_16x16x32_bf16 v[42:45], v[204:207], v[164:167], v[42:45]
	v_mfma_f32_16x16x32_bf16 v[34:37], v[196:199], v[172:175], v[34:37]
	v_mfma_f32_16x16x32_bf16 v[26:29], v[204:207], v[172:175], v[26:29]
	v_mfma_f32_16x16x32_bf16 v[18:21], v[196:199], v[180:183], v[18:21]
	v_mfma_f32_16x16x32_bf16 v[10:13], v[204:207], v[180:183], v[10:13]
	v_mfma_f32_16x16x32_bf16 v[6:9], v[196:199], v[188:191], v[6:9]
	v_mfma_f32_16x16x32_bf16 v[2:5], v[204:207], v[188:191], v[2:5]
	s_setprio 0
	s_barrier
	ds_read_b128 v[136:139], v150
	ds_read_b128 v[140:143], v150 offset:1024
	ds_read_b128 v[152:155], v150 offset:2048
	ds_read_b128 v[156:159], v150 offset:3072
	s_mov_b32 m0, s28
	s_add_i32 s33, s88, 0x40000
	ds_read_b128 v[160:163], v148 offset:32768
	ds_read_b128 v[164:167], v148 offset:33792
	ds_read_b128 v[168:171], v148 offset:34816
	ds_read_b128 v[172:175], v148 offset:35840
	ds_read_b128 v[176:179], v148 offset:36864
	ds_read_b128 v[180:183], v148 offset:37888
	ds_read_b128 v[184:187], v148 offset:38912
	ds_read_b128 v[188:191], v148 offset:39936
	buffer_load_dwordx4 v1, s[40:43], s33 offen lds
	s_add_i32 s33, s88, 0x60000
	s_mov_b32 m0, s29
	s_nop 0
	buffer_load_dwordx4 v1, s[40:43], s33 offen lds
	s_waitcnt lgkmcnt(8)
	s_barrier
	s_waitcnt lgkmcnt(0)
	s_setprio 1
	s_waitcnt lgkmcnt(7)
	v_mfma_f32_16x16x32_bf16 v[126:129], v[136:139], v[160:163], v[126:129]
	v_mfma_f32_16x16x32_bf16 v[122:125], v[152:155], v[160:163], v[122:125]
	s_waitcnt lgkmcnt(5)
	v_mfma_f32_16x16x32_bf16 v[118:121], v[136:139], v[168:171], v[118:121]
	v_mfma_f32_16x16x32_bf16 v[110:113], v[152:155], v[168:171], v[110:113]
	s_waitcnt lgkmcnt(3)
	v_mfma_f32_16x16x32_bf16 v[102:105], v[136:139], v[176:179], v[102:105]
	v_mfma_f32_16x16x32_bf16 v[94:97], v[152:155], v[176:179], v[94:97]
	s_waitcnt lgkmcnt(1)
	v_mfma_f32_16x16x32_bf16 v[86:89], v[136:139], v[184:187], v[86:89]
	v_mfma_f32_16x16x32_bf16 v[78:81], v[152:155], v[184:187], v[78:81]
	v_mfma_f32_16x16x32_bf16 v[126:129], v[140:143], v[164:167], v[126:129]
	v_mfma_f32_16x16x32_bf16 v[122:125], v[156:159], v[164:167], v[122:125]
	v_mfma_f32_16x16x32_bf16 v[118:121], v[140:143], v[172:175], v[118:121]
	v_mfma_f32_16x16x32_bf16 v[110:113], v[156:159], v[172:175], v[110:113]
	v_mfma_f32_16x16x32_bf16 v[102:105], v[140:143], v[180:183], v[102:105]
	v_mfma_f32_16x16x32_bf16 v[94:97], v[156:159], v[180:183], v[94:97]
	s_waitcnt lgkmcnt(0)
	v_mfma_f32_16x16x32_bf16 v[86:89], v[140:143], v[188:191], v[86:89]
	v_mfma_f32_16x16x32_bf16 v[78:81], v[156:159], v[188:191], v[78:81]
	s_setprio 0
	s_barrier
	s_mov_b32 m0, s31
	s_or_b32 s33, s87, 0x80
	ds_read_b128 v[192:195], v151
	ds_read_b128 v[196:199], v151 offset:1024
	ds_read_b128 v[200:203], v151 offset:2048
	ds_read_b128 v[204:207], v151 offset:3072
	buffer_load_dwordx4 v144, s[8:11], s33 offen lds
	s_add_i32 s33, s87, 0x20080
	s_mov_b32 m0, s34
	s_nop 0
	buffer_load_dwordx4 v144, s[8:11], s33 offen lds
	s_waitcnt vmcnt(10)
	s_barrier
	s_waitcnt lgkmcnt(0)
	s_setprio 1
	s_waitcnt lgkmcnt(3)
	v_mfma_f32_16x16x32_bf16 v[114:117], v[192:195], v[160:163], v[114:117]
	s_waitcnt lgkmcnt(1)
	v_mfma_f32_16x16x32_bf16 v[106:109], v[200:203], v[160:163], v[106:109]
	v_mfma_f32_16x16x32_bf16 v[98:101], v[192:195], v[168:171], v[98:101]
	v_mfma_f32_16x16x32_bf16 v[90:93], v[200:203], v[168:171], v[90:93]
	v_mfma_f32_16x16x32_bf16 v[82:85], v[192:195], v[176:179], v[82:85]
	v_mfma_f32_16x16x32_bf16 v[74:77], v[200:203], v[176:179], v[74:77]
	v_mfma_f32_16x16x32_bf16 v[70:73], v[192:195], v[184:187], v[70:73]
	v_mfma_f32_16x16x32_bf16 v[66:69], v[200:203], v[184:187], v[66:69]
	v_mfma_f32_16x16x32_bf16 v[114:117], v[196:199], v[164:167], v[114:117]
	s_waitcnt lgkmcnt(0)
	v_mfma_f32_16x16x32_bf16 v[106:109], v[204:207], v[164:167], v[106:109]
	v_mfma_f32_16x16x32_bf16 v[98:101], v[196:199], v[172:175], v[98:101]
	v_mfma_f32_16x16x32_bf16 v[90:93], v[204:207], v[172:175], v[90:93]
	v_mfma_f32_16x16x32_bf16 v[82:85], v[196:199], v[180:183], v[82:85]
	v_mfma_f32_16x16x32_bf16 v[74:77], v[204:207], v[180:183], v[74:77]
	v_mfma_f32_16x16x32_bf16 v[70:73], v[196:199], v[188:191], v[70:73]
	v_mfma_f32_16x16x32_bf16 v[66:69], v[204:207], v[188:191], v[66:69]
	s_setprio 0
	s_mov_b32 m0, s35
	s_barrier
	ds_read_b128 v[160:163], v148 offset:49152
	ds_read_b128 v[164:167], v148 offset:50176
	ds_read_b128 v[168:171], v148 offset:51200
	ds_read_b128 v[172:175], v148 offset:52224
	ds_read_b128 v[176:179], v148 offset:53248
	ds_read_b128 v[180:183], v148 offset:54272
	ds_read_b128 v[184:187], v148 offset:55296
	ds_read_b128 v[188:191], v148 offset:56320
	buffer_load_dwordx4 v1, s[40:43], s89 offen lds
	s_add_i32 s88, s88, 0x20080
	s_mov_b32 m0, s36
	s_nop 0
	buffer_load_dwordx4 v1, s[40:43], s88 offen lds
	s_barrier
	s_waitcnt lgkmcnt(0)
	s_setprio 1
	s_waitcnt lgkmcnt(7)
	v_mfma_f32_16x16x32_bf16 v[62:65], v[136:139], v[160:163], v[62:65]
	v_mfma_f32_16x16x32_bf16 v[58:61], v[152:155], v[160:163], v[58:61]
	s_waitcnt lgkmcnt(5)
	v_mfma_f32_16x16x32_bf16 v[54:57], v[136:139], v[168:171], v[54:57]
	v_mfma_f32_16x16x32_bf16 v[46:49], v[152:155], v[168:171], v[46:49]
	s_waitcnt lgkmcnt(3)
	v_mfma_f32_16x16x32_bf16 v[38:41], v[136:139], v[176:179], v[38:41]
	v_mfma_f32_16x16x32_bf16 v[30:33], v[152:155], v[176:179], v[30:33]
	s_waitcnt lgkmcnt(1)
	v_mfma_f32_16x16x32_bf16 v[22:25], v[136:139], v[184:187], v[22:25]
	v_mfma_f32_16x16x32_bf16 v[14:17], v[152:155], v[184:187], v[14:17]
	v_mfma_f32_16x16x32_bf16 v[62:65], v[140:143], v[164:167], v[62:65]
	v_mfma_f32_16x16x32_bf16 v[58:61], v[156:159], v[164:167], v[58:61]
	v_mfma_f32_16x16x32_bf16 v[54:57], v[140:143], v[172:175], v[54:57]
	v_mfma_f32_16x16x32_bf16 v[46:49], v[156:159], v[172:175], v[46:49]
	v_mfma_f32_16x16x32_bf16 v[38:41], v[140:143], v[180:183], v[38:41]
	v_mfma_f32_16x16x32_bf16 v[30:33], v[156:159], v[180:183], v[30:33]
	s_waitcnt lgkmcnt(0)
	v_mfma_f32_16x16x32_bf16 v[22:25], v[140:143], v[188:191], v[22:25]
	v_mfma_f32_16x16x32_bf16 v[14:17], v[156:159], v[188:191], v[14:17]
	s_setprio 0
	s_barrier
	s_mov_b32 m0, s37
	s_add_i32 s33, s87, 0x40080
	buffer_load_dwordx4 v144, s[8:11], s33 offen lds
	s_add_i32 s87, s87, 0x60080
	s_mov_b32 m0, s38
	s_nop 0
	buffer_load_dwordx4 v144, s[8:11], s87 offen lds
	s_waitcnt vmcnt(6)
	s_barrier
	s_setprio 1
	v_mfma_f32_16x16x32_bf16 v[50:53], v[192:195], v[160:163], v[50:53]
	v_mfma_f32_16x16x32_bf16 v[42:45], v[200:203], v[160:163], v[42:45]
	v_mfma_f32_16x16x32_bf16 v[34:37], v[192:195], v[168:171], v[34:37]
	v_mfma_f32_16x16x32_bf16 v[26:29], v[200:203], v[168:171], v[26:29]
	v_mfma_f32_16x16x32_bf16 v[18:21], v[192:195], v[176:179], v[18:21]
	v_mfma_f32_16x16x32_bf16 v[10:13], v[200:203], v[176:179], v[10:13]
	v_mfma_f32_16x16x32_bf16 v[6:9], v[192:195], v[184:187], v[6:9]
	v_mfma_f32_16x16x32_bf16 v[2:5], v[200:203], v[184:187], v[2:5]
	v_mfma_f32_16x16x32_bf16 v[50:53], v[196:199], v[164:167], v[50:53]
	v_mfma_f32_16x16x32_bf16 v[42:45], v[204:207], v[164:167], v[42:45]
	v_mfma_f32_16x16x32_bf16 v[34:37], v[196:199], v[172:175], v[34:37]
	v_mfma_f32_16x16x32_bf16 v[26:29], v[204:207], v[172:175], v[26:29]
	v_mfma_f32_16x16x32_bf16 v[18:21], v[196:199], v[180:183], v[18:21]
	v_mfma_f32_16x16x32_bf16 v[10:13], v[204:207], v[180:183], v[10:13]
	v_mfma_f32_16x16x32_bf16 v[6:9], v[196:199], v[188:191], v[6:9]
	v_mfma_f32_16x16x32_bf16 v[2:5], v[204:207], v[188:191], v[2:5]
	s_setprio 0
	s_add_i32 s86, s86, 2
	s_addk_i32 s7, 0x100
	s_addk_i32 s79, 0x100
	s_cmp_gt_u32 s86, 13
	s_barrier

.LBB0_449:
	s_lshl_b32 s73, s59, 19
	s_and_b64 s[6:7], s[6:7], exec
	v_mov_b32_e32 v2, 0
	s_cselect_b32 s6, s73, s17
	s_add_i32 s7, s17, 0x60080
	s_addk_i32 s16, 0x100
	s_mov_b32 s17, -2
	ds_read_b128 v[118:121], v197
	ds_read_b128 v[126:129], v197 offset:1024
	ds_read_b128 v[130:133], v197 offset:2048
	ds_read_b128 v[138:141], v197 offset:3072
	s_add_i32 s10, s7, 0xfffa0080
	s_cmp_eq_u32 s17, 12
	s_cselect_b32 s87, s6, s10
	s_cselect_b32 s86, s72, s16
	s_or_b32 s88, s87, 0x80
	s_add_i32 s10, s7, 0xfffe0000
	s_mov_b32 m0, s41
	ds_read_b128 v[146:149], v198
	ds_read_b128 v[150:153], v198 offset:1024
	ds_read_b128 v[154:157], v198 offset:2048
	ds_read_b128 v[158:161], v198 offset:3072
	ds_read_b128 v[162:165], v198 offset:4096
	ds_read_b128 v[166:169], v198 offset:5120
	ds_read_b128 v[170:173], v198 offset:6144
	ds_read_b128 v[174:177], v198 offset:7168
	buffer_load_dwordx4 v1, s[48:51], s10 offen lds
	s_mov_b32 m0, s42
	s_nop 0
	buffer_load_dwordx4 v1, s[48:51], s7 offen lds
	s_waitcnt lgkmcnt(8)
	s_barrier
	s_waitcnt lgkmcnt(0)
	s_setprio 1
	s_waitcnt lgkmcnt(7)
	v_mfma_f32_16x16x32_bf16 v[142:145], v[118:121], v[146:149], 0
	v_mfma_f32_16x16x32_bf16 v[134:137], v[130:133], v[146:149], 0
	s_waitcnt lgkmcnt(5)
	v_mfma_f32_16x16x32_bf16 v[122:125], v[118:121], v[154:157], 0
	v_mfma_f32_16x16x32_bf16 v[114:117], v[130:133], v[154:157], 0
	s_waitcnt lgkmcnt(3)
	v_mfma_f32_16x16x32_bf16 v[94:97], v[118:121], v[162:165], 0
	v_mfma_f32_16x16x32_bf16 v[90:93], v[130:133], v[162:165], 0
	s_waitcnt lgkmcnt(1)
	v_mfma_f32_16x16x32_bf16 v[82:85], v[118:121], v[170:173], 0
	v_mfma_f32_16x16x32_bf16 v[74:77], v[130:133], v[170:173], 0
	v_mfma_f32_16x16x32_bf16 v[142:145], v[126:129], v[150:153], v[142:145]
	v_mfma_f32_16x16x32_bf16 v[134:137], v[138:141], v[150:153], v[134:137]
	v_mfma_f32_16x16x32_bf16 v[122:125], v[126:129], v[158:161], v[122:125]
	v_mfma_f32_16x16x32_bf16 v[114:117], v[138:141], v[158:161], v[114:117]
	v_mfma_f32_16x16x32_bf16 v[94:97], v[126:129], v[166:169], v[94:97]
	v_mfma_f32_16x16x32_bf16 v[90:93], v[138:141], v[166:169], v[90:93]
	s_waitcnt lgkmcnt(0)
	v_mfma_f32_16x16x32_bf16 v[82:85], v[126:129], v[174:177], v[82:85]
	v_mfma_f32_16x16x32_bf16 v[74:77], v[138:141], v[174:177], v[74:77]
	s_setprio 0
	s_barrier
	s_mov_b32 m0, s21
	s_mov_b32 s10, s50
	s_mov_b32 s11, s51
	ds_read_b128 v[178:181], v199
	ds_read_b128 v[182:185], v199 offset:1024
	ds_read_b128 v[190:193], v199 offset:2048
	ds_read_b128 v[202:205], v199 offset:3072
	buffer_load_dwordx4 v194, s[8:11], s86 offen lds
	s_add_i32 s33, s86, 0x20000
	s_mov_b32 m0, s22
	s_nop 0
	buffer_load_dwordx4 v194, s[8:11], s33 offen lds
	s_barrier
	s_waitcnt lgkmcnt(0)
	s_setprio 1
	s_waitcnt lgkmcnt(3)
	v_mfma_f32_16x16x32_bf16 v[110:113], v[178:181], v[146:149], 0
	s_waitcnt lgkmcnt(1)
	v_mfma_f32_16x16x32_bf16 v[106:109], v[190:193], v[146:149], 0
	v_mfma_f32_16x16x32_bf16 v[102:105], v[178:181], v[154:157], 0
	v_mfma_f32_16x16x32_bf16 v[98:101], v[190:193], v[154:157], 0
	v_mfma_f32_16x16x32_bf16 v[86:89], v[178:181], v[162:165], 0
	v_mfma_f32_16x16x32_bf16 v[78:81], v[190:193], v[162:165], 0
	v_mfma_f32_16x16x32_bf16 v[70:73], v[178:181], v[170:173], 0
	v_mfma_f32_16x16x32_bf16 v[66:69], v[190:193], v[170:173], 0
	v_mfma_f32_16x16x32_bf16 v[110:113], v[182:185], v[150:153], v[110:113]
	s_waitcnt lgkmcnt(0)
	v_mfma_f32_16x16x32_bf16 v[106:109], v[202:205], v[150:153], v[106:109]
	v_mfma_f32_16x16x32_bf16 v[102:105], v[182:185], v[158:161], v[102:105]
	v_mfma_f32_16x16x32_bf16 v[98:101], v[202:205], v[158:161], v[98:101]
	v_mfma_f32_16x16x32_bf16 v[86:89], v[182:185], v[166:169], v[86:89]
	v_mfma_f32_16x16x32_bf16 v[78:81], v[202:205], v[166:169], v[78:81]
	v_mfma_f32_16x16x32_bf16 v[70:73], v[182:185], v[174:177], v[70:73]
	v_mfma_f32_16x16x32_bf16 v[66:69], v[202:205], v[174:177], v[66:69]
	s_setprio 0
	s_mov_b32 m0, s20
	s_barrier
	ds_read_b128 v[146:149], v198 offset:16384
	ds_read_b128 v[150:153], v198 offset:17408
	ds_read_b128 v[154:157], v198 offset:18432
	ds_read_b128 v[158:161], v198 offset:19456
	ds_read_b128 v[162:165], v198 offset:20480
	ds_read_b128 v[166:169], v198 offset:21504
	ds_read_b128 v[170:173], v198 offset:22528
	ds_read_b128 v[174:177], v198 offset:23552
	buffer_load_dwordx4 v1, s[48:51], s87 offen lds
	s_add_i32 s33, s87, 0x20000
	s_mov_b32 m0, s23
	s_nop 0
	buffer_load_dwordx4 v1, s[48:51], s33 offen lds
	s_barrier
	s_waitcnt lgkmcnt(0)
	s_setprio 1
	s_waitcnt lgkmcnt(7)
	v_mfma_f32_16x16x32_bf16 v[62:65], v[118:121], v[146:149], 0
	v_mfma_f32_16x16x32_bf16 v[58:61], v[130:133], v[146:149], 0
	s_waitcnt lgkmcnt(5)
	v_mfma_f32_16x16x32_bf16 v[50:53], v[118:121], v[154:157], 0
	v_mfma_f32_16x16x32_bf16 v[42:45], v[130:133], v[154:157], 0
	s_waitcnt lgkmcnt(3)
	v_mfma_f32_16x16x32_bf16 v[34:37], v[118:121], v[162:165], 0
	v_mfma_f32_16x16x32_bf16 v[26:29], v[130:133], v[162:165], 0
	s_waitcnt lgkmcnt(1)
	v_mfma_f32_16x16x32_bf16 v[18:21], v[118:121], v[170:173], 0
	v_mfma_f32_16x16x32_bf16 v[10:13], v[130:133], v[170:173], 0
	v_mfma_f32_16x16x32_bf16 v[62:65], v[126:129], v[150:153], v[62:65]
	v_mfma_f32_16x16x32_bf16 v[58:61], v[138:141], v[150:153], v[58:61]
	v_mfma_f32_16x16x32_bf16 v[50:53], v[126:129], v[158:161], v[50:53]
	v_mfma_f32_16x16x32_bf16 v[42:45], v[138:141], v[158:161], v[42:45]
	v_mfma_f32_16x16x32_bf16 v[34:37], v[126:129], v[166:169], v[34:37]
	v_mfma_f32_16x16x32_bf16 v[26:29], v[138:141], v[166:169], v[26:29]
	s_waitcnt lgkmcnt(0)
	v_mfma_f32_16x16x32_bf16 v[18:21], v[126:129], v[174:177], v[18:21]
	v_mfma_f32_16x16x32_bf16 v[10:13], v[138:141], v[174:177], v[10:13]
	s_setprio 0
	s_barrier
	s_mov_b32 m0, s24
	s_add_i32 s33, s86, 0x40000
	buffer_load_dwordx4 v194, s[8:11], s33 offen lds
	s_add_i32 s33, s86, 0x60000
	s_mov_b32 m0, s25
	s_nop 0
	buffer_load_dwordx4 v194, s[8:11], s33 offen lds
	s_cmp_eq_u32 s100, 0
	s_cbranch_scc1 .Lfw_2_a_p
	s_waitcnt vmcnt(16)
	s_mov_b32 s100, 0
	s_branch .Lfw_2_b_p

.Lfw_2_b_p:
	s_barrier
	s_setprio 1
	v_mfma_f32_16x16x32_bf16 v[54:57], v[178:181], v[146:149], 0
	v_mfma_f32_16x16x32_bf16 v[46:49], v[190:193], v[146:149], 0
	v_mfma_f32_16x16x32_bf16 v[38:41], v[178:181], v[154:157], 0
	v_mfma_f32_16x16x32_bf16 v[30:33], v[190:193], v[154:157], 0
	v_mfma_f32_16x16x32_bf16 v[22:25], v[178:181], v[162:165], 0
	v_mfma_f32_16x16x32_bf16 v[14:17], v[190:193], v[162:165], 0
	v_mfma_f32_16x16x32_bf16 v[6:9], v[178:181], v[170:173], 0
	v_mfma_f32_16x16x32_bf16 v[2:5], v[190:193], v[170:173], 0
	v_mfma_f32_16x16x32_bf16 v[54:57], v[182:185], v[150:153], v[54:57]
	v_mfma_f32_16x16x32_bf16 v[46:49], v[202:205], v[150:153], v[46:49]
	v_mfma_f32_16x16x32_bf16 v[38:41], v[182:185], v[158:161], v[38:41]
	v_mfma_f32_16x16x32_bf16 v[30:33], v[202:205], v[158:161], v[30:33]
	v_mfma_f32_16x16x32_bf16 v[22:25], v[182:185], v[166:169], v[22:25]
	v_mfma_f32_16x16x32_bf16 v[14:17], v[202:205], v[166:169], v[14:17]
	v_mfma_f32_16x16x32_bf16 v[6:9], v[182:185], v[174:177], v[6:9]
	v_mfma_f32_16x16x32_bf16 v[2:5], v[202:205], v[174:177], v[2:5]
	s_setprio 0
	s_barrier
	ds_read_b128 v[118:121], v200
	ds_read_b128 v[126:129], v200 offset:1024
	ds_read_b128 v[130:133], v200 offset:2048
	ds_read_b128 v[138:141], v200 offset:3072
	s_mov_b32 m0, s26
	s_add_i32 s33, s87, 0x40000
	ds_read_b128 v[146:149], v198 offset:32768
	ds_read_b128 v[150:153], v198 offset:33792
	ds_read_b128 v[154:157], v198 offset:34816
	ds_read_b128 v[158:161], v198 offset:35840
	ds_read_b128 v[162:165], v198 offset:36864
	ds_read_b128 v[166:169], v198 offset:37888
	ds_read_b128 v[170:173], v198 offset:38912
	ds_read_b128 v[174:177], v198 offset:39936
	buffer_load_dwordx4 v1, s[48:51], s33 offen lds
	s_add_i32 s33, s87, 0x60000
	s_mov_b32 m0, s27
	s_nop 0
	buffer_load_dwordx4 v1, s[48:51], s33 offen lds
	s_waitcnt lgkmcnt(8)
	s_barrier
	s_waitcnt lgkmcnt(0)
	s_setprio 1
	s_waitcnt lgkmcnt(7)
	v_mfma_f32_16x16x32_bf16 v[142:145], v[118:121], v[146:149], v[142:145]
	v_mfma_f32_16x16x32_bf16 v[134:137], v[130:133], v[146:149], v[134:137]
	s_waitcnt lgkmcnt(5)
	v_mfma_f32_16x16x32_bf16 v[122:125], v[118:121], v[154:157], v[122:125]
	v_mfma_f32_16x16x32_bf16 v[114:117], v[130:133], v[154:157], v[114:117]
	s_waitcnt lgkmcnt(3)
	v_mfma_f32_16x16x32_bf16 v[94:97], v[118:121], v[162:165], v[94:97]
	v_mfma_f32_16x16x32_bf16 v[90:93], v[130:133], v[162:165], v[90:93]
	s_waitcnt lgkmcnt(1)
	v_mfma_f32_16x16x32_bf16 v[82:85], v[118:121], v[170:173], v[82:85]
	v_mfma_f32_16x16x32_bf16 v[74:77], v[130:133], v[170:173], v[74:77]
	v_mfma_f32_16x16x32_bf16 v[142:145], v[126:129], v[150:153], v[142:145]
	v_mfma_f32_16x16x32_bf16 v[134:137], v[138:141], v[150:153], v[134:137]
	v_mfma_f32_16x16x32_bf16 v[122:125], v[126:129], v[158:161], v[122:125]
	v_mfma_f32_16x16x32_bf16 v[114:117], v[138:141], v[158:161], v[114:117]
	v_mfma_f32_16x16x32_bf16 v[94:97], v[126:129], v[166:169], v[94:97]
	v_mfma_f32_16x16x32_bf16 v[90:93], v[138:141], v[166:169], v[90:93]
	s_waitcnt lgkmcnt(0)
	v_mfma_f32_16x16x32_bf16 v[82:85], v[126:129], v[174:177], v[82:85]
	v_mfma_f32_16x16x32_bf16 v[74:77], v[138:141], v[174:177], v[74:77]
	s_setprio 0
	s_barrier
	s_mov_b32 m0, s34
	s_add_i32 s33, s86, 0x80
	ds_read_b128 v[178:181], v201
	ds_read_b128 v[182:185], v201 offset:1024
	ds_read_b128 v[190:193], v201 offset:2048
	ds_read_b128 v[202:205], v201 offset:3072
	buffer_load_dwordx4 v194, s[8:11], s33 offen lds
	s_add_i32 s33, s86, 0x20080
	s_mov_b32 m0, s35
	s_nop 0
	buffer_load_dwordx4 v194, s[8:11], s33 offen lds
	s_waitcnt vmcnt(10)
	s_barrier
	s_waitcnt lgkmcnt(0)
	s_setprio 1
	s_waitcnt lgkmcnt(3)
	v_mfma_f32_16x16x32_bf16 v[110:113], v[178:181], v[146:149], v[110:113]
	s_waitcnt lgkmcnt(1)
	v_mfma_f32_16x16x32_bf16 v[106:109], v[190:193], v[146:149], v[106:109]
	v_mfma_f32_16x16x32_bf16 v[102:105], v[178:181], v[154:157], v[102:105]
	v_mfma_f32_16x16x32_bf16 v[98:101], v[190:193], v[154:157], v[98:101]
	v_mfma_f32_16x16x32_bf16 v[86:89], v[178:181], v[162:165], v[86:89]
	v_mfma_f32_16x16x32_bf16 v[78:81], v[190:193], v[162:165], v[78:81]
	v_mfma_f32_16x16x32_bf16 v[70:73], v[178:181], v[170:173], v[70:73]
	v_mfma_f32_16x16x32_bf16 v[66:69], v[190:193], v[170:173], v[66:69]
	v_mfma_f32_16x16x32_bf16 v[110:113], v[182:185], v[150:153], v[110:113]
	s_waitcnt lgkmcnt(0)
	v_mfma_f32_16x16x32_bf16 v[106:109], v[202:205], v[150:153], v[106:109]
	v_mfma_f32_16x16x32_bf16 v[102:105], v[182:185], v[158:161], v[102:105]
	v_mfma_f32_16x16x32_bf16 v[98:101], v[202:205], v[158:161], v[98:101]
	v_mfma_f32_16x16x32_bf16 v[86:89], v[182:185], v[166:169], v[86:89]
	v_mfma_f32_16x16x32_bf16 v[78:81], v[202:205], v[166:169], v[78:81]
	v_mfma_f32_16x16x32_bf16 v[70:73], v[182:185], v[174:177], v[70:73]
	v_mfma_f32_16x16x32_bf16 v[66:69], v[202:205], v[174:177], v[66:69]
	s_setprio 0
	s_mov_b32 m0, s36
	s_barrier
	ds_read_b128 v[146:149], v198 offset:49152
	ds_read_b128 v[150:153], v198 offset:50176
	ds_read_b128 v[154:157], v198 offset:51200
	ds_read_b128 v[158:161], v198 offset:52224
	ds_read_b128 v[162:165], v198 offset:53248
	ds_read_b128 v[166:169], v198 offset:54272
	ds_read_b128 v[170:173], v198 offset:55296
	ds_read_b128 v[174:177], v198 offset:56320
	buffer_load_dwordx4 v1, s[48:51], s88 offen lds
	s_add_i32 s87, s87, 0x20080
	s_mov_b32 m0, s37
	s_nop 0
	buffer_load_dwordx4 v1, s[48:51], s87 offen lds
	s_barrier
	s_waitcnt lgkmcnt(0)
	s_setprio 1
	s_waitcnt lgkmcnt(7)
	v_mfma_f32_16x16x32_bf16 v[62:65], v[118:121], v[146:149], v[62:65]
	v_mfma_f32_16x16x32_bf16 v[58:61], v[130:133], v[146:149], v[58:61]
	s_waitcnt lgkmcnt(5)
	v_mfma_f32_16x16x32_bf16 v[50:53], v[118:121], v[154:157], v[50:53]
	v_mfma_f32_16x16x32_bf16 v[42:45], v[130:133], v[154:157], v[42:45]
	s_waitcnt lgkmcnt(3)
	v_mfma_f32_16x16x32_bf16 v[34:37], v[118:121], v[162:165], v[34:37]
	v_mfma_f32_16x16x32_bf16 v[26:29], v[130:133], v[162:165], v[26:29]
	s_waitcnt lgkmcnt(1)
	v_mfma_f32_16x16x32_bf16 v[18:21], v[118:121], v[170:173], v[18:21]
	v_mfma_f32_16x16x32_bf16 v[10:13], v[130:133], v[170:173], v[10:13]
	v_mfma_f32_16x16x32_bf16 v[62:65], v[126:129], v[150:153], v[62:65]
	v_mfma_f32_16x16x32_bf16 v[58:61], v[138:141], v[150:153], v[58:61]
	v_mfma_f32_16x16x32_bf16 v[50:53], v[126:129], v[158:161], v[50:53]
	v_mfma_f32_16x16x32_bf16 v[42:45], v[138:141], v[158:161], v[42:45]
	v_mfma_f32_16x16x32_bf16 v[34:37], v[126:129], v[166:169], v[34:37]
	v_mfma_f32_16x16x32_bf16 v[26:29], v[138:141], v[166:169], v[26:29]
	s_waitcnt lgkmcnt(0)
	v_mfma_f32_16x16x32_bf16 v[18:21], v[126:129], v[174:177], v[18:21]
	v_mfma_f32_16x16x32_bf16 v[10:13], v[138:141], v[174:177], v[10:13]
	s_setprio 0
	s_barrier
	s_mov_b32 m0, s38
	s_add_i32 s33, s86, 0x40080
	buffer_load_dwordx4 v194, s[8:11], s33 offen lds
	s_add_i32 s86, s86, 0x60080
	s_mov_b32 m0, s39
	s_nop 0
	buffer_load_dwordx4 v194, s[8:11], s86 offen lds
	s_waitcnt vmcnt(6)
	s_barrier
	s_setprio 1
	v_mfma_f32_16x16x32_bf16 v[54:57], v[178:181], v[146:149], v[54:57]
	v_mfma_f32_16x16x32_bf16 v[46:49], v[190:193], v[146:149], v[46:49]
	v_mfma_f32_16x16x32_bf16 v[38:41], v[178:181], v[154:157], v[38:41]
	v_mfma_f32_16x16x32_bf16 v[30:33], v[190:193], v[154:157], v[30:33]
	v_mfma_f32_16x16x32_bf16 v[22:25], v[178:181], v[162:165], v[22:25]
	v_mfma_f32_16x16x32_bf16 v[14:17], v[190:193], v[162:165], v[14:17]
	v_mfma_f32_16x16x32_bf16 v[6:9], v[178:181], v[170:173], v[6:9]
	v_mfma_f32_16x16x32_bf16 v[2:5], v[190:193], v[170:173], v[2:5]
	v_mfma_f32_16x16x32_bf16 v[54:57], v[182:185], v[150:153], v[54:57]
	v_mfma_f32_16x16x32_bf16 v[46:49], v[202:205], v[150:153], v[46:49]
	v_mfma_f32_16x16x32_bf16 v[38:41], v[182:185], v[158:161], v[38:41]
	v_mfma_f32_16x16x32_bf16 v[30:33], v[202:205], v[158:161], v[30:33]
	v_mfma_f32_16x16x32_bf16 v[22:25], v[182:185], v[166:169], v[22:25]
	v_mfma_f32_16x16x32_bf16 v[14:17], v[202:205], v[166:169], v[14:17]
	v_mfma_f32_16x16x32_bf16 v[6:9], v[182:185], v[174:177], v[6:9]
	v_mfma_f32_16x16x32_bf16 v[2:5], v[202:205], v[174:177], v[2:5]
	s_setprio 0
	s_add_i32 s17, s17, 2
	s_addk_i32 s7, 0x100
	s_addk_i32 s16, 0x100
	s_cmp_gt_u32 s17, 13
	s_barrier

.LBB0_839:
	s_lshl_b32 s59, s57, 18
	s_and_b64 s[6:7], s[6:7], exec
	v_mov_b32_e32 v2, 0
	s_cselect_b32 s6, s59, s79
	s_add_i32 s7, s79, 0x30080
	s_addk_i32 s78, 0x100
	s_mov_b32 s79, -2
	ds_read_b128 v[142:145], v137
	ds_read_b128 v[146:149], v137 offset:1024
	ds_read_b128 v[150:153], v137 offset:2048
	ds_read_b128 v[154:157], v137 offset:3072
	s_add_i32 s10, s7, 0xfffd0080
	s_cmp_eq_u32 s79, 4
	s_cselect_b32 s87, s6, s10
	s_cselect_b32 s86, s58, s78
	s_or_b32 s88, s87, 0x80
	s_add_i32 s10, s7, 0xffff0000
	s_mov_b32 m0, s39
	ds_read_b128 v[158:161], v138
	ds_read_b128 v[162:165], v138 offset:1024
	ds_read_b128 v[166:169], v138 offset:2048
	ds_read_b128 v[170:173], v138 offset:3072
	ds_read_b128 v[174:177], v138 offset:4096
	ds_read_b128 v[178:181], v138 offset:5120
	ds_read_b128 v[182:185], v138 offset:6144
	ds_read_b128 v[186:189], v138 offset:7168
	buffer_load_dwordx4 v1, s[44:47], s10 offen lds
	s_mov_b32 m0, s41
	s_nop 0
	buffer_load_dwordx4 v1, s[44:47], s7 offen lds
	s_waitcnt lgkmcnt(8)
	s_barrier
	s_waitcnt lgkmcnt(0)
	s_setprio 1
	s_waitcnt lgkmcnt(4)
	v_mfma_f32_16x16x128_f8f6f4 v[114:117], v[142:149], v[166:173], 0
	v_mfma_f32_16x16x128_f8f6f4 v[106:109], v[150:157], v[166:173], 0
	s_waitcnt lgkmcnt(2)
	v_mfma_f32_16x16x128_f8f6f4 v[98:101], v[142:149], v[174:181], 0
	v_mfma_f32_16x16x128_f8f6f4 v[198:201], v[142:149], v[158:165], 0
	v_mfma_f32_16x16x128_f8f6f4 v[202:205], v[150:157], v[158:165], 0
	v_mfma_f32_16x16x128_f8f6f4 v[206:209], v[150:157], v[174:181], 0
	s_waitcnt lgkmcnt(0)
	v_mfma_f32_16x16x128_f8f6f4 v[210:213], v[142:149], v[182:189], 0
	v_mfma_f32_16x16x128_f8f6f4 v[214:217], v[150:157], v[182:189], 0
	s_setprio 0
	s_barrier
	s_mov_b32 m0, s23
	s_mov_b32 s10, s46
	s_mov_b32 s11, s47
	ds_read_b128 v[122:125], v139
	ds_read_b128 v[126:129], v139 offset:1024
	ds_read_b128 v[190:193], v139 offset:2048
	ds_read_b128 v[194:197], v139 offset:3072
	buffer_load_dwordx4 v134, s[8:11], s86 offen lds
	s_add_i32 s33, s86, 0x10000
	s_mov_b32 m0, s24
	s_nop 0
	buffer_load_dwordx4 v134, s[8:11], s33 offen lds
	s_barrier
	s_waitcnt lgkmcnt(0)
	s_setprio 1
	s_waitcnt lgkmcnt(2)
	v_mfma_f32_16x16x128_f8f6f4 v[118:121], v[122:129], v[158:165], 0
	s_waitcnt lgkmcnt(0)
	v_mfma_f32_16x16x128_f8f6f4 v[110:113], v[190:197], v[158:165], 0
	v_mfma_f32_16x16x128_f8f6f4 v[102:105], v[122:129], v[166:173], 0
	v_mfma_f32_16x16x128_f8f6f4 v[158:161], v[190:197], v[166:173], 0
	v_mfma_f32_16x16x128_f8f6f4 v[162:165], v[122:129], v[174:181], 0
	v_mfma_f32_16x16x128_f8f6f4 v[166:169], v[190:197], v[174:181], 0
	v_mfma_f32_16x16x128_f8f6f4 v[170:173], v[122:129], v[182:189], 0
	v_mfma_f32_16x16x128_f8f6f4 v[174:177], v[190:197], v[182:189], 0
	s_setprio 0
	s_mov_b32 m0, s22
	s_barrier
	ds_read_b128 v[66:69], v138 offset:16384
	s_nop 1
	ds_read_b128 v[70:73], v138 offset:17408
	ds_read_b128 v[74:77], v138 offset:18432
	ds_read_b128 v[78:81], v138 offset:19456
	ds_read_b128 v[82:85], v138 offset:20480
	ds_read_b128 v[86:89], v138 offset:21504
	ds_read_b128 v[90:93], v138 offset:22528
	ds_read_b128 v[94:97], v138 offset:23552
	buffer_load_dwordx4 v1, s[44:47], s87 offen lds
	s_add_i32 s33, s87, 0x10000
	s_mov_b32 m0, s25
	s_nop 0
	buffer_load_dwordx4 v1, s[44:47], s33 offen lds
	s_barrier
	s_waitcnt lgkmcnt(0)
	s_setprio 1
	s_waitcnt lgkmcnt(6)
	v_mfma_f32_16x16x128_f8f6f4 v[62:65], v[142:149], v[66:73], 0
	v_mfma_f32_16x16x128_f8f6f4 v[58:61], v[150:157], v[66:73], 0
	s_waitcnt lgkmcnt(4)
	v_mfma_f32_16x16x128_f8f6f4 v[50:53], v[142:149], v[74:81], 0
	s_waitcnt lgkmcnt(0)
	v_mfma_f32_16x16x128_f8f6f4 v[230:233], v[142:149], v[90:97], 0
	v_mfma_f32_16x16x128_f8f6f4 v[218:221], v[150:157], v[74:81], 0
	v_mfma_f32_16x16x128_f8f6f4 v[222:225], v[142:149], v[82:89], 0
	v_mfma_f32_16x16x128_f8f6f4 v[226:229], v[150:157], v[82:89], 0
	v_mfma_f32_16x16x128_f8f6f4 v[234:237], v[150:157], v[90:97], 0
	s_setprio 0
	s_barrier
	s_mov_b32 m0, s26
	s_add_i32 s33, s86, 0x20000
	buffer_load_dwordx4 v134, s[8:11], s33 offen lds
	s_add_i32 s33, s86, 0x30000
	s_mov_b32 m0, s27
	s_nop 0
	buffer_load_dwordx4 v134, s[8:11], s33 offen lds
	s_cmp_eq_u32 s100, 0
	s_cbranch_scc1 .Lfw_4_a_p
	s_waitcnt vmcnt(16)
	s_mov_b32 s100, 0
	s_branch .Lfw_4_b_p

.Lfw_4_b_p:
	s_barrier
	s_setprio 1
	v_mfma_f32_16x16x128_f8f6f4 v[54:57], v[122:129], v[66:73], 0
	v_mfma_f32_16x16x128_f8f6f4 v[238:241], v[190:197], v[66:73], 0
	v_mfma_f32_16x16x128_f8f6f4 v[242:245], v[122:129], v[74:81], 0
	v_mfma_f32_16x16x128_f8f6f4 v[246:249], v[190:197], v[74:81], 0
	v_mfma_f32_16x16x128_f8f6f4 v[250:253], v[122:129], v[82:89], 0
	v_mfma_f32_16x16x128_f8f6f4 v[130:133], v[190:197], v[82:89], 0
	v_mfma_f32_16x16x128_f8f6f4 v[66:69], v[122:129], v[90:97], 0
	v_mfma_f32_16x16x128_f8f6f4 v[190:193], v[190:197], v[90:97], 0
	s_setprio 0
	s_barrier
	s_nop 4
	ds_read_b128 v[2:5], v140
	ds_read_b128 v[6:9], v140 offset:1024
	ds_read_b128 v[10:13], v140 offset:2048
	ds_read_b128 v[14:17], v140 offset:3072
	s_mov_b32 m0, s28
	s_add_i32 s33, s87, 0x20000
	ds_read_b128 v[18:21], v138 offset:32768
	ds_read_b128 v[22:25], v138 offset:33792
	ds_read_b128 v[26:29], v138 offset:34816
	ds_read_b128 v[30:33], v138 offset:35840
	ds_read_b128 v[34:37], v138 offset:36864
	ds_read_b128 v[38:41], v138 offset:37888
	ds_read_b128 v[42:45], v138 offset:38912
	ds_read_b128 v[46:49], v138 offset:39936
	buffer_load_dwordx4 v1, s[44:47], s33 offen lds
	s_add_i32 s33, s87, 0x30000
	s_mov_b32 m0, s29
	s_nop 0
	buffer_load_dwordx4 v1, s[44:47], s33 offen lds
	s_waitcnt lgkmcnt(8)
	s_barrier
	s_waitcnt lgkmcnt(0)
	s_setprio 1
	s_waitcnt lgkmcnt(6)
	v_mfma_f32_16x16x128_f8f6f4 v[126:129], v[2:9], v[18:25], v[198:201]
	v_mfma_f32_16x16x128_f8f6f4 v[122:125], v[10:17], v[18:25], v[202:205]
	s_waitcnt lgkmcnt(4)
	v_mfma_f32_16x16x128_f8f6f4 v[114:117], v[2:9], v[26:33], v[114:117]
	v_mfma_f32_16x16x128_f8f6f4 v[106:109], v[10:17], v[26:33], v[106:109]
	s_waitcnt lgkmcnt(2)
	v_mfma_f32_16x16x128_f8f6f4 v[98:101], v[2:9], v[34:41], v[98:101]
	v_mfma_f32_16x16x128_f8f6f4 v[90:93], v[10:17], v[34:41], v[206:209]
	s_waitcnt lgkmcnt(0)
	v_mfma_f32_16x16x128_f8f6f4 v[82:85], v[2:9], v[42:49], v[210:213]
	v_mfma_f32_16x16x128_f8f6f4 v[74:77], v[10:17], v[42:49], v[214:217]
	s_setprio 0
	s_barrier
	s_mov_b32 m0, s31
	s_add_i32 s33, s86, 0x80
	ds_read_b128 v[142:145], v141
	ds_read_b128 v[146:149], v141 offset:1024
	ds_read_b128 v[150:153], v141 offset:2048
	ds_read_b128 v[154:157], v141 offset:3072
	buffer_load_dwordx4 v134, s[8:11], s33 offen lds
	s_add_i32 s33, s86, 0x10080
	s_mov_b32 m0, s34
	s_nop 0
	buffer_load_dwordx4 v134, s[8:11], s33 offen lds
	s_waitcnt vmcnt(10)
	s_barrier
	s_waitcnt lgkmcnt(0)
	s_setprio 1
	s_waitcnt lgkmcnt(2)
	v_mfma_f32_16x16x128_f8f6f4 v[118:121], v[142:149], v[18:25], v[118:121]
	s_waitcnt lgkmcnt(0)
	v_mfma_f32_16x16x128_f8f6f4 v[110:113], v[150:157], v[18:25], v[110:113]
	v_mfma_f32_16x16x128_f8f6f4 v[102:105], v[142:149], v[26:33], v[102:105]
	v_mfma_f32_16x16x128_f8f6f4 v[94:97], v[150:157], v[26:33], v[158:161]
	v_mfma_f32_16x16x128_f8f6f4 v[86:89], v[142:149], v[34:41], v[162:165]
	v_mfma_f32_16x16x128_f8f6f4 v[78:81], v[150:157], v[34:41], v[166:169]
	v_mfma_f32_16x16x128_f8f6f4 v[70:73], v[142:149], v[42:49], v[170:173]
	v_mfma_f32_16x16x128_f8f6f4 v[18:21], v[150:157], v[42:49], v[174:177]
	s_setprio 0
	s_mov_b32 m0, s35
	s_barrier
	ds_read_b128 v[158:161], v138 offset:49152
	ds_read_b128 v[162:165], v138 offset:50176
	ds_read_b128 v[166:169], v138 offset:51200
	ds_read_b128 v[170:173], v138 offset:52224
	ds_read_b128 v[174:177], v138 offset:53248
	ds_read_b128 v[178:181], v138 offset:54272
	ds_read_b128 v[182:185], v138 offset:55296
	ds_read_b128 v[186:189], v138 offset:56320
	buffer_load_dwordx4 v1, s[44:47], s88 offen lds
	s_add_i32 s87, s87, 0x10080
	s_mov_b32 m0, s36
	s_nop 0
	buffer_load_dwordx4 v1, s[44:47], s87 offen lds
	s_barrier
	s_waitcnt lgkmcnt(0)
	s_setprio 1
	s_waitcnt lgkmcnt(6)
	v_mfma_f32_16x16x128_f8f6f4 v[62:65], v[2:9], v[158:165], v[62:65]
	v_mfma_f32_16x16x128_f8f6f4 v[58:61], v[10:17], v[158:165], v[58:61]
	s_waitcnt lgkmcnt(4)
	v_mfma_f32_16x16x128_f8f6f4 v[50:53], v[2:9], v[166:173], v[50:53]
	v_mfma_f32_16x16x128_f8f6f4 v[42:45], v[10:17], v[166:173], v[218:221]
	s_waitcnt lgkmcnt(2)
	v_mfma_f32_16x16x128_f8f6f4 v[34:37], v[2:9], v[174:181], v[222:225]
	v_mfma_f32_16x16x128_f8f6f4 v[26:29], v[10:17], v[174:181], v[226:229]
	s_waitcnt lgkmcnt(0)
	v_mfma_f32_16x16x128_f8f6f4 v[230:233], v[2:9], v[182:189], v[230:233]
	v_mfma_f32_16x16x128_f8f6f4 v[10:13], v[10:17], v[182:189], v[234:237]
	s_setprio 0
	s_barrier
	s_mov_b32 m0, s37
	s_add_i32 s33, s86, 0x20080
	buffer_load_dwordx4 v134, s[8:11], s33 offen lds
	s_add_i32 s86, s86, 0x30080
	s_mov_b32 m0, s38
	s_nop 0
	buffer_load_dwordx4 v134, s[8:11], s86 offen lds
	s_waitcnt vmcnt(6)
	s_barrier
	s_setprio 1
	v_mfma_f32_16x16x128_f8f6f4 v[54:57], v[142:149], v[158:165], v[54:57]
	v_mfma_f32_16x16x128_f8f6f4 v[46:49], v[150:157], v[158:165], v[238:241]
	v_mfma_f32_16x16x128_f8f6f4 v[38:41], v[142:149], v[166:173], v[242:245]
	v_mfma_f32_16x16x128_f8f6f4 v[30:33], v[150:157], v[166:173], v[246:249]
	v_mfma_f32_16x16x128_f8f6f4 v[22:25], v[142:149], v[174:181], v[250:253]
	v_mfma_f32_16x16x128_f8f6f4 v[14:17], v[150:157], v[174:181], v[130:133]
	v_mfma_f32_16x16x128_f8f6f4 v[6:9], v[142:149], v[182:189], v[66:69]
	v_mfma_f32_16x16x128_f8f6f4 v[2:5], v[150:157], v[182:189], v[190:193]
	s_setprio 0
	s_add_i32 s79, s79, 2
	s_addk_i32 s7, 0x100
	s_addk_i32 s78, 0x100
	s_cmp_gt_u32 s79, 5
	s_barrier

.LBB0_1019:
	s_lshl_b32 s38, s36, 19
	s_and_b64 s[6:7], s[6:7], exec
	v_mov_b32_e32 v2, 0
	s_cselect_b32 s6, s38, s47
	s_add_i32 s7, s47, 0x60080
	s_addk_i32 s46, 0x100
	s_mov_b32 s47, -2
	ds_read_b128 v[134:137], v141
	ds_read_b128 v[146:149], v141 offset:1024
	ds_read_b128 v[150:153], v141 offset:2048
	ds_read_b128 v[154:157], v141 offset:3072
	s_add_i32 s10, s7, 0xfffa0080
	s_cmp_eq_u32 s47, 12
	s_cselect_b32 s50, s6, s10
	s_cselect_b32 s49, s37, s46
	s_or_b32 s51, s50, 0x80
	s_add_i32 s10, s7, 0xfffe0000
	s_mov_b32 m0, s29
	ds_read_b128 v[158:161], v142
	ds_read_b128 v[162:165], v142 offset:1024
	ds_read_b128 v[166:169], v142 offset:2048
	ds_read_b128 v[170:173], v142 offset:3072
	ds_read_b128 v[174:177], v142 offset:4096
	ds_read_b128 v[178:181], v142 offset:5120
	ds_read_b128 v[182:185], v142 offset:6144
	ds_read_b128 v[186:189], v142 offset:7168
	buffer_load_dwordx4 v1, s[40:43], s10 offen lds
	s_mov_b32 m0, s30
	s_nop 0
	buffer_load_dwordx4 v1, s[40:43], s7 offen lds
	s_waitcnt lgkmcnt(8)
	s_barrier
	s_waitcnt lgkmcnt(0)
	s_setprio 1
	s_waitcnt lgkmcnt(7)
	v_mfma_f32_16x16x32_bf16 v[126:129], v[134:137], v[158:161], 0
	v_mfma_f32_16x16x32_bf16 v[122:125], v[150:153], v[158:161], 0
	s_waitcnt lgkmcnt(5)
	v_mfma_f32_16x16x32_bf16 v[118:121], v[134:137], v[166:169], 0
	v_mfma_f32_16x16x32_bf16 v[110:113], v[150:153], v[166:169], 0
	s_waitcnt lgkmcnt(3)
	v_mfma_f32_16x16x32_bf16 v[102:105], v[134:137], v[174:177], 0
	v_mfma_f32_16x16x32_bf16 v[94:97], v[150:153], v[174:177], 0
	s_waitcnt lgkmcnt(1)
	v_mfma_f32_16x16x32_bf16 v[86:89], v[134:137], v[182:185], 0
	v_mfma_f32_16x16x32_bf16 v[78:81], v[150:153], v[182:185], 0
	v_mfma_f32_16x16x32_bf16 v[126:129], v[146:149], v[162:165], v[126:129]
	v_mfma_f32_16x16x32_bf16 v[122:125], v[154:157], v[162:165], v[122:125]
	v_mfma_f32_16x16x32_bf16 v[118:121], v[146:149], v[170:173], v[118:121]
	v_mfma_f32_16x16x32_bf16 v[110:113], v[154:157], v[170:173], v[110:113]
	v_mfma_f32_16x16x32_bf16 v[102:105], v[146:149], v[178:181], v[102:105]
	v_mfma_f32_16x16x32_bf16 v[94:97], v[154:157], v[178:181], v[94:97]
	s_waitcnt lgkmcnt(0)
	v_mfma_f32_16x16x32_bf16 v[86:89], v[146:149], v[186:189], v[86:89]
	v_mfma_f32_16x16x32_bf16 v[78:81], v[154:157], v[186:189], v[78:81]
	s_setprio 0
	s_barrier
	s_mov_b32 m0, s15
	s_mov_b32 s10, s42
	s_mov_b32 s11, s43
	ds_read_b128 v[190:193], v143
	ds_read_b128 v[194:197], v143 offset:1024
	ds_read_b128 v[198:201], v143 offset:2048
	ds_read_b128 v[202:205], v143 offset:3072
	buffer_load_dwordx4 v138, s[8:11], s49 offen lds
	s_add_i32 s33, s49, 0x20000
	s_mov_b32 m0, s16
	s_nop 0
	buffer_load_dwordx4 v138, s[8:11], s33 offen lds
	s_barrier
	s_waitcnt lgkmcnt(0)
	s_setprio 1
	s_waitcnt lgkmcnt(3)
	v_mfma_f32_16x16x32_bf16 v[114:117], v[190:193], v[158:161], 0
	s_waitcnt lgkmcnt(1)
	v_mfma_f32_16x16x32_bf16 v[106:109], v[198:201], v[158:161], 0
	v_mfma_f32_16x16x32_bf16 v[98:101], v[190:193], v[166:169], 0
	v_mfma_f32_16x16x32_bf16 v[90:93], v[198:201], v[166:169], 0
	v_mfma_f32_16x16x32_bf16 v[82:85], v[190:193], v[174:177], 0
	v_mfma_f32_16x16x32_bf16 v[74:77], v[198:201], v[174:177], 0
	v_mfma_f32_16x16x32_bf16 v[70:73], v[190:193], v[182:185], 0
	v_mfma_f32_16x16x32_bf16 v[66:69], v[198:201], v[182:185], 0
	v_mfma_f32_16x16x32_bf16 v[114:117], v[194:197], v[162:165], v[114:117]
	s_waitcnt lgkmcnt(0)
	v_mfma_f32_16x16x32_bf16 v[106:109], v[202:205], v[162:165], v[106:109]
	v_mfma_f32_16x16x32_bf16 v[98:101], v[194:197], v[170:173], v[98:101]
	v_mfma_f32_16x16x32_bf16 v[90:93], v[202:205], v[170:173], v[90:93]
	v_mfma_f32_16x16x32_bf16 v[82:85], v[194:197], v[178:181], v[82:85]
	v_mfma_f32_16x16x32_bf16 v[74:77], v[202:205], v[178:181], v[74:77]
	v_mfma_f32_16x16x32_bf16 v[70:73], v[194:197], v[186:189], v[70:73]
	v_mfma_f32_16x16x32_bf16 v[66:69], v[202:205], v[186:189], v[66:69]
	s_setprio 0
	s_mov_b32 m0, s14
	s_barrier
	ds_read_b128 v[158:161], v142 offset:16384
	ds_read_b128 v[162:165], v142 offset:17408
	ds_read_b128 v[166:169], v142 offset:18432
	ds_read_b128 v[170:173], v142 offset:19456
	ds_read_b128 v[174:177], v142 offset:20480
	ds_read_b128 v[178:181], v142 offset:21504
	ds_read_b128 v[182:185], v142 offset:22528
	ds_read_b128 v[186:189], v142 offset:23552
	buffer_load_dwordx4 v1, s[40:43], s50 offen lds
	s_add_i32 s33, s50, 0x20000
	s_mov_b32 m0, s17
	s_nop 0
	buffer_load_dwordx4 v1, s[40:43], s33 offen lds
	s_barrier
	s_waitcnt lgkmcnt(0)
	s_setprio 1
	s_waitcnt lgkmcnt(7)
	v_mfma_f32_16x16x32_bf16 v[62:65], v[134:137], v[158:161], 0
	v_mfma_f32_16x16x32_bf16 v[58:61], v[150:153], v[158:161], 0
	s_waitcnt lgkmcnt(5)
	v_mfma_f32_16x16x32_bf16 v[54:57], v[134:137], v[166:169], 0
	v_mfma_f32_16x16x32_bf16 v[46:49], v[150:153], v[166:169], 0
	s_waitcnt lgkmcnt(3)
	v_mfma_f32_16x16x32_bf16 v[38:41], v[134:137], v[174:177], 0
	v_mfma_f32_16x16x32_bf16 v[30:33], v[150:153], v[174:177], 0
	s_waitcnt lgkmcnt(1)
	v_mfma_f32_16x16x32_bf16 v[22:25], v[134:137], v[182:185], 0
	v_mfma_f32_16x16x32_bf16 v[14:17], v[150:153], v[182:185], 0
	v_mfma_f32_16x16x32_bf16 v[62:65], v[146:149], v[162:165], v[62:65]
	v_mfma_f32_16x16x32_bf16 v[58:61], v[154:157], v[162:165], v[58:61]
	v_mfma_f32_16x16x32_bf16 v[54:57], v[146:149], v[170:173], v[54:57]
	v_mfma_f32_16x16x32_bf16 v[46:49], v[154:157], v[170:173], v[46:49]
	v_mfma_f32_16x16x32_bf16 v[38:41], v[146:149], v[178:181], v[38:41]
	v_mfma_f32_16x16x32_bf16 v[30:33], v[154:157], v[178:181], v[30:33]
	s_waitcnt lgkmcnt(0)
	v_mfma_f32_16x16x32_bf16 v[22:25], v[146:149], v[186:189], v[22:25]
	v_mfma_f32_16x16x32_bf16 v[14:17], v[154:157], v[186:189], v[14:17]
	s_setprio 0
	s_barrier
	s_mov_b32 m0, s18
	s_add_i32 s33, s49, 0x40000
	buffer_load_dwordx4 v138, s[8:11], s33 offen lds
	s_add_i32 s33, s49, 0x60000
	s_mov_b32 m0, s19
	s_nop 0
	buffer_load_dwordx4 v138, s[8:11], s33 offen lds
	s_cmp_eq_u32 s100, 0
	s_cbranch_scc1 .Lfw_5_a_p
	s_waitcnt vmcnt(16)
	s_mov_b32 s100, 0
	s_branch .Lfw_5_b_p

.Lfw_5_b_p:
	s_barrier
	s_setprio 1
	v_mfma_f32_16x16x32_bf16 v[50:53], v[190:193], v[158:161], 0
	v_mfma_f32_16x16x32_bf16 v[42:45], v[198:201], v[158:161], 0
	v_mfma_f32_16x16x32_bf16 v[34:37], v[190:193], v[166:169], 0
	v_mfma_f32_16x16x32_bf16 v[26:29], v[198:201], v[166:169], 0
	v_mfma_f32_16x16x32_bf16 v[18:21], v[190:193], v[174:177], 0
	v_mfma_f32_16x16x32_bf16 v[10:13], v[198:201], v[174:177], 0
	v_mfma_f32_16x16x32_bf16 v[6:9], v[190:193], v[182:185], 0
	v_mfma_f32_16x16x32_bf16 v[2:5], v[198:201], v[182:185], 0
	v_mfma_f32_16x16x32_bf16 v[50:53], v[194:197], v[162:165], v[50:53]
	v_mfma_f32_16x16x32_bf16 v[42:45], v[202:205], v[162:165], v[42:45]
	v_mfma_f32_16x16x32_bf16 v[34:37], v[194:197], v[170:173], v[34:37]
	v_mfma_f32_16x16x32_bf16 v[26:29], v[202:205], v[170:173], v[26:29]
	v_mfma_f32_16x16x32_bf16 v[18:21], v[194:197], v[178:181], v[18:21]
	v_mfma_f32_16x16x32_bf16 v[10:13], v[202:205], v[178:181], v[10:13]
	v_mfma_f32_16x16x32_bf16 v[6:9], v[194:197], v[186:189], v[6:9]
	v_mfma_f32_16x16x32_bf16 v[2:5], v[202:205], v[186:189], v[2:5]
	s_setprio 0
	s_barrier
	ds_read_b128 v[134:137], v144
	ds_read_b128 v[146:149], v144 offset:1024
	ds_read_b128 v[150:153], v144 offset:2048
	ds_read_b128 v[154:157], v144 offset:3072
	s_mov_b32 m0, s20
	s_add_i32 s33, s50, 0x40000
	ds_read_b128 v[158:161], v142 offset:32768
	ds_read_b128 v[162:165], v142 offset:33792
	ds_read_b128 v[166:169], v142 offset:34816
	ds_read_b128 v[170:173], v142 offset:35840
	ds_read_b128 v[174:177], v142 offset:36864
	ds_read_b128 v[178:181], v142 offset:37888
	ds_read_b128 v[182:185], v142 offset:38912
	ds_read_b128 v[186:189], v142 offset:39936
	buffer_load_dwordx4 v1, s[40:43], s33 offen lds
	s_add_i32 s33, s50, 0x60000
	s_mov_b32 m0, s21
	s_nop 0
	buffer_load_dwordx4 v1, s[40:43], s33 offen lds
	s_waitcnt lgkmcnt(8)
	s_barrier
	s_waitcnt lgkmcnt(0)
	s_setprio 1
	s_waitcnt lgkmcnt(7)
	v_mfma_f32_16x16x32_bf16 v[126:129], v[134:137], v[158:161], v[126:129]
	v_mfma_f32_16x16x32_bf16 v[122:125], v[150:153], v[158:161], v[122:125]
	s_waitcnt lgkmcnt(5)
	v_mfma_f32_16x16x32_bf16 v[118:121], v[134:137], v[166:169], v[118:121]
	v_mfma_f32_16x16x32_bf16 v[110:113], v[150:153], v[166:169], v[110:113]
	s_waitcnt lgkmcnt(3)
	v_mfma_f32_16x16x32_bf16 v[102:105], v[134:137], v[174:177], v[102:105]
	v_mfma_f32_16x16x32_bf16 v[94:97], v[150:153], v[174:177], v[94:97]
	s_waitcnt lgkmcnt(1)
	v_mfma_f32_16x16x32_bf16 v[86:89], v[134:137], v[182:185], v[86:89]
	v_mfma_f32_16x16x32_bf16 v[78:81], v[150:153], v[182:185], v[78:81]
	v_mfma_f32_16x16x32_bf16 v[126:129], v[146:149], v[162:165], v[126:129]
	v_mfma_f32_16x16x32_bf16 v[122:125], v[154:157], v[162:165], v[122:125]
	v_mfma_f32_16x16x32_bf16 v[118:121], v[146:149], v[170:173], v[118:121]
	v_mfma_f32_16x16x32_bf16 v[110:113], v[154:157], v[170:173], v[110:113]
	v_mfma_f32_16x16x32_bf16 v[102:105], v[146:149], v[178:181], v[102:105]
	v_mfma_f32_16x16x32_bf16 v[94:97], v[154:157], v[178:181], v[94:97]
	s_waitcnt lgkmcnt(0)
	v_mfma_f32_16x16x32_bf16 v[86:89], v[146:149], v[186:189], v[86:89]
	v_mfma_f32_16x16x32_bf16 v[78:81], v[154:157], v[186:189], v[78:81]
	s_setprio 0
	s_barrier
	s_mov_b32 m0, s23
	s_or_b32 s33, s49, 0x80
	ds_read_b128 v[190:193], v145
	ds_read_b128 v[194:197], v145 offset:1024
	ds_read_b128 v[198:201], v145 offset:2048
	ds_read_b128 v[202:205], v145 offset:3072
	buffer_load_dwordx4 v138, s[8:11], s33 offen lds
	s_add_i32 s33, s49, 0x20080
	s_mov_b32 m0, s24
	s_nop 0
	buffer_load_dwordx4 v138, s[8:11], s33 offen lds
	s_waitcnt vmcnt(10)
	s_barrier
	s_waitcnt lgkmcnt(0)
	s_setprio 1
	s_waitcnt lgkmcnt(3)
	v_mfma_f32_16x16x32_bf16 v[114:117], v[190:193], v[158:161], v[114:117]
	s_waitcnt lgkmcnt(1)
	v_mfma_f32_16x16x32_bf16 v[106:109], v[198:201], v[158:161], v[106:109]
	v_mfma_f32_16x16x32_bf16 v[98:101], v[190:193], v[166:169], v[98:101]
	v_mfma_f32_16x16x32_bf16 v[90:93], v[198:201], v[166:169], v[90:93]
	v_mfma_f32_16x16x32_bf16 v[82:85], v[190:193], v[174:177], v[82:85]
	v_mfma_f32_16x16x32_bf16 v[74:77], v[198:201], v[174:177], v[74:77]
	v_mfma_f32_16x16x32_bf16 v[70:73], v[190:193], v[182:185], v[70:73]
	v_mfma_f32_16x16x32_bf16 v[66:69], v[198:201], v[182:185], v[66:69]
	v_mfma_f32_16x16x32_bf16 v[114:117], v[194:197], v[162:165], v[114:117]
	s_waitcnt lgkmcnt(0)
	v_mfma_f32_16x16x32_bf16 v[106:109], v[202:205], v[162:165], v[106:109]
	v_mfma_f32_16x16x32_bf16 v[98:101], v[194:197], v[170:173], v[98:101]
	v_mfma_f32_16x16x32_bf16 v[90:93], v[202:205], v[170:173], v[90:93]
	v_mfma_f32_16x16x32_bf16 v[82:85], v[194:197], v[178:181], v[82:85]
	v_mfma_f32_16x16x32_bf16 v[74:77], v[202:205], v[178:181], v[74:77]
	v_mfma_f32_16x16x32_bf16 v[70:73], v[194:197], v[186:189], v[70:73]
	v_mfma_f32_16x16x32_bf16 v[66:69], v[202:205], v[186:189], v[66:69]
	s_setprio 0
	s_mov_b32 m0, s25
	s_barrier
	ds_read_b128 v[158:161], v142 offset:49152
	ds_read_b128 v[162:165], v142 offset:50176
	ds_read_b128 v[166:169], v142 offset:51200
	ds_read_b128 v[170:173], v142 offset:52224
	ds_read_b128 v[174:177], v142 offset:53248
	ds_read_b128 v[178:181], v142 offset:54272
	ds_read_b128 v[182:185], v142 offset:55296
	ds_read_b128 v[186:189], v142 offset:56320
	buffer_load_dwordx4 v1, s[40:43], s51 offen lds
	s_add_i32 s50, s50, 0x20080
	s_mov_b32 m0, s26
	s_nop 0
	buffer_load_dwordx4 v1, s[40:43], s50 offen lds
	s_barrier
	s_waitcnt lgkmcnt(0)
	s_setprio 1
	s_waitcnt lgkmcnt(7)
	v_mfma_f32_16x16x32_bf16 v[62:65], v[134:137], v[158:161], v[62:65]
	v_mfma_f32_16x16x32_bf16 v[58:61], v[150:153], v[158:161], v[58:61]
	s_waitcnt lgkmcnt(5)
	v_mfma_f32_16x16x32_bf16 v[54:57], v[134:137], v[166:169], v[54:57]
	v_mfma_f32_16x16x32_bf16 v[46:49], v[150:153], v[166:169], v[46:49]
	s_waitcnt lgkmcnt(3)
	v_mfma_f32_16x16x32_bf16 v[38:41], v[134:137], v[174:177], v[38:41]
	v_mfma_f32_16x16x32_bf16 v[30:33], v[150:153], v[174:177], v[30:33]
	s_waitcnt lgkmcnt(1)
	v_mfma_f32_16x16x32_bf16 v[22:25], v[134:137], v[182:185], v[22:25]
	v_mfma_f32_16x16x32_bf16 v[14:17], v[150:153], v[182:185], v[14:17]
	v_mfma_f32_16x16x32_bf16 v[62:65], v[146:149], v[162:165], v[62:65]
	v_mfma_f32_16x16x32_bf16 v[58:61], v[154:157], v[162:165], v[58:61]
	v_mfma_f32_16x16x32_bf16 v[54:57], v[146:149], v[170:173], v[54:57]
	v_mfma_f32_16x16x32_bf16 v[46:49], v[154:157], v[170:173], v[46:49]
	v_mfma_f32_16x16x32_bf16 v[38:41], v[146:149], v[178:181], v[38:41]
	v_mfma_f32_16x16x32_bf16 v[30:33], v[154:157], v[178:181], v[30:33]
	s_waitcnt lgkmcnt(0)
	v_mfma_f32_16x16x32_bf16 v[22:25], v[146:149], v[186:189], v[22:25]
	v_mfma_f32_16x16x32_bf16 v[14:17], v[154:157], v[186:189], v[14:17]
	s_setprio 0
	s_barrier
	s_mov_b32 m0, s27
	s_add_i32 s33, s49, 0x40080
	buffer_load_dwordx4 v138, s[8:11], s33 offen lds
	s_add_i32 s49, s49, 0x60080
	s_mov_b32 m0, s28
	s_nop 0
	buffer_load_dwordx4 v138, s[8:11], s49 offen lds
	s_waitcnt vmcnt(6)
	s_barrier
	s_setprio 1
	v_mfma_f32_16x16x32_bf16 v[50:53], v[190:193], v[158:161], v[50:53]
	v_mfma_f32_16x16x32_bf16 v[42:45], v[198:201], v[158:161], v[42:45]
	v_mfma_f32_16x16x32_bf16 v[34:37], v[190:193], v[166:169], v[34:37]
	v_mfma_f32_16x16x32_bf16 v[26:29], v[198:201], v[166:169], v[26:29]
	v_mfma_f32_16x16x32_bf16 v[18:21], v[190:193], v[174:177], v[18:21]
	v_mfma_f32_16x16x32_bf16 v[10:13], v[198:201], v[174:177], v[10:13]
	v_mfma_f32_16x16x32_bf16 v[6:9], v[190:193], v[182:185], v[6:9]
	v_mfma_f32_16x16x32_bf16 v[2:5], v[198:201], v[182:185], v[2:5]
	v_mfma_f32_16x16x32_bf16 v[50:53], v[194:197], v[162:165], v[50:53]
	v_mfma_f32_16x16x32_bf16 v[42:45], v[202:205], v[162:165], v[42:45]
	v_mfma_f32_16x16x32_bf16 v[34:37], v[194:197], v[170:173], v[34:37]
	v_mfma_f32_16x16x32_bf16 v[26:29], v[202:205], v[170:173], v[26:29]
	v_mfma_f32_16x16x32_bf16 v[18:21], v[194:197], v[178:181], v[18:21]
	v_mfma_f32_16x16x32_bf16 v[10:13], v[202:205], v[178:181], v[10:13]
	v_mfma_f32_16x16x32_bf16 v[6:9], v[194:197], v[186:189], v[6:9]
	v_mfma_f32_16x16x32_bf16 v[2:5], v[202:205], v[186:189], v[2:5]
	s_setprio 0
	s_add_i32 s47, s47, 2
	s_addk_i32 s7, 0x100
	s_addk_i32 s46, 0x100
	s_cmp_gt_u32 s47, 13
	s_barrier

.LBB0_1333:
	s_lshl_b32 s59, s57, 19
	s_and_b64 s[6:7], s[6:7], exec
	v_mov_b32_e32 v2, 0
	s_cselect_b32 s6, s59, s13
	s_add_i32 s7, s13, 0x60080
	s_addk_i32 s12, 0x100
	s_mov_b32 s13, -2
	ds_read_b128 v[130:133], v195
	ds_read_b128 v[134:137], v195 offset:1024
	ds_read_b128 v[138:141], v195 offset:2048
	ds_read_b128 v[142:145], v195 offset:3072
	s_add_i32 s10, s7, 0xfffa0080
	s_cmp_eq_u32 s13, 12
	s_cselect_b32 s79, s6, s10
	s_cselect_b32 s78, s58, s12
	s_or_b32 s84, s79, 0x80
	s_add_i32 s10, s7, 0xfffe0000
	s_mov_b32 m0, s39
	ds_read_b128 v[146:149], v196
	ds_read_b128 v[150:153], v196 offset:1024
	ds_read_b128 v[154:157], v196 offset:2048
	ds_read_b128 v[158:161], v196 offset:3072
	ds_read_b128 v[162:165], v196 offset:4096
	ds_read_b128 v[166:169], v196 offset:5120
	ds_read_b128 v[170:173], v196 offset:6144
	ds_read_b128 v[174:177], v196 offset:7168
	buffer_load_dwordx4 v1, s[48:51], s10 offen lds
	s_mov_b32 m0, s41
	s_nop 0
	buffer_load_dwordx4 v1, s[48:51], s7 offen lds
	s_waitcnt lgkmcnt(8)
	s_barrier
	s_waitcnt lgkmcnt(0)
	s_setprio 1
	s_waitcnt lgkmcnt(7)
	v_mfma_f32_16x16x32_bf16 v[126:129], v[130:133], v[146:149], 0
	v_mfma_f32_16x16x32_bf16 v[122:125], v[138:141], v[146:149], 0
	s_waitcnt lgkmcnt(5)
	v_mfma_f32_16x16x32_bf16 v[110:113], v[130:133], v[154:157], 0
	v_mfma_f32_16x16x32_bf16 v[106:109], v[138:141], v[154:157], 0
	s_waitcnt lgkmcnt(3)
	v_mfma_f32_16x16x32_bf16 v[94:97], v[130:133], v[162:165], 0
	v_mfma_f32_16x16x32_bf16 v[90:93], v[138:141], v[162:165], 0
	s_waitcnt lgkmcnt(1)
	v_mfma_f32_16x16x32_bf16 v[78:81], v[130:133], v[170:173], 0
	v_mfma_f32_16x16x32_bf16 v[74:77], v[138:141], v[170:173], 0
	v_mfma_f32_16x16x32_bf16 v[126:129], v[134:137], v[150:153], v[126:129]
	v_mfma_f32_16x16x32_bf16 v[122:125], v[142:145], v[150:153], v[122:125]
	v_mfma_f32_16x16x32_bf16 v[110:113], v[134:137], v[158:161], v[110:113]
	v_mfma_f32_16x16x32_bf16 v[106:109], v[142:145], v[158:161], v[106:109]
	v_mfma_f32_16x16x32_bf16 v[94:97], v[134:137], v[166:169], v[94:97]
	v_mfma_f32_16x16x32_bf16 v[90:93], v[142:145], v[166:169], v[90:93]
	s_waitcnt lgkmcnt(0)
	v_mfma_f32_16x16x32_bf16 v[78:81], v[134:137], v[174:177], v[78:81]
	v_mfma_f32_16x16x32_bf16 v[74:77], v[142:145], v[174:177], v[74:77]
	s_setprio 0
	s_barrier
	s_mov_b32 m0, s17
	s_mov_b32 s10, s50
	s_mov_b32 s11, s51
	ds_read_b128 v[178:181], v197
	ds_read_b128 v[182:185], v197 offset:1024
	ds_read_b128 v[200:203], v197 offset:2048
	ds_read_b128 v[204:207], v197 offset:3072
	buffer_load_dwordx4 v192, s[8:11], s78 offen lds
	s_add_i32 s33, s78, 0x20000
	s_mov_b32 m0, s18
	s_nop 0
	buffer_load_dwordx4 v192, s[8:11], s33 offen lds
	s_barrier
	s_waitcnt lgkmcnt(0)
	s_setprio 1
	s_waitcnt lgkmcnt(3)
	v_mfma_f32_16x16x32_bf16 v[118:121], v[178:181], v[146:149], 0
	s_waitcnt lgkmcnt(1)
	v_mfma_f32_16x16x32_bf16 v[114:117], v[200:203], v[146:149], 0
	v_mfma_f32_16x16x32_bf16 v[102:105], v[178:181], v[154:157], 0
	v_mfma_f32_16x16x32_bf16 v[98:101], v[200:203], v[154:157], 0
	v_mfma_f32_16x16x32_bf16 v[86:89], v[178:181], v[162:165], 0
	v_mfma_f32_16x16x32_bf16 v[82:85], v[200:203], v[162:165], 0
	v_mfma_f32_16x16x32_bf16 v[70:73], v[178:181], v[170:173], 0
	v_mfma_f32_16x16x32_bf16 v[66:69], v[200:203], v[170:173], 0
	v_mfma_f32_16x16x32_bf16 v[118:121], v[182:185], v[150:153], v[118:121]
	s_waitcnt lgkmcnt(0)
	v_mfma_f32_16x16x32_bf16 v[114:117], v[204:207], v[150:153], v[114:117]
	v_mfma_f32_16x16x32_bf16 v[102:105], v[182:185], v[158:161], v[102:105]
	v_mfma_f32_16x16x32_bf16 v[98:101], v[204:207], v[158:161], v[98:101]
	v_mfma_f32_16x16x32_bf16 v[86:89], v[182:185], v[166:169], v[86:89]
	v_mfma_f32_16x16x32_bf16 v[82:85], v[204:207], v[166:169], v[82:85]
	v_mfma_f32_16x16x32_bf16 v[70:73], v[182:185], v[174:177], v[70:73]
	v_mfma_f32_16x16x32_bf16 v[66:69], v[204:207], v[174:177], v[66:69]
	s_setprio 0
	s_mov_b32 m0, s16
	s_barrier
	ds_read_b128 v[146:149], v196 offset:16384
	ds_read_b128 v[150:153], v196 offset:17408
	ds_read_b128 v[154:157], v196 offset:18432
	ds_read_b128 v[158:161], v196 offset:19456
	ds_read_b128 v[162:165], v196 offset:20480
	ds_read_b128 v[166:169], v196 offset:21504
	ds_read_b128 v[170:173], v196 offset:22528
	ds_read_b128 v[174:177], v196 offset:23552
	buffer_load_dwordx4 v1, s[48:51], s79 offen lds
	s_add_i32 s33, s79, 0x20000
	s_mov_b32 m0, s19
	s_nop 0
	buffer_load_dwordx4 v1, s[48:51], s33 offen lds
	s_barrier
	s_waitcnt lgkmcnt(0)
	s_setprio 1
	s_waitcnt lgkmcnt(7)
	v_mfma_f32_16x16x32_bf16 v[62:65], v[130:133], v[146:149], 0
	v_mfma_f32_16x16x32_bf16 v[58:61], v[138:141], v[146:149], 0
	s_waitcnt lgkmcnt(5)
	v_mfma_f32_16x16x32_bf16 v[46:49], v[130:133], v[154:157], 0
	v_mfma_f32_16x16x32_bf16 v[42:45], v[138:141], v[154:157], 0
	s_waitcnt lgkmcnt(3)
	v_mfma_f32_16x16x32_bf16 v[30:33], v[130:133], v[162:165], 0
	v_mfma_f32_16x16x32_bf16 v[26:29], v[138:141], v[162:165], 0
	s_waitcnt lgkmcnt(1)
	v_mfma_f32_16x16x32_bf16 v[14:17], v[130:133], v[170:173], 0
	v_mfma_f32_16x16x32_bf16 v[10:13], v[138:141], v[170:173], 0
	v_mfma_f32_16x16x32_bf16 v[62:65], v[134:137], v[150:153], v[62:65]
	v_mfma_f32_16x16x32_bf16 v[58:61], v[142:145], v[150:153], v[58:61]
	v_mfma_f32_16x16x32_bf16 v[46:49], v[134:137], v[158:161], v[46:49]
	v_mfma_f32_16x16x32_bf16 v[42:45], v[142:145], v[158:161], v[42:45]
	v_mfma_f32_16x16x32_bf16 v[30:33], v[134:137], v[166:169], v[30:33]
	v_mfma_f32_16x16x32_bf16 v[26:29], v[142:145], v[166:169], v[26:29]
	s_waitcnt lgkmcnt(0)
	v_mfma_f32_16x16x32_bf16 v[14:17], v[134:137], v[174:177], v[14:17]
	v_mfma_f32_16x16x32_bf16 v[10:13], v[142:145], v[174:177], v[10:13]
	s_setprio 0
	s_barrier
	s_mov_b32 m0, s20
	s_add_i32 s33, s78, 0x40000
	buffer_load_dwordx4 v192, s[8:11], s33 offen lds
	s_add_i32 s33, s78, 0x60000
	s_mov_b32 m0, s21
	s_nop 0
	buffer_load_dwordx4 v192, s[8:11], s33 offen lds
	s_cmp_eq_u32 s100, 0
	s_cbranch_scc1 .Lfw_6_a_p
	s_waitcnt vmcnt(16)
	s_mov_b32 s100, 0
	s_branch .Lfw_6_b_p

.Lfw_6_b_p:
	s_barrier
	s_setprio 1
	v_mfma_f32_16x16x32_bf16 v[54:57], v[178:181], v[146:149], 0
	v_mfma_f32_16x16x32_bf16 v[50:53], v[200:203], v[146:149], 0
	v_mfma_f32_16x16x32_bf16 v[38:41], v[178:181], v[154:157], 0
	v_mfma_f32_16x16x32_bf16 v[34:37], v[200:203], v[154:157], 0
	v_mfma_f32_16x16x32_bf16 v[22:25], v[178:181], v[162:165], 0
	v_mfma_f32_16x16x32_bf16 v[18:21], v[200:203], v[162:165], 0
	v_mfma_f32_16x16x32_bf16 v[6:9], v[178:181], v[170:173], 0
	v_mfma_f32_16x16x32_bf16 v[2:5], v[200:203], v[170:173], 0
	v_mfma_f32_16x16x32_bf16 v[54:57], v[182:185], v[150:153], v[54:57]
	v_mfma_f32_16x16x32_bf16 v[50:53], v[204:207], v[150:153], v[50:53]
	v_mfma_f32_16x16x32_bf16 v[38:41], v[182:185], v[158:161], v[38:41]
	v_mfma_f32_16x16x32_bf16 v[34:37], v[204:207], v[158:161], v[34:37]
	v_mfma_f32_16x16x32_bf16 v[22:25], v[182:185], v[166:169], v[22:25]
	v_mfma_f32_16x16x32_bf16 v[18:21], v[204:207], v[166:169], v[18:21]
	v_mfma_f32_16x16x32_bf16 v[6:9], v[182:185], v[174:177], v[6:9]
	v_mfma_f32_16x16x32_bf16 v[2:5], v[204:207], v[174:177], v[2:5]
	s_setprio 0
	s_barrier
	ds_read_b128 v[130:133], v198
	ds_read_b128 v[134:137], v198 offset:1024
	ds_read_b128 v[138:141], v198 offset:2048
	ds_read_b128 v[142:145], v198 offset:3072
	s_mov_b32 m0, s22
	s_add_i32 s33, s79, 0x40000
	ds_read_b128 v[146:149], v196 offset:32768
	ds_read_b128 v[150:153], v196 offset:33792
	ds_read_b128 v[154:157], v196 offset:34816
	ds_read_b128 v[158:161], v196 offset:35840
	ds_read_b128 v[162:165], v196 offset:36864
	ds_read_b128 v[166:169], v196 offset:37888
	ds_read_b128 v[170:173], v196 offset:38912
	ds_read_b128 v[174:177], v196 offset:39936
	buffer_load_dwordx4 v1, s[48:51], s33 offen lds
	s_add_i32 s33, s79, 0x60000
	s_mov_b32 m0, s23
	s_nop 0
	buffer_load_dwordx4 v1, s[48:51], s33 offen lds
	s_waitcnt lgkmcnt(8)
	s_barrier
	s_waitcnt lgkmcnt(0)
	s_setprio 1
	s_waitcnt lgkmcnt(7)
	v_mfma_f32_16x16x32_bf16 v[126:129], v[130:133], v[146:149], v[126:129]
	v_mfma_f32_16x16x32_bf16 v[122:125], v[138:141], v[146:149], v[122:125]
	s_waitcnt lgkmcnt(5)
	v_mfma_f32_16x16x32_bf16 v[110:113], v[130:133], v[154:157], v[110:113]
	v_mfma_f32_16x16x32_bf16 v[106:109], v[138:141], v[154:157], v[106:109]
	s_waitcnt lgkmcnt(3)
	v_mfma_f32_16x16x32_bf16 v[94:97], v[130:133], v[162:165], v[94:97]
	v_mfma_f32_16x16x32_bf16 v[90:93], v[138:141], v[162:165], v[90:93]
	s_waitcnt lgkmcnt(1)
	v_mfma_f32_16x16x32_bf16 v[78:81], v[130:133], v[170:173], v[78:81]
	v_mfma_f32_16x16x32_bf16 v[74:77], v[138:141], v[170:173], v[74:77]
	v_mfma_f32_16x16x32_bf16 v[126:129], v[134:137], v[150:153], v[126:129]
	v_mfma_f32_16x16x32_bf16 v[122:125], v[142:145], v[150:153], v[122:125]
	v_mfma_f32_16x16x32_bf16 v[110:113], v[134:137], v[158:161], v[110:113]
	v_mfma_f32_16x16x32_bf16 v[106:109], v[142:145], v[158:161], v[106:109]
	v_mfma_f32_16x16x32_bf16 v[94:97], v[134:137], v[166:169], v[94:97]
	v_mfma_f32_16x16x32_bf16 v[90:93], v[142:145], v[166:169], v[90:93]
	s_waitcnt lgkmcnt(0)
	v_mfma_f32_16x16x32_bf16 v[78:81], v[134:137], v[174:177], v[78:81]
	v_mfma_f32_16x16x32_bf16 v[74:77], v[142:145], v[174:177], v[74:77]
	s_setprio 0
	s_barrier
	s_mov_b32 m0, s29
	s_add_i32 s33, s78, 0x80
	ds_read_b128 v[178:181], v199
	ds_read_b128 v[182:185], v199 offset:1024
	ds_read_b128 v[200:203], v199 offset:2048
	ds_read_b128 v[204:207], v199 offset:3072
	buffer_load_dwordx4 v192, s[8:11], s33 offen lds
	s_add_i32 s33, s78, 0x20080
	s_mov_b32 m0, s30
	s_nop 0
	buffer_load_dwordx4 v192, s[8:11], s33 offen lds
	s_waitcnt vmcnt(10)
	s_barrier
	s_waitcnt lgkmcnt(0)
	s_setprio 1
	s_waitcnt lgkmcnt(3)
	v_mfma_f32_16x16x32_bf16 v[118:121], v[178:181], v[146:149], v[118:121]
	s_waitcnt lgkmcnt(1)
	v_mfma_f32_16x16x32_bf16 v[114:117], v[200:203], v[146:149], v[114:117]
	v_mfma_f32_16x16x32_bf16 v[102:105], v[178:181], v[154:157], v[102:105]
	v_mfma_f32_16x16x32_bf16 v[98:101], v[200:203], v[154:157], v[98:101]
	v_mfma_f32_16x16x32_bf16 v[86:89], v[178:181], v[162:165], v[86:89]
	v_mfma_f32_16x16x32_bf16 v[82:85], v[200:203], v[162:165], v[82:85]
	v_mfma_f32_16x16x32_bf16 v[70:73], v[178:181], v[170:173], v[70:73]
	v_mfma_f32_16x16x32_bf16 v[66:69], v[200:203], v[170:173], v[66:69]
	v_mfma_f32_16x16x32_bf16 v[118:121], v[182:185], v[150:153], v[118:121]
	s_waitcnt lgkmcnt(0)
	v_mfma_f32_16x16x32_bf16 v[114:117], v[204:207], v[150:153], v[114:117]
	v_mfma_f32_16x16x32_bf16 v[102:105], v[182:185], v[158:161], v[102:105]
	v_mfma_f32_16x16x32_bf16 v[98:101], v[204:207], v[158:161], v[98:101]
	v_mfma_f32_16x16x32_bf16 v[86:89], v[182:185], v[166:169], v[86:89]
	v_mfma_f32_16x16x32_bf16 v[82:85], v[204:207], v[166:169], v[82:85]
	v_mfma_f32_16x16x32_bf16 v[70:73], v[182:185], v[174:177], v[70:73]
	v_mfma_f32_16x16x32_bf16 v[66:69], v[204:207], v[174:177], v[66:69]
	s_setprio 0
	s_mov_b32 m0, s31
	s_barrier
	ds_read_b128 v[146:149], v196 offset:49152
	ds_read_b128 v[150:153], v196 offset:50176
	ds_read_b128 v[154:157], v196 offset:51200
	ds_read_b128 v[158:161], v196 offset:52224
	ds_read_b128 v[162:165], v196 offset:53248
	ds_read_b128 v[166:169], v196 offset:54272
	ds_read_b128 v[170:173], v196 offset:55296
	ds_read_b128 v[174:177], v196 offset:56320
	buffer_load_dwordx4 v1, s[48:51], s84 offen lds
	s_add_i32 s79, s79, 0x20080
	s_mov_b32 m0, s34
	s_nop 0
	buffer_load_dwordx4 v1, s[48:51], s79 offen lds
	s_barrier
	s_waitcnt lgkmcnt(0)
	s_setprio 1
	s_waitcnt lgkmcnt(7)
	v_mfma_f32_16x16x32_bf16 v[62:65], v[130:133], v[146:149], v[62:65]
	v_mfma_f32_16x16x32_bf16 v[58:61], v[138:141], v[146:149], v[58:61]
	s_waitcnt lgkmcnt(5)
	v_mfma_f32_16x16x32_bf16 v[46:49], v[130:133], v[154:157], v[46:49]
	v_mfma_f32_16x16x32_bf16 v[42:45], v[138:141], v[154:157], v[42:45]
	s_waitcnt lgkmcnt(3)
	v_mfma_f32_16x16x32_bf16 v[30:33], v[130:133], v[162:165], v[30:33]
	v_mfma_f32_16x16x32_bf16 v[26:29], v[138:141], v[162:165], v[26:29]
	s_waitcnt lgkmcnt(1)
	v_mfma_f32_16x16x32_bf16 v[14:17], v[130:133], v[170:173], v[14:17]
	v_mfma_f32_16x16x32_bf16 v[10:13], v[138:141], v[170:173], v[10:13]
	v_mfma_f32_16x16x32_bf16 v[62:65], v[134:137], v[150:153], v[62:65]
	v_mfma_f32_16x16x32_bf16 v[58:61], v[142:145], v[150:153], v[58:61]
	v_mfma_f32_16x16x32_bf16 v[46:49], v[134:137], v[158:161], v[46:49]
	v_mfma_f32_16x16x32_bf16 v[42:45], v[142:145], v[158:161], v[42:45]
	v_mfma_f32_16x16x32_bf16 v[30:33], v[134:137], v[166:169], v[30:33]
	v_mfma_f32_16x16x32_bf16 v[26:29], v[142:145], v[166:169], v[26:29]
	s_waitcnt lgkmcnt(0)
	v_mfma_f32_16x16x32_bf16 v[14:17], v[134:137], v[174:177], v[14:17]
	v_mfma_f32_16x16x32_bf16 v[10:13], v[142:145], v[174:177], v[10:13]
	s_setprio 0
	s_barrier
	s_mov_b32 m0, s35
	s_add_i32 s33, s78, 0x40080
	buffer_load_dwordx4 v192, s[8:11], s33 offen lds
	s_add_i32 s78, s78, 0x60080
	s_mov_b32 m0, s36
	s_nop 0
	buffer_load_dwordx4 v192, s[8:11], s78 offen lds
	s_waitcnt vmcnt(6)
	s_barrier
	s_setprio 1
	v_mfma_f32_16x16x32_bf16 v[54:57], v[178:181], v[146:149], v[54:57]
	v_mfma_f32_16x16x32_bf16 v[50:53], v[200:203], v[146:149], v[50:53]
	v_mfma_f32_16x16x32_bf16 v[38:41], v[178:181], v[154:157], v[38:41]
	v_mfma_f32_16x16x32_bf16 v[34:37], v[200:203], v[154:157], v[34:37]
	v_mfma_f32_16x16x32_bf16 v[22:25], v[178:181], v[162:165], v[22:25]
	v_mfma_f32_16x16x32_bf16 v[18:21], v[200:203], v[162:165], v[18:21]
	v_mfma_f32_16x16x32_bf16 v[6:9], v[178:181], v[170:173], v[6:9]
	v_mfma_f32_16x16x32_bf16 v[2:5], v[200:203], v[170:173], v[2:5]
	v_mfma_f32_16x16x32_bf16 v[54:57], v[182:185], v[150:153], v[54:57]
	v_mfma_f32_16x16x32_bf16 v[50:53], v[204:207], v[150:153], v[50:53]
	v_mfma_f32_16x16x32_bf16 v[38:41], v[182:185], v[158:161], v[38:41]
	v_mfma_f32_16x16x32_bf16 v[34:37], v[204:207], v[158:161], v[34:37]
	v_mfma_f32_16x16x32_bf16 v[22:25], v[182:185], v[166:169], v[22:25]
	v_mfma_f32_16x16x32_bf16 v[18:21], v[204:207], v[166:169], v[18:21]
	v_mfma_f32_16x16x32_bf16 v[6:9], v[182:185], v[174:177], v[6:9]
	v_mfma_f32_16x16x32_bf16 v[2:5], v[204:207], v[174:177], v[2:5]
	s_setprio 0
	s_add_i32 s13, s13, 2
	s_addk_i32 s7, 0x100
	s_addk_i32 s12, 0x100
	s_cmp_gt_u32 s13, 13
	s_barrier

.LBB0_1723:
	s_lshl_b32 s73, s59, 18
	s_and_b64 s[6:7], s[6:7], exec
	v_mov_b32_e32 v2, 0
	s_cselect_b32 s6, s73, s85
	s_add_i32 s7, s85, 0x30080
	s_addk_i32 s84, 0x100
	s_mov_b32 s85, -2
	ds_read_b128 v[142:145], v137
	ds_read_b128 v[146:149], v137 offset:1024
	ds_read_b128 v[150:153], v137 offset:2048
	ds_read_b128 v[154:157], v137 offset:3072
	s_add_i32 s10, s7, 0xfffd0080
	s_cmp_eq_u32 s85, 4
	s_cselect_b32 s87, s6, s10
	s_cselect_b32 s86, s72, s84
	s_or_b32 s88, s87, 0x80
	s_add_i32 s10, s7, 0xffff0000
	s_mov_b32 m0, s39
	ds_read_b128 v[158:161], v138
	ds_read_b128 v[162:165], v138 offset:1024
	ds_read_b128 v[166:169], v138 offset:2048
	ds_read_b128 v[170:173], v138 offset:3072
	ds_read_b128 v[174:177], v138 offset:4096
	ds_read_b128 v[178:181], v138 offset:5120
	ds_read_b128 v[182:185], v138 offset:6144
	ds_read_b128 v[186:189], v138 offset:7168
	buffer_load_dwordx4 v1, s[44:47], s10 offen lds
	s_mov_b32 m0, s41
	s_nop 0
	buffer_load_dwordx4 v1, s[44:47], s7 offen lds
	s_waitcnt lgkmcnt(8)
	s_barrier
	s_waitcnt lgkmcnt(0)
	s_setprio 1
	s_waitcnt lgkmcnt(4)
	v_mfma_f32_16x16x128_f8f6f4 v[114:117], v[142:149], v[166:173], 0
	v_mfma_f32_16x16x128_f8f6f4 v[106:109], v[150:157], v[166:173], 0
	s_waitcnt lgkmcnt(2)
	v_mfma_f32_16x16x128_f8f6f4 v[98:101], v[142:149], v[174:181], 0
	v_mfma_f32_16x16x128_f8f6f4 v[198:201], v[142:149], v[158:165], 0
	v_mfma_f32_16x16x128_f8f6f4 v[202:205], v[150:157], v[158:165], 0
	v_mfma_f32_16x16x128_f8f6f4 v[206:209], v[150:157], v[174:181], 0
	s_waitcnt lgkmcnt(0)
	v_mfma_f32_16x16x128_f8f6f4 v[210:213], v[142:149], v[182:189], 0
	v_mfma_f32_16x16x128_f8f6f4 v[214:217], v[150:157], v[182:189], 0
	s_setprio 0
	s_barrier
	s_mov_b32 m0, s23
	s_mov_b32 s10, s46
	s_mov_b32 s11, s47
	ds_read_b128 v[122:125], v139
	ds_read_b128 v[126:129], v139 offset:1024
	ds_read_b128 v[190:193], v139 offset:2048
	ds_read_b128 v[194:197], v139 offset:3072
	buffer_load_dwordx4 v134, s[8:11], s86 offen lds
	s_add_i32 s33, s86, 0x10000
	s_mov_b32 m0, s24
	s_nop 0
	buffer_load_dwordx4 v134, s[8:11], s33 offen lds
	s_barrier
	s_waitcnt lgkmcnt(0)
	s_setprio 1
	s_waitcnt lgkmcnt(2)
	v_mfma_f32_16x16x128_f8f6f4 v[118:121], v[122:129], v[158:165], 0
	s_waitcnt lgkmcnt(0)
	v_mfma_f32_16x16x128_f8f6f4 v[110:113], v[190:197], v[158:165], 0
	v_mfma_f32_16x16x128_f8f6f4 v[102:105], v[122:129], v[166:173], 0
	v_mfma_f32_16x16x128_f8f6f4 v[158:161], v[190:197], v[166:173], 0
	v_mfma_f32_16x16x128_f8f6f4 v[162:165], v[122:129], v[174:181], 0
	v_mfma_f32_16x16x128_f8f6f4 v[166:169], v[190:197], v[174:181], 0
	v_mfma_f32_16x16x128_f8f6f4 v[170:173], v[122:129], v[182:189], 0
	v_mfma_f32_16x16x128_f8f6f4 v[174:177], v[190:197], v[182:189], 0
	s_setprio 0
	s_mov_b32 m0, s22
	s_barrier
	ds_read_b128 v[66:69], v138 offset:16384
	s_nop 1
	ds_read_b128 v[70:73], v138 offset:17408
	ds_read_b128 v[74:77], v138 offset:18432
	ds_read_b128 v[78:81], v138 offset:19456
	ds_read_b128 v[82:85], v138 offset:20480
	ds_read_b128 v[86:89], v138 offset:21504
	ds_read_b128 v[90:93], v138 offset:22528
	ds_read_b128 v[94:97], v138 offset:23552
	buffer_load_dwordx4 v1, s[44:47], s87 offen lds
	s_add_i32 s33, s87, 0x10000
	s_mov_b32 m0, s25
	s_nop 0
	buffer_load_dwordx4 v1, s[44:47], s33 offen lds
	s_barrier
	s_waitcnt lgkmcnt(0)
	s_setprio 1
	s_waitcnt lgkmcnt(6)
	v_mfma_f32_16x16x128_f8f6f4 v[62:65], v[142:149], v[66:73], 0
	v_mfma_f32_16x16x128_f8f6f4 v[58:61], v[150:157], v[66:73], 0
	s_waitcnt lgkmcnt(4)
	v_mfma_f32_16x16x128_f8f6f4 v[50:53], v[142:149], v[74:81], 0
	s_waitcnt lgkmcnt(0)
	v_mfma_f32_16x16x128_f8f6f4 v[230:233], v[142:149], v[90:97], 0
	v_mfma_f32_16x16x128_f8f6f4 v[218:221], v[150:157], v[74:81], 0
	v_mfma_f32_16x16x128_f8f6f4 v[222:225], v[142:149], v[82:89], 0
	v_mfma_f32_16x16x128_f8f6f4 v[226:229], v[150:157], v[82:89], 0
	v_mfma_f32_16x16x128_f8f6f4 v[234:237], v[150:157], v[90:97], 0
	s_setprio 0
	s_barrier
	s_mov_b32 m0, s26
	s_add_i32 s33, s86, 0x20000
	buffer_load_dwordx4 v134, s[8:11], s33 offen lds
	s_add_i32 s33, s86, 0x30000
	s_mov_b32 m0, s27
	s_nop 0
	buffer_load_dwordx4 v134, s[8:11], s33 offen lds
	s_cmp_eq_u32 s100, 0
	s_cbranch_scc1 .Lfw_8_a_p
	s_waitcnt vmcnt(16)
	s_mov_b32 s100, 0
	s_branch .Lfw_8_b_p

.Lfw_8_b_p:
	s_barrier
	s_setprio 1
	v_mfma_f32_16x16x128_f8f6f4 v[54:57], v[122:129], v[66:73], 0
	v_mfma_f32_16x16x128_f8f6f4 v[238:241], v[190:197], v[66:73], 0
	v_mfma_f32_16x16x128_f8f6f4 v[242:245], v[122:129], v[74:81], 0
	v_mfma_f32_16x16x128_f8f6f4 v[246:249], v[190:197], v[74:81], 0
	v_mfma_f32_16x16x128_f8f6f4 v[250:253], v[122:129], v[82:89], 0
	v_mfma_f32_16x16x128_f8f6f4 v[130:133], v[190:197], v[82:89], 0
	v_mfma_f32_16x16x128_f8f6f4 v[66:69], v[122:129], v[90:97], 0
	v_mfma_f32_16x16x128_f8f6f4 v[190:193], v[190:197], v[90:97], 0
	s_setprio 0
	s_barrier
	s_nop 4
	ds_read_b128 v[2:5], v140
	ds_read_b128 v[6:9], v140 offset:1024
	ds_read_b128 v[10:13], v140 offset:2048
	ds_read_b128 v[14:17], v140 offset:3072
	s_mov_b32 m0, s28
	s_add_i32 s33, s87, 0x20000
	ds_read_b128 v[18:21], v138 offset:32768
	ds_read_b128 v[22:25], v138 offset:33792
	ds_read_b128 v[26:29], v138 offset:34816
	ds_read_b128 v[30:33], v138 offset:35840
	ds_read_b128 v[34:37], v138 offset:36864
	ds_read_b128 v[38:41], v138 offset:37888
	ds_read_b128 v[42:45], v138 offset:38912
	ds_read_b128 v[46:49], v138 offset:39936
	buffer_load_dwordx4 v1, s[44:47], s33 offen lds
	s_add_i32 s33, s87, 0x30000
	s_mov_b32 m0, s29
	s_nop 0
	buffer_load_dwordx4 v1, s[44:47], s33 offen lds
	s_waitcnt lgkmcnt(8)
	s_barrier
	s_waitcnt lgkmcnt(0)
	s_setprio 1
	s_waitcnt lgkmcnt(6)
	v_mfma_f32_16x16x128_f8f6f4 v[126:129], v[2:9], v[18:25], v[198:201]
	v_mfma_f32_16x16x128_f8f6f4 v[122:125], v[10:17], v[18:25], v[202:205]
	s_waitcnt lgkmcnt(4)
	v_mfma_f32_16x16x128_f8f6f4 v[114:117], v[2:9], v[26:33], v[114:117]
	v_mfma_f32_16x16x128_f8f6f4 v[106:109], v[10:17], v[26:33], v[106:109]
	s_waitcnt lgkmcnt(2)
	v_mfma_f32_16x16x128_f8f6f4 v[98:101], v[2:9], v[34:41], v[98:101]
	v_mfma_f32_16x16x128_f8f6f4 v[90:93], v[10:17], v[34:41], v[206:209]
	s_waitcnt lgkmcnt(0)
	v_mfma_f32_16x16x128_f8f6f4 v[82:85], v[2:9], v[42:49], v[210:213]
	v_mfma_f32_16x16x128_f8f6f4 v[74:77], v[10:17], v[42:49], v[214:217]
	s_setprio 0
	s_barrier
	s_mov_b32 m0, s31
	s_add_i32 s33, s86, 0x80
	ds_read_b128 v[142:145], v141
	ds_read_b128 v[146:149], v141 offset:1024
	ds_read_b128 v[150:153], v141 offset:2048
	ds_read_b128 v[154:157], v141 offset:3072
	buffer_load_dwordx4 v134, s[8:11], s33 offen lds
	s_add_i32 s33, s86, 0x10080
	s_mov_b32 m0, s34
	s_nop 0
	buffer_load_dwordx4 v134, s[8:11], s33 offen lds
	s_waitcnt vmcnt(10)
	s_barrier
	s_waitcnt lgkmcnt(0)
	s_setprio 1
	s_waitcnt lgkmcnt(2)
	v_mfma_f32_16x16x128_f8f6f4 v[118:121], v[142:149], v[18:25], v[118:121]
	s_waitcnt lgkmcnt(0)
	v_mfma_f32_16x16x128_f8f6f4 v[110:113], v[150:157], v[18:25], v[110:113]
	v_mfma_f32_16x16x128_f8f6f4 v[102:105], v[142:149], v[26:33], v[102:105]
	v_mfma_f32_16x16x128_f8f6f4 v[94:97], v[150:157], v[26:33], v[158:161]
	v_mfma_f32_16x16x128_f8f6f4 v[86:89], v[142:149], v[34:41], v[162:165]
	v_mfma_f32_16x16x128_f8f6f4 v[78:81], v[150:157], v[34:41], v[166:169]
	v_mfma_f32_16x16x128_f8f6f4 v[70:73], v[142:149], v[42:49], v[170:173]
	v_mfma_f32_16x16x128_f8f6f4 v[18:21], v[150:157], v[42:49], v[174:177]
	s_setprio 0
	s_mov_b32 m0, s35
	s_barrier
	ds_read_b128 v[158:161], v138 offset:49152
	ds_read_b128 v[162:165], v138 offset:50176
	ds_read_b128 v[166:169], v138 offset:51200
	ds_read_b128 v[170:173], v138 offset:52224
	ds_read_b128 v[174:177], v138 offset:53248
	ds_read_b128 v[178:181], v138 offset:54272
	ds_read_b128 v[182:185], v138 offset:55296
	ds_read_b128 v[186:189], v138 offset:56320
	buffer_load_dwordx4 v1, s[44:47], s88 offen lds
	s_add_i32 s87, s87, 0x10080
	s_mov_b32 m0, s36
	s_nop 0
	buffer_load_dwordx4 v1, s[44:47], s87 offen lds
	s_barrier
	s_waitcnt lgkmcnt(0)
	s_setprio 1
	s_waitcnt lgkmcnt(6)
	v_mfma_f32_16x16x128_f8f6f4 v[62:65], v[2:9], v[158:165], v[62:65]
	v_mfma_f32_16x16x128_f8f6f4 v[58:61], v[10:17], v[158:165], v[58:61]
	s_waitcnt lgkmcnt(4)
	v_mfma_f32_16x16x128_f8f6f4 v[50:53], v[2:9], v[166:173], v[50:53]
	v_mfma_f32_16x16x128_f8f6f4 v[42:45], v[10:17], v[166:173], v[218:221]
	s_waitcnt lgkmcnt(2)
	v_mfma_f32_16x16x128_f8f6f4 v[34:37], v[2:9], v[174:181], v[222:225]
	v_mfma_f32_16x16x128_f8f6f4 v[26:29], v[10:17], v[174:181], v[226:229]
	s_waitcnt lgkmcnt(0)
	v_mfma_f32_16x16x128_f8f6f4 v[230:233], v[2:9], v[182:189], v[230:233]
	v_mfma_f32_16x16x128_f8f6f4 v[10:13], v[10:17], v[182:189], v[234:237]
	s_setprio 0
	s_barrier
	s_mov_b32 m0, s37
	s_add_i32 s33, s86, 0x20080
	buffer_load_dwordx4 v134, s[8:11], s33 offen lds
	s_add_i32 s86, s86, 0x30080
	s_mov_b32 m0, s38
	s_nop 0
	buffer_load_dwordx4 v134, s[8:11], s86 offen lds
	s_waitcnt vmcnt(6)
	s_barrier
	s_setprio 1
	v_mfma_f32_16x16x128_f8f6f4 v[54:57], v[142:149], v[158:165], v[54:57]
	v_mfma_f32_16x16x128_f8f6f4 v[46:49], v[150:157], v[158:165], v[238:241]
	v_mfma_f32_16x16x128_f8f6f4 v[38:41], v[142:149], v[166:173], v[242:245]
	v_mfma_f32_16x16x128_f8f6f4 v[30:33], v[150:157], v[166:173], v[246:249]
	v_mfma_f32_16x16x128_f8f6f4 v[22:25], v[142:149], v[174:181], v[250:253]
	v_mfma_f32_16x16x128_f8f6f4 v[14:17], v[150:157], v[174:181], v[130:133]
	v_mfma_f32_16x16x128_f8f6f4 v[6:9], v[142:149], v[182:189], v[66:69]
	v_mfma_f32_16x16x128_f8f6f4 v[2:5], v[150:157], v[182:189], v[190:193]
	s_setprio 0
	s_add_i32 s85, s85, 2
	s_addk_i32 s7, 0x100
	s_addk_i32 s84, 0x100
	s_cmp_gt_u32 s85, 5
	s_barrier

.LBB0_2150:
	s_lshl_b32 s58, s47, 19
	s_and_b64 s[6:7], s[6:7], exec
	v_mov_b32_e32 v2, 0
	s_cselect_b32 s6, s58, s13
	s_add_i32 s7, s13, 0x60080
	s_addk_i32 s12, 0x100
	s_mov_b32 s13, -2
	ds_read_b128 v[130:133], v195
	ds_read_b128 v[134:137], v195 offset:1024
	ds_read_b128 v[138:141], v195 offset:2048
	ds_read_b128 v[142:145], v195 offset:3072
	s_add_i32 s10, s7, 0xfffa0080
	s_cmp_eq_u32 s13, 12
	s_cselect_b32 s78, s6, s10
	s_cselect_b32 s73, s57, s12
	s_or_b32 s79, s78, 0x80
	s_add_i32 s10, s7, 0xfffe0000
	s_mov_b32 m0, s38
	ds_read_b128 v[146:149], v196
	ds_read_b128 v[150:153], v196 offset:1024
	ds_read_b128 v[154:157], v196 offset:2048
	ds_read_b128 v[158:161], v196 offset:3072
	ds_read_b128 v[162:165], v196 offset:4096
	ds_read_b128 v[166:169], v196 offset:5120
	ds_read_b128 v[170:173], v196 offset:6144
	ds_read_b128 v[174:177], v196 offset:7168
	buffer_load_dwordx4 v1, s[48:51], s10 offen lds
	s_mov_b32 m0, s39
	s_nop 0
	buffer_load_dwordx4 v1, s[48:51], s7 offen lds
	s_waitcnt lgkmcnt(8)
	s_barrier
	s_waitcnt lgkmcnt(0)
	s_setprio 1
	s_waitcnt lgkmcnt(7)
	v_mfma_f32_16x16x32_bf16 v[126:129], v[130:133], v[146:149], 0
	v_mfma_f32_16x16x32_bf16 v[122:125], v[138:141], v[146:149], 0
	s_waitcnt lgkmcnt(5)
	v_mfma_f32_16x16x32_bf16 v[110:113], v[130:133], v[154:157], 0
	v_mfma_f32_16x16x32_bf16 v[106:109], v[138:141], v[154:157], 0
	s_waitcnt lgkmcnt(3)
	v_mfma_f32_16x16x32_bf16 v[94:97], v[130:133], v[162:165], 0
	v_mfma_f32_16x16x32_bf16 v[90:93], v[138:141], v[162:165], 0
	s_waitcnt lgkmcnt(1)
	v_mfma_f32_16x16x32_bf16 v[78:81], v[130:133], v[170:173], 0
	v_mfma_f32_16x16x32_bf16 v[74:77], v[138:141], v[170:173], 0
	v_mfma_f32_16x16x32_bf16 v[126:129], v[134:137], v[150:153], v[126:129]
	v_mfma_f32_16x16x32_bf16 v[122:125], v[142:145], v[150:153], v[122:125]
	v_mfma_f32_16x16x32_bf16 v[110:113], v[134:137], v[158:161], v[110:113]
	v_mfma_f32_16x16x32_bf16 v[106:109], v[142:145], v[158:161], v[106:109]
	v_mfma_f32_16x16x32_bf16 v[94:97], v[134:137], v[166:169], v[94:97]
	v_mfma_f32_16x16x32_bf16 v[90:93], v[142:145], v[166:169], v[90:93]
	s_waitcnt lgkmcnt(0)
	v_mfma_f32_16x16x32_bf16 v[78:81], v[134:137], v[174:177], v[78:81]
	v_mfma_f32_16x16x32_bf16 v[74:77], v[142:145], v[174:177], v[74:77]
	s_setprio 0
	s_barrier
	s_mov_b32 m0, s16
	s_mov_b32 s10, s50
	s_mov_b32 s11, s51
	ds_read_b128 v[178:181], v197
	ds_read_b128 v[182:185], v197 offset:1024
	ds_read_b128 v[200:203], v197 offset:2048
	ds_read_b128 v[204:207], v197 offset:3072
	buffer_load_dwordx4 v192, s[8:11], s73 offen lds
	s_add_i32 s33, s73, 0x20000
	s_mov_b32 m0, s17
	s_nop 0
	buffer_load_dwordx4 v192, s[8:11], s33 offen lds
	s_barrier
	s_waitcnt lgkmcnt(0)
	s_setprio 1
	s_waitcnt lgkmcnt(3)
	v_mfma_f32_16x16x32_bf16 v[118:121], v[178:181], v[146:149], 0
	s_waitcnt lgkmcnt(1)
	v_mfma_f32_16x16x32_bf16 v[114:117], v[200:203], v[146:149], 0
	v_mfma_f32_16x16x32_bf16 v[102:105], v[178:181], v[154:157], 0
	v_mfma_f32_16x16x32_bf16 v[98:101], v[200:203], v[154:157], 0
	v_mfma_f32_16x16x32_bf16 v[86:89], v[178:181], v[162:165], 0
	v_mfma_f32_16x16x32_bf16 v[82:85], v[200:203], v[162:165], 0
	v_mfma_f32_16x16x32_bf16 v[70:73], v[178:181], v[170:173], 0
	v_mfma_f32_16x16x32_bf16 v[66:69], v[200:203], v[170:173], 0
	v_mfma_f32_16x16x32_bf16 v[118:121], v[182:185], v[150:153], v[118:121]
	s_waitcnt lgkmcnt(0)
	v_mfma_f32_16x16x32_bf16 v[114:117], v[204:207], v[150:153], v[114:117]
	v_mfma_f32_16x16x32_bf16 v[102:105], v[182:185], v[158:161], v[102:105]
	v_mfma_f32_16x16x32_bf16 v[98:101], v[204:207], v[158:161], v[98:101]
	v_mfma_f32_16x16x32_bf16 v[86:89], v[182:185], v[166:169], v[86:89]
	v_mfma_f32_16x16x32_bf16 v[82:85], v[204:207], v[166:169], v[82:85]
	v_mfma_f32_16x16x32_bf16 v[70:73], v[182:185], v[174:177], v[70:73]
	v_mfma_f32_16x16x32_bf16 v[66:69], v[204:207], v[174:177], v[66:69]
	s_setprio 0
	s_mov_b32 m0, s15
	s_barrier
	ds_read_b128 v[146:149], v196 offset:16384
	ds_read_b128 v[150:153], v196 offset:17408
	ds_read_b128 v[154:157], v196 offset:18432
	ds_read_b128 v[158:161], v196 offset:19456
	ds_read_b128 v[162:165], v196 offset:20480
	ds_read_b128 v[166:169], v196 offset:21504
	ds_read_b128 v[170:173], v196 offset:22528
	ds_read_b128 v[174:177], v196 offset:23552
	buffer_load_dwordx4 v1, s[48:51], s78 offen lds
	s_add_i32 s33, s78, 0x20000
	s_mov_b32 m0, s18
	s_nop 0
	buffer_load_dwordx4 v1, s[48:51], s33 offen lds
	s_barrier
	s_waitcnt lgkmcnt(0)
	s_setprio 1
	s_waitcnt lgkmcnt(7)
	v_mfma_f32_16x16x32_bf16 v[62:65], v[130:133], v[146:149], 0
	v_mfma_f32_16x16x32_bf16 v[58:61], v[138:141], v[146:149], 0
	s_waitcnt lgkmcnt(5)
	v_mfma_f32_16x16x32_bf16 v[46:49], v[130:133], v[154:157], 0
	v_mfma_f32_16x16x32_bf16 v[42:45], v[138:141], v[154:157], 0
	s_waitcnt lgkmcnt(3)
	v_mfma_f32_16x16x32_bf16 v[30:33], v[130:133], v[162:165], 0
	v_mfma_f32_16x16x32_bf16 v[26:29], v[138:141], v[162:165], 0
	s_waitcnt lgkmcnt(1)
	v_mfma_f32_16x16x32_bf16 v[14:17], v[130:133], v[170:173], 0
	v_mfma_f32_16x16x32_bf16 v[10:13], v[138:141], v[170:173], 0
	v_mfma_f32_16x16x32_bf16 v[62:65], v[134:137], v[150:153], v[62:65]
	v_mfma_f32_16x16x32_bf16 v[58:61], v[142:145], v[150:153], v[58:61]
	v_mfma_f32_16x16x32_bf16 v[46:49], v[134:137], v[158:161], v[46:49]
	v_mfma_f32_16x16x32_bf16 v[42:45], v[142:145], v[158:161], v[42:45]
	v_mfma_f32_16x16x32_bf16 v[30:33], v[134:137], v[166:169], v[30:33]
	v_mfma_f32_16x16x32_bf16 v[26:29], v[142:145], v[166:169], v[26:29]
	s_waitcnt lgkmcnt(0)
	v_mfma_f32_16x16x32_bf16 v[14:17], v[134:137], v[174:177], v[14:17]
	v_mfma_f32_16x16x32_bf16 v[10:13], v[142:145], v[174:177], v[10:13]
	s_setprio 0
	s_barrier
	s_mov_b32 m0, s19
	s_add_i32 s33, s73, 0x40000
	buffer_load_dwordx4 v192, s[8:11], s33 offen lds
	s_add_i32 s33, s73, 0x60000
	s_mov_b32 m0, s20
	s_nop 0
	buffer_load_dwordx4 v192, s[8:11], s33 offen lds
	s_cmp_eq_u32 s100, 0
	s_cbranch_scc1 .Lfw_10_a_p
	s_waitcnt vmcnt(16)
	s_mov_b32 s100, 0
	s_branch .Lfw_10_b_p

.Lfw_10_b_p:
	s_barrier
	s_setprio 1
	v_mfma_f32_16x16x32_bf16 v[54:57], v[178:181], v[146:149], 0
	v_mfma_f32_16x16x32_bf16 v[50:53], v[200:203], v[146:149], 0
	v_mfma_f32_16x16x32_bf16 v[38:41], v[178:181], v[154:157], 0
	v_mfma_f32_16x16x32_bf16 v[34:37], v[200:203], v[154:157], 0
	v_mfma_f32_16x16x32_bf16 v[22:25], v[178:181], v[162:165], 0
	v_mfma_f32_16x16x32_bf16 v[18:21], v[200:203], v[162:165], 0
	v_mfma_f32_16x16x32_bf16 v[6:9], v[178:181], v[170:173], 0
	v_mfma_f32_16x16x32_bf16 v[2:5], v[200:203], v[170:173], 0
	v_mfma_f32_16x16x32_bf16 v[54:57], v[182:185], v[150:153], v[54:57]
	v_mfma_f32_16x16x32_bf16 v[50:53], v[204:207], v[150:153], v[50:53]
	v_mfma_f32_16x16x32_bf16 v[38:41], v[182:185], v[158:161], v[38:41]
	v_mfma_f32_16x16x32_bf16 v[34:37], v[204:207], v[158:161], v[34:37]
	v_mfma_f32_16x16x32_bf16 v[22:25], v[182:185], v[166:169], v[22:25]
	v_mfma_f32_16x16x32_bf16 v[18:21], v[204:207], v[166:169], v[18:21]
	v_mfma_f32_16x16x32_bf16 v[6:9], v[182:185], v[174:177], v[6:9]
	v_mfma_f32_16x16x32_bf16 v[2:5], v[204:207], v[174:177], v[2:5]
	s_setprio 0
	s_barrier
	ds_read_b128 v[130:133], v198
	ds_read_b128 v[134:137], v198 offset:1024
	ds_read_b128 v[138:141], v198 offset:2048
	ds_read_b128 v[142:145], v198 offset:3072
	s_mov_b32 m0, s21
	s_add_i32 s33, s78, 0x40000
	ds_read_b128 v[146:149], v196 offset:32768
	ds_read_b128 v[150:153], v196 offset:33792
	ds_read_b128 v[154:157], v196 offset:34816
	ds_read_b128 v[158:161], v196 offset:35840
	ds_read_b128 v[162:165], v196 offset:36864
	ds_read_b128 v[166:169], v196 offset:37888
	ds_read_b128 v[170:173], v196 offset:38912
	ds_read_b128 v[174:177], v196 offset:39936
	buffer_load_dwordx4 v1, s[48:51], s33 offen lds
	s_add_i32 s33, s78, 0x60000
	s_mov_b32 m0, s22
	s_nop 0
	buffer_load_dwordx4 v1, s[48:51], s33 offen lds
	s_waitcnt lgkmcnt(8)
	s_barrier
	s_waitcnt lgkmcnt(0)
	s_setprio 1
	s_waitcnt lgkmcnt(7)
	v_mfma_f32_16x16x32_bf16 v[126:129], v[130:133], v[146:149], v[126:129]
	v_mfma_f32_16x16x32_bf16 v[122:125], v[138:141], v[146:149], v[122:125]
	s_waitcnt lgkmcnt(5)
	v_mfma_f32_16x16x32_bf16 v[110:113], v[130:133], v[154:157], v[110:113]
	v_mfma_f32_16x16x32_bf16 v[106:109], v[138:141], v[154:157], v[106:109]
	s_waitcnt lgkmcnt(3)
	v_mfma_f32_16x16x32_bf16 v[94:97], v[130:133], v[162:165], v[94:97]
	v_mfma_f32_16x16x32_bf16 v[90:93], v[138:141], v[162:165], v[90:93]
	s_waitcnt lgkmcnt(1)
	v_mfma_f32_16x16x32_bf16 v[78:81], v[130:133], v[170:173], v[78:81]
	v_mfma_f32_16x16x32_bf16 v[74:77], v[138:141], v[170:173], v[74:77]
	v_mfma_f32_16x16x32_bf16 v[126:129], v[134:137], v[150:153], v[126:129]
	v_mfma_f32_16x16x32_bf16 v[122:125], v[142:145], v[150:153], v[122:125]
	v_mfma_f32_16x16x32_bf16 v[110:113], v[134:137], v[158:161], v[110:113]
	v_mfma_f32_16x16x32_bf16 v[106:109], v[142:145], v[158:161], v[106:109]
	v_mfma_f32_16x16x32_bf16 v[94:97], v[134:137], v[166:169], v[94:97]
	v_mfma_f32_16x16x32_bf16 v[90:93], v[142:145], v[166:169], v[90:93]
	s_waitcnt lgkmcnt(0)
	v_mfma_f32_16x16x32_bf16 v[78:81], v[134:137], v[174:177], v[78:81]
	v_mfma_f32_16x16x32_bf16 v[74:77], v[142:145], v[174:177], v[74:77]
	s_setprio 0
	s_barrier
	s_mov_b32 m0, s28
	s_add_i32 s33, s73, 0x80
	ds_read_b128 v[178:181], v199
	ds_read_b128 v[182:185], v199 offset:1024
	ds_read_b128 v[200:203], v199 offset:2048
	ds_read_b128 v[204:207], v199 offset:3072
	buffer_load_dwordx4 v192, s[8:11], s33 offen lds
	s_add_i32 s33, s73, 0x20080
	s_mov_b32 m0, s29
	s_nop 0
	buffer_load_dwordx4 v192, s[8:11], s33 offen lds
	s_waitcnt vmcnt(10)
	s_barrier
	s_waitcnt lgkmcnt(0)
	s_setprio 1
	s_waitcnt lgkmcnt(3)
	v_mfma_f32_16x16x32_bf16 v[118:121], v[178:181], v[146:149], v[118:121]
	s_waitcnt lgkmcnt(1)
	v_mfma_f32_16x16x32_bf16 v[114:117], v[200:203], v[146:149], v[114:117]
	v_mfma_f32_16x16x32_bf16 v[102:105], v[178:181], v[154:157], v[102:105]
	v_mfma_f32_16x16x32_bf16 v[98:101], v[200:203], v[154:157], v[98:101]
	v_mfma_f32_16x16x32_bf16 v[86:89], v[178:181], v[162:165], v[86:89]
	v_mfma_f32_16x16x32_bf16 v[82:85], v[200:203], v[162:165], v[82:85]
	v_mfma_f32_16x16x32_bf16 v[70:73], v[178:181], v[170:173], v[70:73]
	v_mfma_f32_16x16x32_bf16 v[66:69], v[200:203], v[170:173], v[66:69]
	v_mfma_f32_16x16x32_bf16 v[118:121], v[182:185], v[150:153], v[118:121]
	s_waitcnt lgkmcnt(0)
	v_mfma_f32_16x16x32_bf16 v[114:117], v[204:207], v[150:153], v[114:117]
	v_mfma_f32_16x16x32_bf16 v[102:105], v[182:185], v[158:161], v[102:105]
	v_mfma_f32_16x16x32_bf16 v[98:101], v[204:207], v[158:161], v[98:101]
	v_mfma_f32_16x16x32_bf16 v[86:89], v[182:185], v[166:169], v[86:89]
	v_mfma_f32_16x16x32_bf16 v[82:85], v[204:207], v[166:169], v[82:85]
	v_mfma_f32_16x16x32_bf16 v[70:73], v[182:185], v[174:177], v[70:73]
	v_mfma_f32_16x16x32_bf16 v[66:69], v[204:207], v[174:177], v[66:69]
	s_setprio 0
	s_mov_b32 m0, s30
	s_barrier
	ds_read_b128 v[146:149], v196 offset:49152
	ds_read_b128 v[150:153], v196 offset:50176
	ds_read_b128 v[154:157], v196 offset:51200
	ds_read_b128 v[158:161], v196 offset:52224
	ds_read_b128 v[162:165], v196 offset:53248
	ds_read_b128 v[166:169], v196 offset:54272
	ds_read_b128 v[170:173], v196 offset:55296
	ds_read_b128 v[174:177], v196 offset:56320
	buffer_load_dwordx4 v1, s[48:51], s79 offen lds
	s_add_i32 s78, s78, 0x20080
	s_mov_b32 m0, s31
	s_nop 0
	buffer_load_dwordx4 v1, s[48:51], s78 offen lds
	s_barrier
	s_waitcnt lgkmcnt(0)
	s_setprio 1
	s_waitcnt lgkmcnt(7)
	v_mfma_f32_16x16x32_bf16 v[62:65], v[130:133], v[146:149], v[62:65]
	v_mfma_f32_16x16x32_bf16 v[58:61], v[138:141], v[146:149], v[58:61]
	s_waitcnt lgkmcnt(5)
	v_mfma_f32_16x16x32_bf16 v[46:49], v[130:133], v[154:157], v[46:49]
	v_mfma_f32_16x16x32_bf16 v[42:45], v[138:141], v[154:157], v[42:45]
	s_waitcnt lgkmcnt(3)
	v_mfma_f32_16x16x32_bf16 v[30:33], v[130:133], v[162:165], v[30:33]
	v_mfma_f32_16x16x32_bf16 v[26:29], v[138:141], v[162:165], v[26:29]
	s_waitcnt lgkmcnt(1)
	v_mfma_f32_16x16x32_bf16 v[14:17], v[130:133], v[170:173], v[14:17]
	v_mfma_f32_16x16x32_bf16 v[10:13], v[138:141], v[170:173], v[10:13]
	v_mfma_f32_16x16x32_bf16 v[62:65], v[134:137], v[150:153], v[62:65]
	v_mfma_f32_16x16x32_bf16 v[58:61], v[142:145], v[150:153], v[58:61]
	v_mfma_f32_16x16x32_bf16 v[46:49], v[134:137], v[158:161], v[46:49]
	v_mfma_f32_16x16x32_bf16 v[42:45], v[142:145], v[158:161], v[42:45]
	v_mfma_f32_16x16x32_bf16 v[30:33], v[134:137], v[166:169], v[30:33]
	v_mfma_f32_16x16x32_bf16 v[26:29], v[142:145], v[166:169], v[26:29]
	s_waitcnt lgkmcnt(0)
	v_mfma_f32_16x16x32_bf16 v[14:17], v[134:137], v[174:177], v[14:17]
	v_mfma_f32_16x16x32_bf16 v[10:13], v[142:145], v[174:177], v[10:13]
	s_setprio 0
	s_barrier
	s_mov_b32 m0, s34
	s_add_i32 s33, s73, 0x40080
	buffer_load_dwordx4 v192, s[8:11], s33 offen lds
	s_add_i32 s73, s73, 0x60080
	s_mov_b32 m0, s35
	s_nop 0
	buffer_load_dwordx4 v192, s[8:11], s73 offen lds
	s_waitcnt vmcnt(6)
	s_barrier
	s_setprio 1
	v_mfma_f32_16x16x32_bf16 v[54:57], v[178:181], v[146:149], v[54:57]
	v_mfma_f32_16x16x32_bf16 v[50:53], v[200:203], v[146:149], v[50:53]
	v_mfma_f32_16x16x32_bf16 v[38:41], v[178:181], v[154:157], v[38:41]
	v_mfma_f32_16x16x32_bf16 v[34:37], v[200:203], v[154:157], v[34:37]
	v_mfma_f32_16x16x32_bf16 v[22:25], v[178:181], v[162:165], v[22:25]
	v_mfma_f32_16x16x32_bf16 v[18:21], v[200:203], v[162:165], v[18:21]
	v_mfma_f32_16x16x32_bf16 v[6:9], v[178:181], v[170:173], v[6:9]
	v_mfma_f32_16x16x32_bf16 v[2:5], v[200:203], v[170:173], v[2:5]
	v_mfma_f32_16x16x32_bf16 v[54:57], v[182:185], v[150:153], v[54:57]
	v_mfma_f32_16x16x32_bf16 v[50:53], v[204:207], v[150:153], v[50:53]
	v_mfma_f32_16x16x32_bf16 v[38:41], v[182:185], v[158:161], v[38:41]
	v_mfma_f32_16x16x32_bf16 v[34:37], v[204:207], v[158:161], v[34:37]
	v_mfma_f32_16x16x32_bf16 v[22:25], v[182:185], v[166:169], v[22:25]
	v_mfma_f32_16x16x32_bf16 v[18:21], v[204:207], v[166:169], v[18:21]
	v_mfma_f32_16x16x32_bf16 v[6:9], v[182:185], v[174:177], v[6:9]
	v_mfma_f32_16x16x32_bf16 v[2:5], v[204:207], v[174:177], v[2:5]
	s_setprio 0
	s_add_i32 s13, s13, 2
	s_addk_i32 s7, 0x100
	s_addk_i32 s12, 0x100
	s_cmp_gt_u32 s13, 13
	s_barrier

.LBB0_2508:
	s_lshl_b32 s72, s58, 18
	s_and_b64 s[6:7], s[6:7], exec
	v_mov_b32_e32 v2, 0
	s_cselect_b32 s6, s72, s84
	s_add_i32 s7, s84, 0x30080
	s_addk_i32 s79, 0x100
	s_mov_b32 s84, -2
	ds_read_b128 v[142:145], v137
	ds_read_b128 v[146:149], v137 offset:1024
	ds_read_b128 v[150:153], v137 offset:2048
	ds_read_b128 v[154:157], v137 offset:3072
	s_add_i32 s10, s7, 0xfffd0080
	s_cmp_eq_u32 s84, 4
	s_cselect_b32 s86, s6, s10
	s_cselect_b32 s85, s59, s79
	s_or_b32 s87, s86, 0x80
	s_add_i32 s10, s7, 0xffff0000
	s_mov_b32 m0, s38
	ds_read_b128 v[158:161], v138
	ds_read_b128 v[162:165], v138 offset:1024
	ds_read_b128 v[166:169], v138 offset:2048
	ds_read_b128 v[170:173], v138 offset:3072
	ds_read_b128 v[174:177], v138 offset:4096
	ds_read_b128 v[178:181], v138 offset:5120
	ds_read_b128 v[182:185], v138 offset:6144
	ds_read_b128 v[186:189], v138 offset:7168
	buffer_load_dwordx4 v1, s[44:47], s10 offen lds
	s_mov_b32 m0, s39
	s_nop 0
	buffer_load_dwordx4 v1, s[44:47], s7 offen lds
	s_waitcnt lgkmcnt(8)
	s_barrier
	s_waitcnt lgkmcnt(0)
	s_setprio 1
	s_waitcnt lgkmcnt(4)
	v_mfma_f32_16x16x128_f8f6f4 v[114:117], v[142:149], v[166:173], 0
	v_mfma_f32_16x16x128_f8f6f4 v[106:109], v[150:157], v[166:173], 0
	s_waitcnt lgkmcnt(2)
	v_mfma_f32_16x16x128_f8f6f4 v[98:101], v[142:149], v[174:181], 0
	v_mfma_f32_16x16x128_f8f6f4 v[198:201], v[142:149], v[158:165], 0
	v_mfma_f32_16x16x128_f8f6f4 v[202:205], v[150:157], v[158:165], 0
	v_mfma_f32_16x16x128_f8f6f4 v[206:209], v[150:157], v[174:181], 0
	s_waitcnt lgkmcnt(0)
	v_mfma_f32_16x16x128_f8f6f4 v[210:213], v[142:149], v[182:189], 0
	v_mfma_f32_16x16x128_f8f6f4 v[214:217], v[150:157], v[182:189], 0
	s_setprio 0
	s_barrier
	s_mov_b32 m0, s22
	s_mov_b32 s10, s46
	s_mov_b32 s11, s47
	ds_read_b128 v[122:125], v139
	ds_read_b128 v[126:129], v139 offset:1024
	ds_read_b128 v[190:193], v139 offset:2048
	ds_read_b128 v[194:197], v139 offset:3072
	buffer_load_dwordx4 v134, s[8:11], s85 offen lds
	s_add_i32 s33, s85, 0x10000
	s_mov_b32 m0, s23
	s_nop 0
	buffer_load_dwordx4 v134, s[8:11], s33 offen lds
	s_barrier
	s_waitcnt lgkmcnt(0)
	s_setprio 1
	s_waitcnt lgkmcnt(2)
	v_mfma_f32_16x16x128_f8f6f4 v[118:121], v[122:129], v[158:165], 0
	s_waitcnt lgkmcnt(0)
	v_mfma_f32_16x16x128_f8f6f4 v[110:113], v[190:197], v[158:165], 0
	v_mfma_f32_16x16x128_f8f6f4 v[102:105], v[122:129], v[166:173], 0
	v_mfma_f32_16x16x128_f8f6f4 v[158:161], v[190:197], v[166:173], 0
	v_mfma_f32_16x16x128_f8f6f4 v[162:165], v[122:129], v[174:181], 0
	v_mfma_f32_16x16x128_f8f6f4 v[166:169], v[190:197], v[174:181], 0
	v_mfma_f32_16x16x128_f8f6f4 v[170:173], v[122:129], v[182:189], 0
	v_mfma_f32_16x16x128_f8f6f4 v[174:177], v[190:197], v[182:189], 0
	s_setprio 0
	s_mov_b32 m0, s21
	s_barrier
	ds_read_b128 v[66:69], v138 offset:16384
	s_nop 1
	ds_read_b128 v[70:73], v138 offset:17408
	ds_read_b128 v[74:77], v138 offset:18432
	ds_read_b128 v[78:81], v138 offset:19456
	ds_read_b128 v[82:85], v138 offset:20480
	ds_read_b128 v[86:89], v138 offset:21504
	ds_read_b128 v[90:93], v138 offset:22528
	ds_read_b128 v[94:97], v138 offset:23552
	buffer_load_dwordx4 v1, s[44:47], s86 offen lds
	s_add_i32 s33, s86, 0x10000
	s_mov_b32 m0, s24
	s_nop 0
	buffer_load_dwordx4 v1, s[44:47], s33 offen lds
	s_barrier
	s_waitcnt lgkmcnt(0)
	s_setprio 1
	s_waitcnt lgkmcnt(6)
	v_mfma_f32_16x16x128_f8f6f4 v[62:65], v[142:149], v[66:73], 0
	v_mfma_f32_16x16x128_f8f6f4 v[58:61], v[150:157], v[66:73], 0
	s_waitcnt lgkmcnt(4)
	v_mfma_f32_16x16x128_f8f6f4 v[50:53], v[142:149], v[74:81], 0
	s_waitcnt lgkmcnt(0)
	v_mfma_f32_16x16x128_f8f6f4 v[230:233], v[142:149], v[90:97], 0
	v_mfma_f32_16x16x128_f8f6f4 v[218:221], v[150:157], v[74:81], 0
	v_mfma_f32_16x16x128_f8f6f4 v[222:225], v[142:149], v[82:89], 0
	v_mfma_f32_16x16x128_f8f6f4 v[226:229], v[150:157], v[82:89], 0
	v_mfma_f32_16x16x128_f8f6f4 v[234:237], v[150:157], v[90:97], 0
	s_setprio 0
	s_barrier
	s_mov_b32 m0, s25
	s_add_i32 s33, s85, 0x20000
	buffer_load_dwordx4 v134, s[8:11], s33 offen lds
	s_add_i32 s33, s85, 0x30000
	s_mov_b32 m0, s26
	s_nop 0
	buffer_load_dwordx4 v134, s[8:11], s33 offen lds
	s_cmp_eq_u32 s100, 0
	s_cbranch_scc1 .Lfw_12_a_p
	s_waitcnt vmcnt(16)
	s_mov_b32 s100, 0
	s_branch .Lfw_12_b_p

.Lfw_12_b_p:
	s_barrier
	s_setprio 1
	v_mfma_f32_16x16x128_f8f6f4 v[54:57], v[122:129], v[66:73], 0
	v_mfma_f32_16x16x128_f8f6f4 v[238:241], v[190:197], v[66:73], 0
	v_mfma_f32_16x16x128_f8f6f4 v[242:245], v[122:129], v[74:81], 0
	v_mfma_f32_16x16x128_f8f6f4 v[246:249], v[190:197], v[74:81], 0
	v_mfma_f32_16x16x128_f8f6f4 v[250:253], v[122:129], v[82:89], 0
	v_mfma_f32_16x16x128_f8f6f4 v[130:133], v[190:197], v[82:89], 0
	v_mfma_f32_16x16x128_f8f6f4 v[66:69], v[122:129], v[90:97], 0
	v_mfma_f32_16x16x128_f8f6f4 v[190:193], v[190:197], v[90:97], 0
	s_setprio 0
	s_barrier
	s_nop 4
	ds_read_b128 v[2:5], v140
	ds_read_b128 v[6:9], v140 offset:1024
	ds_read_b128 v[10:13], v140 offset:2048
	ds_read_b128 v[14:17], v140 offset:3072
	s_mov_b32 m0, s27
	s_add_i32 s33, s86, 0x20000
	ds_read_b128 v[18:21], v138 offset:32768
	ds_read_b128 v[22:25], v138 offset:33792
	ds_read_b128 v[26:29], v138 offset:34816
	ds_read_b128 v[30:33], v138 offset:35840
	ds_read_b128 v[34:37], v138 offset:36864
	ds_read_b128 v[38:41], v138 offset:37888
	ds_read_b128 v[42:45], v138 offset:38912
	ds_read_b128 v[46:49], v138 offset:39936
	buffer_load_dwordx4 v1, s[44:47], s33 offen lds
	s_add_i32 s33, s86, 0x30000
	s_mov_b32 m0, s28
	s_nop 0
	buffer_load_dwordx4 v1, s[44:47], s33 offen lds
	s_waitcnt lgkmcnt(8)
	s_barrier
	s_waitcnt lgkmcnt(0)
	s_setprio 1
	s_waitcnt lgkmcnt(6)
	v_mfma_f32_16x16x128_f8f6f4 v[126:129], v[2:9], v[18:25], v[198:201]
	v_mfma_f32_16x16x128_f8f6f4 v[122:125], v[10:17], v[18:25], v[202:205]
	s_waitcnt lgkmcnt(4)
	v_mfma_f32_16x16x128_f8f6f4 v[114:117], v[2:9], v[26:33], v[114:117]
	v_mfma_f32_16x16x128_f8f6f4 v[106:109], v[10:17], v[26:33], v[106:109]
	s_waitcnt lgkmcnt(2)
	v_mfma_f32_16x16x128_f8f6f4 v[98:101], v[2:9], v[34:41], v[98:101]
	v_mfma_f32_16x16x128_f8f6f4 v[90:93], v[10:17], v[34:41], v[206:209]
	s_waitcnt lgkmcnt(0)
	v_mfma_f32_16x16x128_f8f6f4 v[82:85], v[2:9], v[42:49], v[210:213]
	v_mfma_f32_16x16x128_f8f6f4 v[74:77], v[10:17], v[42:49], v[214:217]
	s_setprio 0
	s_barrier
	s_mov_b32 m0, s30
	s_add_i32 s33, s85, 0x80
	ds_read_b128 v[142:145], v141
	ds_read_b128 v[146:149], v141 offset:1024
	ds_read_b128 v[150:153], v141 offset:2048
	ds_read_b128 v[154:157], v141 offset:3072
	buffer_load_dwordx4 v134, s[8:11], s33 offen lds
	s_add_i32 s33, s85, 0x10080
	s_mov_b32 m0, s31
	s_nop 0
	buffer_load_dwordx4 v134, s[8:11], s33 offen lds
	s_waitcnt vmcnt(10)
	s_barrier
	s_waitcnt lgkmcnt(0)
	s_setprio 1
	s_waitcnt lgkmcnt(2)
	v_mfma_f32_16x16x128_f8f6f4 v[118:121], v[142:149], v[18:25], v[118:121]
	s_waitcnt lgkmcnt(0)
	v_mfma_f32_16x16x128_f8f6f4 v[110:113], v[150:157], v[18:25], v[110:113]
	v_mfma_f32_16x16x128_f8f6f4 v[102:105], v[142:149], v[26:33], v[102:105]
	v_mfma_f32_16x16x128_f8f6f4 v[94:97], v[150:157], v[26:33], v[158:161]
	v_mfma_f32_16x16x128_f8f6f4 v[86:89], v[142:149], v[34:41], v[162:165]
	v_mfma_f32_16x16x128_f8f6f4 v[78:81], v[150:157], v[34:41], v[166:169]
	v_mfma_f32_16x16x128_f8f6f4 v[70:73], v[142:149], v[42:49], v[170:173]
	v_mfma_f32_16x16x128_f8f6f4 v[18:21], v[150:157], v[42:49], v[174:177]
	s_setprio 0
	s_mov_b32 m0, s34
	s_barrier
	ds_read_b128 v[158:161], v138 offset:49152
	ds_read_b128 v[162:165], v138 offset:50176
	ds_read_b128 v[166:169], v138 offset:51200
	ds_read_b128 v[170:173], v138 offset:52224
	ds_read_b128 v[174:177], v138 offset:53248
	ds_read_b128 v[178:181], v138 offset:54272
	ds_read_b128 v[182:185], v138 offset:55296
	ds_read_b128 v[186:189], v138 offset:56320
	buffer_load_dwordx4 v1, s[44:47], s87 offen lds
	s_add_i32 s86, s86, 0x10080
	s_mov_b32 m0, s35
	s_nop 0
	buffer_load_dwordx4 v1, s[44:47], s86 offen lds
	s_barrier
	s_waitcnt lgkmcnt(0)
	s_setprio 1
	s_waitcnt lgkmcnt(6)
	v_mfma_f32_16x16x128_f8f6f4 v[62:65], v[2:9], v[158:165], v[62:65]
	v_mfma_f32_16x16x128_f8f6f4 v[58:61], v[10:17], v[158:165], v[58:61]
	s_waitcnt lgkmcnt(4)
	v_mfma_f32_16x16x128_f8f6f4 v[50:53], v[2:9], v[166:173], v[50:53]
	v_mfma_f32_16x16x128_f8f6f4 v[42:45], v[10:17], v[166:173], v[218:221]
	s_waitcnt lgkmcnt(2)
	v_mfma_f32_16x16x128_f8f6f4 v[34:37], v[2:9], v[174:181], v[222:225]
	v_mfma_f32_16x16x128_f8f6f4 v[26:29], v[10:17], v[174:181], v[226:229]
	s_waitcnt lgkmcnt(0)
	v_mfma_f32_16x16x128_f8f6f4 v[230:233], v[2:9], v[182:189], v[230:233]
	v_mfma_f32_16x16x128_f8f6f4 v[10:13], v[10:17], v[182:189], v[234:237]
	s_setprio 0
	s_barrier
	s_mov_b32 m0, s36
	s_add_i32 s33, s85, 0x20080
	buffer_load_dwordx4 v134, s[8:11], s33 offen lds
	s_add_i32 s85, s85, 0x30080
	s_mov_b32 m0, s37
	s_nop 0
	buffer_load_dwordx4 v134, s[8:11], s85 offen lds
	s_waitcnt vmcnt(6)
	s_barrier
	s_setprio 1
	v_mfma_f32_16x16x128_f8f6f4 v[54:57], v[142:149], v[158:165], v[54:57]
	v_mfma_f32_16x16x128_f8f6f4 v[46:49], v[150:157], v[158:165], v[238:241]
	v_mfma_f32_16x16x128_f8f6f4 v[38:41], v[142:149], v[166:173], v[242:245]
	v_mfma_f32_16x16x128_f8f6f4 v[30:33], v[150:157], v[166:173], v[246:249]
	v_mfma_f32_16x16x128_f8f6f4 v[22:25], v[142:149], v[174:181], v[250:253]
	v_mfma_f32_16x16x128_f8f6f4 v[14:17], v[150:157], v[174:181], v[130:133]
	v_mfma_f32_16x16x128_f8f6f4 v[6:9], v[142:149], v[182:189], v[66:69]
	v_mfma_f32_16x16x128_f8f6f4 v[2:5], v[150:157], v[182:189], v[190:193]
	s_setprio 0
	s_add_i32 s84, s84, 2
	s_addk_i32 s7, 0x100
	s_addk_i32 s79, 0x100
	s_cmp_gt_u32 s84, 5
	s_barrier

.LBB0_2681:
	s_lshl_b32 s72, s58, 19
	s_and_b64 s[6:7], s[6:7], exec
	v_mov_b32_e32 v2, 0
	s_cselect_b32 s6, s72, s84
	s_add_i32 s7, s84, 0x60080
	s_addk_i32 s79, 0x100
	s_mov_b32 s84, -2
	ds_read_b128 v[136:139], v147
	ds_read_b128 v[140:143], v147 offset:1024
	ds_read_b128 v[152:155], v147 offset:2048
	ds_read_b128 v[156:159], v147 offset:3072
	s_add_i32 s10, s7, 0xfffa0080
	s_cmp_eq_u32 s84, 12
	s_cselect_b32 s86, s6, s10
	s_cselect_b32 s85, s59, s79
	s_or_b32 s87, s86, 0x80
	s_add_i32 s10, s7, 0xfffe0000
	s_mov_b32 m0, s39
	ds_read_b128 v[160:163], v148
	ds_read_b128 v[164:167], v148 offset:1024
	ds_read_b128 v[168:171], v148 offset:2048
	ds_read_b128 v[172:175], v148 offset:3072
	ds_read_b128 v[176:179], v148 offset:4096
	ds_read_b128 v[180:183], v148 offset:5120
	ds_read_b128 v[184:187], v148 offset:6144
	ds_read_b128 v[188:191], v148 offset:7168
	buffer_load_dwordx4 v1, s[40:43], s10 offen lds
	s_mov_b32 m0, s45
	s_nop 0
	buffer_load_dwordx4 v1, s[40:43], s7 offen lds
	s_waitcnt lgkmcnt(8)
	s_barrier
	s_waitcnt lgkmcnt(0)
	s_setprio 1
	s_waitcnt lgkmcnt(7)
	v_mfma_f32_16x16x32_bf16 v[126:129], v[136:139], v[160:163], 0
	v_mfma_f32_16x16x32_bf16 v[122:125], v[152:155], v[160:163], 0
	s_waitcnt lgkmcnt(5)
	v_mfma_f32_16x16x32_bf16 v[118:121], v[136:139], v[168:171], 0
	v_mfma_f32_16x16x32_bf16 v[110:113], v[152:155], v[168:171], 0
	s_waitcnt lgkmcnt(3)
	v_mfma_f32_16x16x32_bf16 v[102:105], v[136:139], v[176:179], 0
	v_mfma_f32_16x16x32_bf16 v[94:97], v[152:155], v[176:179], 0
	s_waitcnt lgkmcnt(1)
	v_mfma_f32_16x16x32_bf16 v[86:89], v[136:139], v[184:187], 0
	v_mfma_f32_16x16x32_bf16 v[78:81], v[152:155], v[184:187], 0
	v_mfma_f32_16x16x32_bf16 v[126:129], v[140:143], v[164:167], v[126:129]
	v_mfma_f32_16x16x32_bf16 v[122:125], v[156:159], v[164:167], v[122:125]
	v_mfma_f32_16x16x32_bf16 v[118:121], v[140:143], v[172:175], v[118:121]
	v_mfma_f32_16x16x32_bf16 v[110:113], v[156:159], v[172:175], v[110:113]
	v_mfma_f32_16x16x32_bf16 v[102:105], v[140:143], v[180:183], v[102:105]
	v_mfma_f32_16x16x32_bf16 v[94:97], v[156:159], v[180:183], v[94:97]
	s_waitcnt lgkmcnt(0)
	v_mfma_f32_16x16x32_bf16 v[86:89], v[140:143], v[188:191], v[86:89]
	v_mfma_f32_16x16x32_bf16 v[78:81], v[156:159], v[188:191], v[78:81]
	s_setprio 0
	s_barrier
	s_mov_b32 m0, s23
	s_mov_b32 s10, s42
	s_mov_b32 s11, s43
	ds_read_b128 v[192:195], v149
	ds_read_b128 v[196:199], v149 offset:1024
	ds_read_b128 v[200:203], v149 offset:2048
	ds_read_b128 v[204:207], v149 offset:3072
	buffer_load_dwordx4 v144, s[8:11], s85 offen lds
	s_add_i32 s33, s85, 0x20000
	s_mov_b32 m0, s24
	s_nop 0
	buffer_load_dwordx4 v144, s[8:11], s33 offen lds
	s_barrier
	s_waitcnt lgkmcnt(0)
	s_setprio 1
	s_waitcnt lgkmcnt(3)
	v_mfma_f32_16x16x32_bf16 v[114:117], v[192:195], v[160:163], 0
	s_waitcnt lgkmcnt(1)
	v_mfma_f32_16x16x32_bf16 v[106:109], v[200:203], v[160:163], 0
	v_mfma_f32_16x16x32_bf16 v[98:101], v[192:195], v[168:171], 0
	v_mfma_f32_16x16x32_bf16 v[90:93], v[200:203], v[168:171], 0
	v_mfma_f32_16x16x32_bf16 v[82:85], v[192:195], v[176:179], 0
	v_mfma_f32_16x16x32_bf16 v[74:77], v[200:203], v[176:179], 0
	v_mfma_f32_16x16x32_bf16 v[70:73], v[192:195], v[184:187], 0
	v_mfma_f32_16x16x32_bf16 v[66:69], v[200:203], v[184:187], 0
	v_mfma_f32_16x16x32_bf16 v[114:117], v[196:199], v[164:167], v[114:117]
	s_waitcnt lgkmcnt(0)
	v_mfma_f32_16x16x32_bf16 v[106:109], v[204:207], v[164:167], v[106:109]
	v_mfma_f32_16x16x32_bf16 v[98:101], v[196:199], v[172:175], v[98:101]
	v_mfma_f32_16x16x32_bf16 v[90:93], v[204:207], v[172:175], v[90:93]
	v_mfma_f32_16x16x32_bf16 v[82:85], v[196:199], v[180:183], v[82:85]
	v_mfma_f32_16x16x32_bf16 v[74:77], v[204:207], v[180:183], v[74:77]
	v_mfma_f32_16x16x32_bf16 v[70:73], v[196:199], v[188:191], v[70:73]
	v_mfma_f32_16x16x32_bf16 v[66:69], v[204:207], v[188:191], v[66:69]
	s_setprio 0
	s_mov_b32 m0, s22
	s_barrier
	ds_read_b128 v[160:163], v148 offset:16384
	ds_read_b128 v[164:167], v148 offset:17408
	ds_read_b128 v[168:171], v148 offset:18432
	ds_read_b128 v[172:175], v148 offset:19456
	ds_read_b128 v[176:179], v148 offset:20480
	ds_read_b128 v[180:183], v148 offset:21504
	ds_read_b128 v[184:187], v148 offset:22528
	ds_read_b128 v[188:191], v148 offset:23552
	buffer_load_dwordx4 v1, s[40:43], s86 offen lds
	s_add_i32 s33, s86, 0x20000
	s_mov_b32 m0, s25
	s_nop 0
	buffer_load_dwordx4 v1, s[40:43], s33 offen lds
	s_barrier
	s_waitcnt lgkmcnt(0)
	s_setprio 1
	s_waitcnt lgkmcnt(7)
	v_mfma_f32_16x16x32_bf16 v[62:65], v[136:139], v[160:163], 0
	v_mfma_f32_16x16x32_bf16 v[58:61], v[152:155], v[160:163], 0
	s_waitcnt lgkmcnt(5)
	v_mfma_f32_16x16x32_bf16 v[54:57], v[136:139], v[168:171], 0
	v_mfma_f32_16x16x32_bf16 v[46:49], v[152:155], v[168:171], 0
	s_waitcnt lgkmcnt(3)
	v_mfma_f32_16x16x32_bf16 v[38:41], v[136:139], v[176:179], 0
	v_mfma_f32_16x16x32_bf16 v[30:33], v[152:155], v[176:179], 0
	s_waitcnt lgkmcnt(1)
	v_mfma_f32_16x16x32_bf16 v[22:25], v[136:139], v[184:187], 0
	v_mfma_f32_16x16x32_bf16 v[14:17], v[152:155], v[184:187], 0
	v_mfma_f32_16x16x32_bf16 v[62:65], v[140:143], v[164:167], v[62:65]
	v_mfma_f32_16x16x32_bf16 v[58:61], v[156:159], v[164:167], v[58:61]
	v_mfma_f32_16x16x32_bf16 v[54:57], v[140:143], v[172:175], v[54:57]
	v_mfma_f32_16x16x32_bf16 v[46:49], v[156:159], v[172:175], v[46:49]
	v_mfma_f32_16x16x32_bf16 v[38:41], v[140:143], v[180:183], v[38:41]
	v_mfma_f32_16x16x32_bf16 v[30:33], v[156:159], v[180:183], v[30:33]
	s_waitcnt lgkmcnt(0)
	v_mfma_f32_16x16x32_bf16 v[22:25], v[140:143], v[188:191], v[22:25]
	v_mfma_f32_16x16x32_bf16 v[14:17], v[156:159], v[188:191], v[14:17]
	s_setprio 0
	s_barrier
	s_mov_b32 m0, s26
	s_add_i32 s33, s85, 0x40000
	buffer_load_dwordx4 v144, s[8:11], s33 offen lds
	s_add_i32 s33, s85, 0x60000
	s_mov_b32 m0, s27
	s_nop 0
	buffer_load_dwordx4 v144, s[8:11], s33 offen lds
	s_cmp_eq_u32 s100, 0
	s_cbranch_scc1 .Lfw_13_a_p
	s_waitcnt vmcnt(16)
	s_mov_b32 s100, 0
	s_branch .Lfw_13_b_p

.Lfw_13_b_p:
	s_barrier
	s_setprio 1
	v_mfma_f32_16x16x32_bf16 v[50:53], v[192:195], v[160:163], 0
	v_mfma_f32_16x16x32_bf16 v[42:45], v[200:203], v[160:163], 0
	v_mfma_f32_16x16x32_bf16 v[34:37], v[192:195], v[168:171], 0
	v_mfma_f32_16x16x32_bf16 v[26:29], v[200:203], v[168:171], 0
	v_mfma_f32_16x16x32_bf16 v[18:21], v[192:195], v[176:179], 0
	v_mfma_f32_16x16x32_bf16 v[10:13], v[200:203], v[176:179], 0
	v_mfma_f32_16x16x32_bf16 v[6:9], v[192:195], v[184:187], 0
	v_mfma_f32_16x16x32_bf16 v[2:5], v[200:203], v[184:187], 0
	v_mfma_f32_16x16x32_bf16 v[50:53], v[196:199], v[164:167], v[50:53]
	v_mfma_f32_16x16x32_bf16 v[42:45], v[204:207], v[164:167], v[42:45]
	v_mfma_f32_16x16x32_bf16 v[34:37], v[196:199], v[172:175], v[34:37]
	v_mfma_f32_16x16x32_bf16 v[26:29], v[204:207], v[172:175], v[26:29]
	v_mfma_f32_16x16x32_bf16 v[18:21], v[196:199], v[180:183], v[18:21]
	v_mfma_f32_16x16x32_bf16 v[10:13], v[204:207], v[180:183], v[10:13]
	v_mfma_f32_16x16x32_bf16 v[6:9], v[196:199], v[188:191], v[6:9]
	v_mfma_f32_16x16x32_bf16 v[2:5], v[204:207], v[188:191], v[2:5]
	s_setprio 0
	s_barrier
	ds_read_b128 v[136:139], v150
	ds_read_b128 v[140:143], v150 offset:1024
	ds_read_b128 v[152:155], v150 offset:2048
	ds_read_b128 v[156:159], v150 offset:3072
	s_mov_b32 m0, s28
	s_add_i32 s33, s86, 0x40000
	ds_read_b128 v[160:163], v148 offset:32768
	ds_read_b128 v[164:167], v148 offset:33792
	ds_read_b128 v[168:171], v148 offset:34816
	ds_read_b128 v[172:175], v148 offset:35840
	ds_read_b128 v[176:179], v148 offset:36864
	ds_read_b128 v[180:183], v148 offset:37888
	ds_read_b128 v[184:187], v148 offset:38912
	ds_read_b128 v[188:191], v148 offset:39936
	buffer_load_dwordx4 v1, s[40:43], s33 offen lds
	s_add_i32 s33, s86, 0x60000
	s_mov_b32 m0, s29
	s_nop 0
	buffer_load_dwordx4 v1, s[40:43], s33 offen lds
	s_waitcnt lgkmcnt(8)
	s_barrier
	s_waitcnt lgkmcnt(0)
	s_setprio 1
	s_waitcnt lgkmcnt(7)
	v_mfma_f32_16x16x32_bf16 v[126:129], v[136:139], v[160:163], v[126:129]
	v_mfma_f32_16x16x32_bf16 v[122:125], v[152:155], v[160:163], v[122:125]
	s_waitcnt lgkmcnt(5)
	v_mfma_f32_16x16x32_bf16 v[118:121], v[136:139], v[168:171], v[118:121]
	v_mfma_f32_16x16x32_bf16 v[110:113], v[152:155], v[168:171], v[110:113]
	s_waitcnt lgkmcnt(3)
	v_mfma_f32_16x16x32_bf16 v[102:105], v[136:139], v[176:179], v[102:105]
	v_mfma_f32_16x16x32_bf16 v[94:97], v[152:155], v[176:179], v[94:97]
	s_waitcnt lgkmcnt(1)
	v_mfma_f32_16x16x32_bf16 v[86:89], v[136:139], v[184:187], v[86:89]
	v_mfma_f32_16x16x32_bf16 v[78:81], v[152:155], v[184:187], v[78:81]
	v_mfma_f32_16x16x32_bf16 v[126:129], v[140:143], v[164:167], v[126:129]
	v_mfma_f32_16x16x32_bf16 v[122:125], v[156:159], v[164:167], v[122:125]
	v_mfma_f32_16x16x32_bf16 v[118:121], v[140:143], v[172:175], v[118:121]
	v_mfma_f32_16x16x32_bf16 v[110:113], v[156:159], v[172:175], v[110:113]
	v_mfma_f32_16x16x32_bf16 v[102:105], v[140:143], v[180:183], v[102:105]
	v_mfma_f32_16x16x32_bf16 v[94:97], v[156:159], v[180:183], v[94:97]
	s_waitcnt lgkmcnt(0)
	v_mfma_f32_16x16x32_bf16 v[86:89], v[140:143], v[188:191], v[86:89]
	v_mfma_f32_16x16x32_bf16 v[78:81], v[156:159], v[188:191], v[78:81]
	s_setprio 0
	s_barrier
	s_mov_b32 m0, s31
	s_or_b32 s33, s85, 0x80
	ds_read_b128 v[192:195], v151
	ds_read_b128 v[196:199], v151 offset:1024
	ds_read_b128 v[200:203], v151 offset:2048
	ds_read_b128 v[204:207], v151 offset:3072
	buffer_load_dwordx4 v144, s[8:11], s33 offen lds
	s_add_i32 s33, s85, 0x20080
	s_mov_b32 m0, s34
	s_nop 0
	buffer_load_dwordx4 v144, s[8:11], s33 offen lds
	s_waitcnt vmcnt(10)
	s_barrier
	s_waitcnt lgkmcnt(0)
	s_setprio 1
	s_waitcnt lgkmcnt(3)
	v_mfma_f32_16x16x32_bf16 v[114:117], v[192:195], v[160:163], v[114:117]
	s_waitcnt lgkmcnt(1)
	v_mfma_f32_16x16x32_bf16 v[106:109], v[200:203], v[160:163], v[106:109]
	v_mfma_f32_16x16x32_bf16 v[98:101], v[192:195], v[168:171], v[98:101]
	v_mfma_f32_16x16x32_bf16 v[90:93], v[200:203], v[168:171], v[90:93]
	v_mfma_f32_16x16x32_bf16 v[82:85], v[192:195], v[176:179], v[82:85]
	v_mfma_f32_16x16x32_bf16 v[74:77], v[200:203], v[176:179], v[74:77]
	v_mfma_f32_16x16x32_bf16 v[70:73], v[192:195], v[184:187], v[70:73]
	v_mfma_f32_16x16x32_bf16 v[66:69], v[200:203], v[184:187], v[66:69]
	v_mfma_f32_16x16x32_bf16 v[114:117], v[196:199], v[164:167], v[114:117]
	s_waitcnt lgkmcnt(0)
	v_mfma_f32_16x16x32_bf16 v[106:109], v[204:207], v[164:167], v[106:109]
	v_mfma_f32_16x16x32_bf16 v[98:101], v[196:199], v[172:175], v[98:101]
	v_mfma_f32_16x16x32_bf16 v[90:93], v[204:207], v[172:175], v[90:93]
	v_mfma_f32_16x16x32_bf16 v[82:85], v[196:199], v[180:183], v[82:85]
	v_mfma_f32_16x16x32_bf16 v[74:77], v[204:207], v[180:183], v[74:77]
	v_mfma_f32_16x16x32_bf16 v[70:73], v[196:199], v[188:191], v[70:73]
	v_mfma_f32_16x16x32_bf16 v[66:69], v[204:207], v[188:191], v[66:69]
	s_setprio 0
	s_mov_b32 m0, s35
	s_barrier
	ds_read_b128 v[160:163], v148 offset:49152
	ds_read_b128 v[164:167], v148 offset:50176
	ds_read_b128 v[168:171], v148 offset:51200
	ds_read_b128 v[172:175], v148 offset:52224
	ds_read_b128 v[176:179], v148 offset:53248
	ds_read_b128 v[180:183], v148 offset:54272
	ds_read_b128 v[184:187], v148 offset:55296
	ds_read_b128 v[188:191], v148 offset:56320
	buffer_load_dwordx4 v1, s[40:43], s87 offen lds
	s_add_i32 s86, s86, 0x20080
	s_mov_b32 m0, s36
	s_nop 0
	buffer_load_dwordx4 v1, s[40:43], s86 offen lds
	s_barrier
	s_waitcnt lgkmcnt(0)
	s_setprio 1
	s_waitcnt lgkmcnt(7)
	v_mfma_f32_16x16x32_bf16 v[62:65], v[136:139], v[160:163], v[62:65]
	v_mfma_f32_16x16x32_bf16 v[58:61], v[152:155], v[160:163], v[58:61]
	s_waitcnt lgkmcnt(5)
	v_mfma_f32_16x16x32_bf16 v[54:57], v[136:139], v[168:171], v[54:57]
	v_mfma_f32_16x16x32_bf16 v[46:49], v[152:155], v[168:171], v[46:49]
	s_waitcnt lgkmcnt(3)
	v_mfma_f32_16x16x32_bf16 v[38:41], v[136:139], v[176:179], v[38:41]
	v_mfma_f32_16x16x32_bf16 v[30:33], v[152:155], v[176:179], v[30:33]
	s_waitcnt lgkmcnt(1)
	v_mfma_f32_16x16x32_bf16 v[22:25], v[136:139], v[184:187], v[22:25]
	v_mfma_f32_16x16x32_bf16 v[14:17], v[152:155], v[184:187], v[14:17]
	v_mfma_f32_16x16x32_bf16 v[62:65], v[140:143], v[164:167], v[62:65]
	v_mfma_f32_16x16x32_bf16 v[58:61], v[156:159], v[164:167], v[58:61]
	v_mfma_f32_16x16x32_bf16 v[54:57], v[140:143], v[172:175], v[54:57]
	v_mfma_f32_16x16x32_bf16 v[46:49], v[156:159], v[172:175], v[46:49]
	v_mfma_f32_16x16x32_bf16 v[38:41], v[140:143], v[180:183], v[38:41]
	v_mfma_f32_16x16x32_bf16 v[30:33], v[156:159], v[180:183], v[30:33]
	s_waitcnt lgkmcnt(0)
	v_mfma_f32_16x16x32_bf16 v[22:25], v[140:143], v[188:191], v[22:25]
	v_mfma_f32_16x16x32_bf16 v[14:17], v[156:159], v[188:191], v[14:17]
	s_setprio 0
	s_barrier
	s_mov_b32 m0, s37
	s_add_i32 s33, s85, 0x40080
	buffer_load_dwordx4 v144, s[8:11], s33 offen lds
	s_add_i32 s85, s85, 0x60080
	s_mov_b32 m0, s38
	s_nop 0
	buffer_load_dwordx4 v144, s[8:11], s85 offen lds
	s_waitcnt vmcnt(6)
	s_barrier
	s_setprio 1
	v_mfma_f32_16x16x32_bf16 v[50:53], v[192:195], v[160:163], v[50:53]
	v_mfma_f32_16x16x32_bf16 v[42:45], v[200:203], v[160:163], v[42:45]
	v_mfma_f32_16x16x32_bf16 v[34:37], v[192:195], v[168:171], v[34:37]
	v_mfma_f32_16x16x32_bf16 v[26:29], v[200:203], v[168:171], v[26:29]
	v_mfma_f32_16x16x32_bf16 v[18:21], v[192:195], v[176:179], v[18:21]
	v_mfma_f32_16x16x32_bf16 v[10:13], v[200:203], v[176:179], v[10:13]
	v_mfma_f32_16x16x32_bf16 v[6:9], v[192:195], v[184:187], v[6:9]
	v_mfma_f32_16x16x32_bf16 v[2:5], v[200:203], v[184:187], v[2:5]
	v_mfma_f32_16x16x32_bf16 v[50:53], v[196:199], v[164:167], v[50:53]
	v_mfma_f32_16x16x32_bf16 v[42:45], v[204:207], v[164:167], v[42:45]
	v_mfma_f32_16x16x32_bf16 v[34:37], v[196:199], v[172:175], v[34:37]
	v_mfma_f32_16x16x32_bf16 v[26:29], v[204:207], v[172:175], v[26:29]
	v_mfma_f32_16x16x32_bf16 v[18:21], v[196:199], v[180:183], v[18:21]
	v_mfma_f32_16x16x32_bf16 v[10:13], v[204:207], v[180:183], v[10:13]
	v_mfma_f32_16x16x32_bf16 v[6:9], v[196:199], v[188:191], v[6:9]
	v_mfma_f32_16x16x32_bf16 v[2:5], v[204:207], v[188:191], v[2:5]
	s_setprio 0
	s_add_i32 s84, s84, 2
	s_addk_i32 s7, 0x100
	s_addk_i32 s79, 0x100
	s_cmp_gt_u32 s84, 13
	s_barrier

.LBB0_2826:
	s_lshl_b32 s58, s47, 19
	s_and_b64 s[6:7], s[6:7], exec
	v_mov_b32_e32 v2, 0
	s_cselect_b32 s6, s58, s13
	s_add_i32 s7, s13, 0x60080
	s_addk_i32 s12, 0x100
	s_mov_b32 s13, -2
	ds_read_b128 v[130:133], v196
	ds_read_b128 v[134:137], v196 offset:1024
	ds_read_b128 v[138:141], v196 offset:2048
	ds_read_b128 v[142:145], v196 offset:3072
	s_add_i32 s10, s7, 0xfffa0080
	s_cmp_eq_u32 s13, 12
	s_cselect_b32 s78, s6, s10
	s_cselect_b32 s73, s57, s12
	s_or_b32 s79, s78, 0x80
	s_add_i32 s10, s7, 0xfffe0000
	s_mov_b32 m0, s38
	ds_read_b128 v[146:149], v197
	ds_read_b128 v[150:153], v197 offset:1024
	ds_read_b128 v[154:157], v197 offset:2048
	ds_read_b128 v[158:161], v197 offset:3072
	ds_read_b128 v[162:165], v197 offset:4096
	ds_read_b128 v[166:169], v197 offset:5120
	ds_read_b128 v[170:173], v197 offset:6144
	ds_read_b128 v[174:177], v197 offset:7168
	buffer_load_dwordx4 v192, s[48:51], s10 offen lds
	s_mov_b32 m0, s39
	s_nop 0
	buffer_load_dwordx4 v192, s[48:51], s7 offen lds
	s_waitcnt lgkmcnt(8)
	s_barrier
	s_waitcnt lgkmcnt(0)
	s_setprio 1
	s_waitcnt lgkmcnt(7)
	v_mfma_f32_16x16x32_bf16 v[126:129], v[130:133], v[146:149], 0
	v_mfma_f32_16x16x32_bf16 v[122:125], v[138:141], v[146:149], 0
	s_waitcnt lgkmcnt(5)
	v_mfma_f32_16x16x32_bf16 v[110:113], v[130:133], v[154:157], 0
	v_mfma_f32_16x16x32_bf16 v[106:109], v[138:141], v[154:157], 0
	s_waitcnt lgkmcnt(3)
	v_mfma_f32_16x16x32_bf16 v[94:97], v[130:133], v[162:165], 0
	v_mfma_f32_16x16x32_bf16 v[90:93], v[138:141], v[162:165], 0
	s_waitcnt lgkmcnt(1)
	v_mfma_f32_16x16x32_bf16 v[78:81], v[130:133], v[170:173], 0
	v_mfma_f32_16x16x32_bf16 v[74:77], v[138:141], v[170:173], 0
	v_mfma_f32_16x16x32_bf16 v[126:129], v[134:137], v[150:153], v[126:129]
	v_mfma_f32_16x16x32_bf16 v[122:125], v[142:145], v[150:153], v[122:125]
	v_mfma_f32_16x16x32_bf16 v[110:113], v[134:137], v[158:161], v[110:113]
	v_mfma_f32_16x16x32_bf16 v[106:109], v[142:145], v[158:161], v[106:109]
	v_mfma_f32_16x16x32_bf16 v[94:97], v[134:137], v[166:169], v[94:97]
	v_mfma_f32_16x16x32_bf16 v[90:93], v[142:145], v[166:169], v[90:93]
	s_waitcnt lgkmcnt(0)
	v_mfma_f32_16x16x32_bf16 v[78:81], v[134:137], v[174:177], v[78:81]
	v_mfma_f32_16x16x32_bf16 v[74:77], v[142:145], v[174:177], v[74:77]
	s_setprio 0
	s_barrier
	s_mov_b32 m0, s16
	s_mov_b32 s10, s50
	s_mov_b32 s11, s51
	ds_read_b128 v[178:181], v198
	ds_read_b128 v[182:185], v198 offset:1024
	ds_read_b128 v[202:205], v198 offset:2048
	ds_read_b128 v[206:209], v198 offset:3072
	buffer_load_dwordx4 v193, s[8:11], s73 offen lds
	s_add_i32 s33, s73, 0x20000
	s_mov_b32 m0, s17
	s_nop 0
	buffer_load_dwordx4 v193, s[8:11], s33 offen lds
	s_barrier
	s_waitcnt lgkmcnt(0)
	s_setprio 1
	s_waitcnt lgkmcnt(3)
	v_mfma_f32_16x16x32_bf16 v[118:121], v[178:181], v[146:149], 0
	s_waitcnt lgkmcnt(1)
	v_mfma_f32_16x16x32_bf16 v[114:117], v[202:205], v[146:149], 0
	v_mfma_f32_16x16x32_bf16 v[102:105], v[178:181], v[154:157], 0
	v_mfma_f32_16x16x32_bf16 v[98:101], v[202:205], v[154:157], 0
	v_mfma_f32_16x16x32_bf16 v[86:89], v[178:181], v[162:165], 0
	v_mfma_f32_16x16x32_bf16 v[82:85], v[202:205], v[162:165], 0
	v_mfma_f32_16x16x32_bf16 v[70:73], v[178:181], v[170:173], 0
	v_mfma_f32_16x16x32_bf16 v[66:69], v[202:205], v[170:173], 0
	v_mfma_f32_16x16x32_bf16 v[118:121], v[182:185], v[150:153], v[118:121]
	s_waitcnt lgkmcnt(0)
	v_mfma_f32_16x16x32_bf16 v[114:117], v[206:209], v[150:153], v[114:117]
	v_mfma_f32_16x16x32_bf16 v[102:105], v[182:185], v[158:161], v[102:105]
	v_mfma_f32_16x16x32_bf16 v[98:101], v[206:209], v[158:161], v[98:101]
	v_mfma_f32_16x16x32_bf16 v[86:89], v[182:185], v[166:169], v[86:89]
	v_mfma_f32_16x16x32_bf16 v[82:85], v[206:209], v[166:169], v[82:85]
	v_mfma_f32_16x16x32_bf16 v[70:73], v[182:185], v[174:177], v[70:73]
	v_mfma_f32_16x16x32_bf16 v[66:69], v[206:209], v[174:177], v[66:69]
	s_setprio 0
	s_mov_b32 m0, s15
	s_barrier
	ds_read_b128 v[146:149], v197 offset:16384
	ds_read_b128 v[150:153], v197 offset:17408
	ds_read_b128 v[154:157], v197 offset:18432
	ds_read_b128 v[158:161], v197 offset:19456
	ds_read_b128 v[162:165], v197 offset:20480
	ds_read_b128 v[166:169], v197 offset:21504
	ds_read_b128 v[170:173], v197 offset:22528
	ds_read_b128 v[174:177], v197 offset:23552
	buffer_load_dwordx4 v192, s[48:51], s78 offen lds
	s_add_i32 s33, s78, 0x20000
	s_mov_b32 m0, s18
	s_nop 0
	buffer_load_dwordx4 v192, s[48:51], s33 offen lds
	s_barrier
	s_waitcnt lgkmcnt(0)
	s_setprio 1
	s_waitcnt lgkmcnt(7)
	v_mfma_f32_16x16x32_bf16 v[62:65], v[130:133], v[146:149], 0
	v_mfma_f32_16x16x32_bf16 v[58:61], v[138:141], v[146:149], 0
	s_waitcnt lgkmcnt(5)
	v_mfma_f32_16x16x32_bf16 v[46:49], v[130:133], v[154:157], 0
	v_mfma_f32_16x16x32_bf16 v[42:45], v[138:141], v[154:157], 0
	s_waitcnt lgkmcnt(3)
	v_mfma_f32_16x16x32_bf16 v[30:33], v[130:133], v[162:165], 0
	v_mfma_f32_16x16x32_bf16 v[26:29], v[138:141], v[162:165], 0
	s_waitcnt lgkmcnt(1)
	v_mfma_f32_16x16x32_bf16 v[14:17], v[130:133], v[170:173], 0
	v_mfma_f32_16x16x32_bf16 v[10:13], v[138:141], v[170:173], 0
	v_mfma_f32_16x16x32_bf16 v[62:65], v[134:137], v[150:153], v[62:65]
	v_mfma_f32_16x16x32_bf16 v[58:61], v[142:145], v[150:153], v[58:61]
	v_mfma_f32_16x16x32_bf16 v[46:49], v[134:137], v[158:161], v[46:49]
	v_mfma_f32_16x16x32_bf16 v[42:45], v[142:145], v[158:161], v[42:45]
	v_mfma_f32_16x16x32_bf16 v[30:33], v[134:137], v[166:169], v[30:33]
	v_mfma_f32_16x16x32_bf16 v[26:29], v[142:145], v[166:169], v[26:29]
	s_waitcnt lgkmcnt(0)
	v_mfma_f32_16x16x32_bf16 v[14:17], v[134:137], v[174:177], v[14:17]
	v_mfma_f32_16x16x32_bf16 v[10:13], v[142:145], v[174:177], v[10:13]
	s_setprio 0
	s_barrier
	s_mov_b32 m0, s19
	s_add_i32 s33, s73, 0x40000
	buffer_load_dwordx4 v193, s[8:11], s33 offen lds
	s_add_i32 s33, s73, 0x60000
	s_mov_b32 m0, s20
	s_nop 0
	buffer_load_dwordx4 v193, s[8:11], s33 offen lds
	s_cmp_eq_u32 s100, 0
	s_cbranch_scc1 .Lfw_14_a_p
	s_waitcnt vmcnt(16)
	s_mov_b32 s100, 0
	s_branch .Lfw_14_b_p

.Lfw_14_b_p:
	s_barrier
	s_setprio 1
	v_mfma_f32_16x16x32_bf16 v[54:57], v[178:181], v[146:149], 0
	v_mfma_f32_16x16x32_bf16 v[50:53], v[202:205], v[146:149], 0
	v_mfma_f32_16x16x32_bf16 v[38:41], v[178:181], v[154:157], 0
	v_mfma_f32_16x16x32_bf16 v[34:37], v[202:205], v[154:157], 0
	v_mfma_f32_16x16x32_bf16 v[22:25], v[178:181], v[162:165], 0
	v_mfma_f32_16x16x32_bf16 v[18:21], v[202:205], v[162:165], 0
	v_mfma_f32_16x16x32_bf16 v[6:9], v[178:181], v[170:173], 0
	v_mfma_f32_16x16x32_bf16 v[2:5], v[202:205], v[170:173], 0
	v_mfma_f32_16x16x32_bf16 v[54:57], v[182:185], v[150:153], v[54:57]
	v_mfma_f32_16x16x32_bf16 v[50:53], v[206:209], v[150:153], v[50:53]
	v_mfma_f32_16x16x32_bf16 v[38:41], v[182:185], v[158:161], v[38:41]
	v_mfma_f32_16x16x32_bf16 v[34:37], v[206:209], v[158:161], v[34:37]
	v_mfma_f32_16x16x32_bf16 v[22:25], v[182:185], v[166:169], v[22:25]
	v_mfma_f32_16x16x32_bf16 v[18:21], v[206:209], v[166:169], v[18:21]
	v_mfma_f32_16x16x32_bf16 v[6:9], v[182:185], v[174:177], v[6:9]
	v_mfma_f32_16x16x32_bf16 v[2:5], v[206:209], v[174:177], v[2:5]
	s_setprio 0
	s_barrier
	ds_read_b128 v[130:133], v199
	ds_read_b128 v[134:137], v199 offset:1024
	ds_read_b128 v[138:141], v199 offset:2048
	ds_read_b128 v[142:145], v199 offset:3072
	s_mov_b32 m0, s21
	s_add_i32 s33, s78, 0x40000
	ds_read_b128 v[146:149], v197 offset:32768
	ds_read_b128 v[150:153], v197 offset:33792
	ds_read_b128 v[154:157], v197 offset:34816
	ds_read_b128 v[158:161], v197 offset:35840
	ds_read_b128 v[162:165], v197 offset:36864
	ds_read_b128 v[166:169], v197 offset:37888
	ds_read_b128 v[170:173], v197 offset:38912
	ds_read_b128 v[174:177], v197 offset:39936
	buffer_load_dwordx4 v192, s[48:51], s33 offen lds
	s_add_i32 s33, s78, 0x60000
	s_mov_b32 m0, s22
	s_nop 0
	buffer_load_dwordx4 v192, s[48:51], s33 offen lds
	s_waitcnt lgkmcnt(8)
	s_barrier
	s_waitcnt lgkmcnt(0)
	s_setprio 1
	s_waitcnt lgkmcnt(7)
	v_mfma_f32_16x16x32_bf16 v[126:129], v[130:133], v[146:149], v[126:129]
	v_mfma_f32_16x16x32_bf16 v[122:125], v[138:141], v[146:149], v[122:125]
	s_waitcnt lgkmcnt(5)
	v_mfma_f32_16x16x32_bf16 v[110:113], v[130:133], v[154:157], v[110:113]
	v_mfma_f32_16x16x32_bf16 v[106:109], v[138:141], v[154:157], v[106:109]
	s_waitcnt lgkmcnt(3)
	v_mfma_f32_16x16x32_bf16 v[94:97], v[130:133], v[162:165], v[94:97]
	v_mfma_f32_16x16x32_bf16 v[90:93], v[138:141], v[162:165], v[90:93]
	s_waitcnt lgkmcnt(1)
	v_mfma_f32_16x16x32_bf16 v[78:81], v[130:133], v[170:173], v[78:81]
	v_mfma_f32_16x16x32_bf16 v[74:77], v[138:141], v[170:173], v[74:77]
	v_mfma_f32_16x16x32_bf16 v[126:129], v[134:137], v[150:153], v[126:129]
	v_mfma_f32_16x16x32_bf16 v[122:125], v[142:145], v[150:153], v[122:125]
	v_mfma_f32_16x16x32_bf16 v[110:113], v[134:137], v[158:161], v[110:113]
	v_mfma_f32_16x16x32_bf16 v[106:109], v[142:145], v[158:161], v[106:109]
	v_mfma_f32_16x16x32_bf16 v[94:97], v[134:137], v[166:169], v[94:97]
	v_mfma_f32_16x16x32_bf16 v[90:93], v[142:145], v[166:169], v[90:93]
	s_waitcnt lgkmcnt(0)
	v_mfma_f32_16x16x32_bf16 v[78:81], v[134:137], v[174:177], v[78:81]
	v_mfma_f32_16x16x32_bf16 v[74:77], v[142:145], v[174:177], v[74:77]
	s_setprio 0
	s_barrier
	s_mov_b32 m0, s28
	s_add_i32 s33, s73, 0x80
	ds_read_b128 v[178:181], v200
	ds_read_b128 v[182:185], v200 offset:1024
	ds_read_b128 v[202:205], v200 offset:2048
	ds_read_b128 v[206:209], v200 offset:3072
	buffer_load_dwordx4 v193, s[8:11], s33 offen lds
	s_add_i32 s33, s73, 0x20080
	s_mov_b32 m0, s29
	s_nop 0
	buffer_load_dwordx4 v193, s[8:11], s33 offen lds
	s_waitcnt vmcnt(10)
	s_barrier
	s_waitcnt lgkmcnt(0)
	s_setprio 1
	s_waitcnt lgkmcnt(3)
	v_mfma_f32_16x16x32_bf16 v[118:121], v[178:181], v[146:149], v[118:121]
	s_waitcnt lgkmcnt(1)
	v_mfma_f32_16x16x32_bf16 v[114:117], v[202:205], v[146:149], v[114:117]
	v_mfma_f32_16x16x32_bf16 v[102:105], v[178:181], v[154:157], v[102:105]
	v_mfma_f32_16x16x32_bf16 v[98:101], v[202:205], v[154:157], v[98:101]
	v_mfma_f32_16x16x32_bf16 v[86:89], v[178:181], v[162:165], v[86:89]
	v_mfma_f32_16x16x32_bf16 v[82:85], v[202:205], v[162:165], v[82:85]
	v_mfma_f32_16x16x32_bf16 v[70:73], v[178:181], v[170:173], v[70:73]
	v_mfma_f32_16x16x32_bf16 v[66:69], v[202:205], v[170:173], v[66:69]
	v_mfma_f32_16x16x32_bf16 v[118:121], v[182:185], v[150:153], v[118:121]
	s_waitcnt lgkmcnt(0)
	v_mfma_f32_16x16x32_bf16 v[114:117], v[206:209], v[150:153], v[114:117]
	v_mfma_f32_16x16x32_bf16 v[102:105], v[182:185], v[158:161], v[102:105]
	v_mfma_f32_16x16x32_bf16 v[98:101], v[206:209], v[158:161], v[98:101]
	v_mfma_f32_16x16x32_bf16 v[86:89], v[182:185], v[166:169], v[86:89]
	v_mfma_f32_16x16x32_bf16 v[82:85], v[206:209], v[166:169], v[82:85]
	v_mfma_f32_16x16x32_bf16 v[70:73], v[182:185], v[174:177], v[70:73]
	v_mfma_f32_16x16x32_bf16 v[66:69], v[206:209], v[174:177], v[66:69]
	s_setprio 0
	s_mov_b32 m0, s30
	s_barrier
	ds_read_b128 v[146:149], v197 offset:49152
	ds_read_b128 v[150:153], v197 offset:50176
	ds_read_b128 v[154:157], v197 offset:51200
	ds_read_b128 v[158:161], v197 offset:52224
	ds_read_b128 v[162:165], v197 offset:53248
	ds_read_b128 v[166:169], v197 offset:54272
	ds_read_b128 v[170:173], v197 offset:55296
	ds_read_b128 v[174:177], v197 offset:56320
	buffer_load_dwordx4 v192, s[48:51], s79 offen lds
	s_add_i32 s78, s78, 0x20080
	s_mov_b32 m0, s31
	s_nop 0
	buffer_load_dwordx4 v192, s[48:51], s78 offen lds
	s_barrier
	s_waitcnt lgkmcnt(0)
	s_setprio 1
	s_waitcnt lgkmcnt(7)
	v_mfma_f32_16x16x32_bf16 v[62:65], v[130:133], v[146:149], v[62:65]
	v_mfma_f32_16x16x32_bf16 v[58:61], v[138:141], v[146:149], v[58:61]
	s_waitcnt lgkmcnt(5)
	v_mfma_f32_16x16x32_bf16 v[46:49], v[130:133], v[154:157], v[46:49]
	v_mfma_f32_16x16x32_bf16 v[42:45], v[138:141], v[154:157], v[42:45]
	s_waitcnt lgkmcnt(3)
	v_mfma_f32_16x16x32_bf16 v[30:33], v[130:133], v[162:165], v[30:33]
	v_mfma_f32_16x16x32_bf16 v[26:29], v[138:141], v[162:165], v[26:29]
	s_waitcnt lgkmcnt(1)
	v_mfma_f32_16x16x32_bf16 v[14:17], v[130:133], v[170:173], v[14:17]
	v_mfma_f32_16x16x32_bf16 v[10:13], v[138:141], v[170:173], v[10:13]
	v_mfma_f32_16x16x32_bf16 v[62:65], v[134:137], v[150:153], v[62:65]
	v_mfma_f32_16x16x32_bf16 v[58:61], v[142:145], v[150:153], v[58:61]
	v_mfma_f32_16x16x32_bf16 v[46:49], v[134:137], v[158:161], v[46:49]
	v_mfma_f32_16x16x32_bf16 v[42:45], v[142:145], v[158:161], v[42:45]
	v_mfma_f32_16x16x32_bf16 v[30:33], v[134:137], v[166:169], v[30:33]
	v_mfma_f32_16x16x32_bf16 v[26:29], v[142:145], v[166:169], v[26:29]
	s_waitcnt lgkmcnt(0)
	v_mfma_f32_16x16x32_bf16 v[14:17], v[134:137], v[174:177], v[14:17]
	v_mfma_f32_16x16x32_bf16 v[10:13], v[142:145], v[174:177], v[10:13]
	s_setprio 0
	s_barrier
	s_mov_b32 m0, s34
	s_add_i32 s33, s73, 0x40080
	buffer_load_dwordx4 v193, s[8:11], s33 offen lds
	s_add_i32 s73, s73, 0x60080
	s_mov_b32 m0, s35
	s_nop 0
	buffer_load_dwordx4 v193, s[8:11], s73 offen lds
	s_waitcnt vmcnt(6)
	s_barrier
	s_setprio 1
	v_mfma_f32_16x16x32_bf16 v[54:57], v[178:181], v[146:149], v[54:57]
	v_mfma_f32_16x16x32_bf16 v[50:53], v[202:205], v[146:149], v[50:53]
	v_mfma_f32_16x16x32_bf16 v[38:41], v[178:181], v[154:157], v[38:41]
	v_mfma_f32_16x16x32_bf16 v[34:37], v[202:205], v[154:157], v[34:37]
	v_mfma_f32_16x16x32_bf16 v[22:25], v[178:181], v[162:165], v[22:25]
	v_mfma_f32_16x16x32_bf16 v[18:21], v[202:205], v[162:165], v[18:21]
	v_mfma_f32_16x16x32_bf16 v[6:9], v[178:181], v[170:173], v[6:9]
	v_mfma_f32_16x16x32_bf16 v[2:5], v[202:205], v[170:173], v[2:5]
	v_mfma_f32_16x16x32_bf16 v[54:57], v[182:185], v[150:153], v[54:57]
	v_mfma_f32_16x16x32_bf16 v[50:53], v[206:209], v[150:153], v[50:53]
	v_mfma_f32_16x16x32_bf16 v[38:41], v[182:185], v[158:161], v[38:41]
	v_mfma_f32_16x16x32_bf16 v[34:37], v[206:209], v[158:161], v[34:37]
	v_mfma_f32_16x16x32_bf16 v[22:25], v[182:185], v[166:169], v[22:25]
	v_mfma_f32_16x16x32_bf16 v[18:21], v[206:209], v[166:169], v[18:21]
	v_mfma_f32_16x16x32_bf16 v[6:9], v[182:185], v[174:177], v[6:9]
	v_mfma_f32_16x16x32_bf16 v[2:5], v[206:209], v[174:177], v[2:5]
	s_setprio 0
	s_add_i32 s13, s13, 2
	s_addk_i32 s7, 0x100
	s_addk_i32 s12, 0x100
	s_cmp_gt_u32 s13, 13
	s_barrier

.LBB0_3184:
	s_lshl_b32 s58, s51, 18
	s_and_b64 s[6:7], s[6:7], exec
	v_mov_b32_e32 v2, 0
	s_cselect_b32 s6, s58, s72
	s_add_i32 s7, s72, 0x30080
	s_addk_i32 s71, 0x100
	s_mov_b32 s72, -2
	ds_read_b128 v[144:147], v138
	ds_read_b128 v[148:151], v138 offset:1024
	ds_read_b128 v[152:155], v138 offset:2048
	ds_read_b128 v[156:159], v138 offset:3072
	s_add_i32 s10, s7, 0xfffd0080
	s_cmp_eq_u32 s72, 4
	s_cselect_b32 s74, s6, s10
	s_cselect_b32 s73, s57, s71
	s_or_b32 s75, s74, 0x80
	s_add_i32 s10, s7, 0xffff0000
	s_mov_b32 m0, s38
	ds_read_b128 v[160:163], v139
	ds_read_b128 v[164:167], v139 offset:1024
	ds_read_b128 v[168:171], v139 offset:2048
	ds_read_b128 v[172:175], v139 offset:3072
	ds_read_b128 v[176:179], v139 offset:4096
	ds_read_b128 v[180:183], v139 offset:5120
	ds_read_b128 v[184:187], v139 offset:6144
	ds_read_b128 v[188:191], v139 offset:7168
	buffer_load_dwordx4 v134, s[44:47], s10 offen lds
	s_mov_b32 m0, s39
	s_nop 0
	buffer_load_dwordx4 v134, s[44:47], s7 offen lds
	s_waitcnt lgkmcnt(8)
	s_barrier
	s_waitcnt lgkmcnt(0)
	s_setprio 1
	s_waitcnt lgkmcnt(4)
	v_mfma_f32_16x16x128_f8f6f4 v[114:117], v[144:151], v[168:175], 0
	v_mfma_f32_16x16x128_f8f6f4 v[106:109], v[152:159], v[168:175], 0
	s_waitcnt lgkmcnt(2)
	v_mfma_f32_16x16x128_f8f6f4 v[98:101], v[144:151], v[176:183], 0
	v_mfma_f32_16x16x128_f8f6f4 v[200:203], v[144:151], v[160:167], 0
	v_mfma_f32_16x16x128_f8f6f4 v[204:207], v[152:159], v[160:167], 0
	v_mfma_f32_16x16x128_f8f6f4 v[208:211], v[152:159], v[176:183], 0
	s_waitcnt lgkmcnt(0)
	v_mfma_f32_16x16x128_f8f6f4 v[212:215], v[144:151], v[184:191], 0
	v_mfma_f32_16x16x128_f8f6f4 v[216:219], v[152:159], v[184:191], 0
	s_setprio 0
	s_barrier
	s_mov_b32 m0, s22
	s_mov_b32 s10, s46
	s_mov_b32 s11, s47
	ds_read_b128 v[122:125], v254
	ds_read_b128 v[126:129], v254 offset:1024
	ds_read_b128 v[192:195], v254 offset:2048
	ds_read_b128 v[196:199], v254 offset:3072
	buffer_load_dwordx4 v135, s[8:11], s73 offen lds
	s_add_i32 s33, s73, 0x10000
	s_mov_b32 m0, s23
	s_nop 0
	buffer_load_dwordx4 v135, s[8:11], s33 offen lds
	s_barrier
	s_waitcnt lgkmcnt(0)
	s_setprio 1
	s_waitcnt lgkmcnt(2)
	v_mfma_f32_16x16x128_f8f6f4 v[118:121], v[122:129], v[160:167], 0
	s_waitcnt lgkmcnt(0)
	v_mfma_f32_16x16x128_f8f6f4 v[110:113], v[192:199], v[160:167], 0
	v_mfma_f32_16x16x128_f8f6f4 v[102:105], v[122:129], v[168:175], 0
	v_mfma_f32_16x16x128_f8f6f4 v[160:163], v[192:199], v[168:175], 0
	v_mfma_f32_16x16x128_f8f6f4 v[164:167], v[122:129], v[176:183], 0
	v_mfma_f32_16x16x128_f8f6f4 v[168:171], v[192:199], v[176:183], 0
	v_mfma_f32_16x16x128_f8f6f4 v[172:175], v[122:129], v[184:191], 0
	v_mfma_f32_16x16x128_f8f6f4 v[176:179], v[192:199], v[184:191], 0
	s_setprio 0
	s_mov_b32 m0, s21
	s_barrier
	ds_read_b128 v[66:69], v139 offset:16384
	s_nop 1
	ds_read_b128 v[70:73], v139 offset:17408
	ds_read_b128 v[74:77], v139 offset:18432
	ds_read_b128 v[78:81], v139 offset:19456
	ds_read_b128 v[82:85], v139 offset:20480
	ds_read_b128 v[86:89], v139 offset:21504
	ds_read_b128 v[90:93], v139 offset:22528
	ds_read_b128 v[94:97], v139 offset:23552
	buffer_load_dwordx4 v134, s[44:47], s74 offen lds
	s_add_i32 s33, s74, 0x10000
	s_mov_b32 m0, s24
	s_nop 0
	buffer_load_dwordx4 v134, s[44:47], s33 offen lds
	s_barrier
	s_waitcnt lgkmcnt(0)
	s_setprio 1
	s_waitcnt lgkmcnt(6)
	v_mfma_f32_16x16x128_f8f6f4 v[62:65], v[144:151], v[66:73], 0
	v_mfma_f32_16x16x128_f8f6f4 v[58:61], v[152:159], v[66:73], 0
	s_waitcnt lgkmcnt(4)
	v_mfma_f32_16x16x128_f8f6f4 v[50:53], v[144:151], v[74:81], 0
	s_waitcnt lgkmcnt(0)
	v_mfma_f32_16x16x128_f8f6f4 v[232:235], v[144:151], v[90:97], 0
	v_mfma_f32_16x16x128_f8f6f4 v[220:223], v[152:159], v[74:81], 0
	v_mfma_f32_16x16x128_f8f6f4 v[224:227], v[144:151], v[82:89], 0
	v_mfma_f32_16x16x128_f8f6f4 v[228:231], v[152:159], v[82:89], 0
	v_mfma_f32_16x16x128_f8f6f4 v[236:239], v[152:159], v[90:97], 0
	s_setprio 0
	s_barrier
	s_mov_b32 m0, s25
	s_add_i32 s33, s73, 0x20000
	buffer_load_dwordx4 v135, s[8:11], s33 offen lds
	s_add_i32 s33, s73, 0x30000
	s_mov_b32 m0, s26
	s_nop 0
	buffer_load_dwordx4 v135, s[8:11], s33 offen lds
	s_cmp_eq_u32 s100, 0
	s_cbranch_scc1 .Lfw_16_a_p
	s_waitcnt vmcnt(16)
	s_mov_b32 s100, 0
	s_branch .Lfw_16_b_p

.Lfw_16_b_p:
	s_barrier
	s_setprio 1
	v_mfma_f32_16x16x128_f8f6f4 v[54:57], v[122:129], v[66:73], 0
	v_mfma_f32_16x16x128_f8f6f4 v[240:243], v[192:199], v[66:73], 0
	v_mfma_f32_16x16x128_f8f6f4 v[244:247], v[122:129], v[74:81], 0
	v_mfma_f32_16x16x128_f8f6f4 v[248:251], v[192:199], v[74:81], 0
	v_mfma_f32_16x16x128_f8f6f4 v[130:133], v[122:129], v[82:89], 0
	v_mfma_f32_16x16x128_f8f6f4 v[140:143], v[192:199], v[82:89], 0
	v_mfma_f32_16x16x128_f8f6f4 v[66:69], v[122:129], v[90:97], 0
	v_mfma_f32_16x16x128_f8f6f4 v[192:195], v[192:199], v[90:97], 0
	s_setprio 0
	s_barrier
	s_nop 4
	ds_read_b128 v[2:5], v252
	ds_read_b128 v[6:9], v252 offset:1024
	ds_read_b128 v[10:13], v252 offset:2048
	ds_read_b128 v[14:17], v252 offset:3072
	s_mov_b32 m0, s27
	s_add_i32 s33, s74, 0x20000
	ds_read_b128 v[18:21], v139 offset:32768
	ds_read_b128 v[22:25], v139 offset:33792
	ds_read_b128 v[26:29], v139 offset:34816
	ds_read_b128 v[30:33], v139 offset:35840
	ds_read_b128 v[34:37], v139 offset:36864
	ds_read_b128 v[38:41], v139 offset:37888
	ds_read_b128 v[42:45], v139 offset:38912
	ds_read_b128 v[46:49], v139 offset:39936
	buffer_load_dwordx4 v134, s[44:47], s33 offen lds
	s_add_i32 s33, s74, 0x30000
	s_mov_b32 m0, s28
	s_nop 0
	buffer_load_dwordx4 v134, s[44:47], s33 offen lds
	s_waitcnt lgkmcnt(8)
	s_barrier
	s_waitcnt lgkmcnt(0)
	s_setprio 1
	s_waitcnt lgkmcnt(6)
	v_mfma_f32_16x16x128_f8f6f4 v[126:129], v[2:9], v[18:25], v[200:203]
	v_mfma_f32_16x16x128_f8f6f4 v[122:125], v[10:17], v[18:25], v[204:207]
	s_waitcnt lgkmcnt(4)
	v_mfma_f32_16x16x128_f8f6f4 v[114:117], v[2:9], v[26:33], v[114:117]
	v_mfma_f32_16x16x128_f8f6f4 v[106:109], v[10:17], v[26:33], v[106:109]
	s_waitcnt lgkmcnt(2)
	v_mfma_f32_16x16x128_f8f6f4 v[98:101], v[2:9], v[34:41], v[98:101]
	v_mfma_f32_16x16x128_f8f6f4 v[90:93], v[10:17], v[34:41], v[208:211]
	s_waitcnt lgkmcnt(0)
	v_mfma_f32_16x16x128_f8f6f4 v[82:85], v[2:9], v[42:49], v[212:215]
	v_mfma_f32_16x16x128_f8f6f4 v[74:77], v[10:17], v[42:49], v[216:219]
	s_setprio 0
	s_barrier
	s_mov_b32 m0, s30
	s_add_i32 s33, s73, 0x80
	ds_read_b128 v[144:147], v253
	ds_read_b128 v[148:151], v253 offset:1024
	ds_read_b128 v[152:155], v253 offset:2048
	ds_read_b128 v[156:159], v253 offset:3072
	buffer_load_dwordx4 v135, s[8:11], s33 offen lds
	s_add_i32 s33, s73, 0x10080
	s_mov_b32 m0, s31
	s_nop 0
	buffer_load_dwordx4 v135, s[8:11], s33 offen lds
	s_waitcnt vmcnt(10)
	s_barrier
	s_waitcnt lgkmcnt(0)
	s_setprio 1
	s_waitcnt lgkmcnt(2)
	v_mfma_f32_16x16x128_f8f6f4 v[118:121], v[144:151], v[18:25], v[118:121]
	s_waitcnt lgkmcnt(0)
	v_mfma_f32_16x16x128_f8f6f4 v[110:113], v[152:159], v[18:25], v[110:113]
	v_mfma_f32_16x16x128_f8f6f4 v[102:105], v[144:151], v[26:33], v[102:105]
	v_mfma_f32_16x16x128_f8f6f4 v[94:97], v[152:159], v[26:33], v[160:163]
	v_mfma_f32_16x16x128_f8f6f4 v[86:89], v[144:151], v[34:41], v[164:167]
	v_mfma_f32_16x16x128_f8f6f4 v[78:81], v[152:159], v[34:41], v[168:171]
	v_mfma_f32_16x16x128_f8f6f4 v[70:73], v[144:151], v[42:49], v[172:175]
	v_mfma_f32_16x16x128_f8f6f4 v[18:21], v[152:159], v[42:49], v[176:179]
	s_setprio 0
	s_mov_b32 m0, s34
	s_barrier
	ds_read_b128 v[160:163], v139 offset:49152
	ds_read_b128 v[164:167], v139 offset:50176
	ds_read_b128 v[168:171], v139 offset:51200
	ds_read_b128 v[172:175], v139 offset:52224
	ds_read_b128 v[176:179], v139 offset:53248
	ds_read_b128 v[180:183], v139 offset:54272
	ds_read_b128 v[184:187], v139 offset:55296
	ds_read_b128 v[188:191], v139 offset:56320
	buffer_load_dwordx4 v134, s[44:47], s75 offen lds
	s_add_i32 s74, s74, 0x10080
	s_mov_b32 m0, s35
	s_nop 0
	buffer_load_dwordx4 v134, s[44:47], s74 offen lds
	s_barrier
	s_waitcnt lgkmcnt(0)
	s_setprio 1
	s_waitcnt lgkmcnt(6)
	v_mfma_f32_16x16x128_f8f6f4 v[62:65], v[2:9], v[160:167], v[62:65]
	v_mfma_f32_16x16x128_f8f6f4 v[58:61], v[10:17], v[160:167], v[58:61]
	s_waitcnt lgkmcnt(4)
	v_mfma_f32_16x16x128_f8f6f4 v[50:53], v[2:9], v[168:175], v[50:53]
	v_mfma_f32_16x16x128_f8f6f4 v[42:45], v[10:17], v[168:175], v[220:223]
	s_waitcnt lgkmcnt(2)
	v_mfma_f32_16x16x128_f8f6f4 v[34:37], v[2:9], v[176:183], v[224:227]
	v_mfma_f32_16x16x128_f8f6f4 v[26:29], v[10:17], v[176:183], v[228:231]
	s_waitcnt lgkmcnt(0)
	v_mfma_f32_16x16x128_f8f6f4 v[232:235], v[2:9], v[184:191], v[232:235]
	v_mfma_f32_16x16x128_f8f6f4 v[10:13], v[10:17], v[184:191], v[236:239]
	s_setprio 0
	s_barrier
	s_mov_b32 m0, s36
	s_add_i32 s33, s73, 0x20080
	buffer_load_dwordx4 v135, s[8:11], s33 offen lds
	s_add_i32 s73, s73, 0x30080
	s_mov_b32 m0, s37
	s_nop 0
	buffer_load_dwordx4 v135, s[8:11], s73 offen lds
	s_waitcnt vmcnt(6)
	s_barrier
	s_setprio 1
	v_mfma_f32_16x16x128_f8f6f4 v[54:57], v[144:151], v[160:167], v[54:57]
	v_mfma_f32_16x16x128_f8f6f4 v[46:49], v[152:159], v[160:167], v[240:243]
	v_mfma_f32_16x16x128_f8f6f4 v[38:41], v[144:151], v[168:175], v[244:247]
	v_mfma_f32_16x16x128_f8f6f4 v[30:33], v[152:159], v[168:175], v[248:251]
	v_mfma_f32_16x16x128_f8f6f4 v[22:25], v[144:151], v[176:183], v[130:133]
	v_mfma_f32_16x16x128_f8f6f4 v[14:17], v[152:159], v[176:183], v[140:143]
	v_mfma_f32_16x16x128_f8f6f4 v[6:9], v[144:151], v[184:191], v[66:69]
	v_mfma_f32_16x16x128_f8f6f4 v[2:5], v[152:159], v[184:191], v[192:195]
	s_setprio 0
	s_add_i32 s72, s72, 2
	s_addk_i32 s7, 0x100
	s_addk_i32 s71, 0x100
	s_cmp_gt_u32 s72, 5
	s_barrier
